# first K-iteration of every GEMM tile peeled with C=0 MFMAs (no accumulator zeroing), no s_setprio, batched final ssp reloads
# speedup vs baseline: 1.0102x; 1.0102x over previous
; #define PG8_STAGE(bufoff, gbase, voff) do { _Pragma("unroll") for (int _i = 0; _i < 2; ++_i) \
;         __builtin_amdgcn_global_load_lds((const unsigned*)((const char*)(gbase) + (voff)[_i]), (LAS unsigned*)(lds + (bufoff) + ldsw + _i * 8192), 16, 0, 0); } while (0)
; #define PG8_LDA(dst, b, h) do { _Pragma("unroll") for (int m = 0; m < 4; ++m) _Pragma("unroll") for (int k = 0; k < 2; ++k) dst[m][k] = *(const LAS bf16x8*)(lds + PG8_SA(b, h) + aoff + m * 2048 + k * 1024); } while (0)
; #define PG8_LDB(dst, b, h) do { _Pragma("unroll") for (int n = 0; n < 2; ++n) _Pragma("unroll") for (int k = 0; k < 2; ++k) dst[n][k] = *(const LAS bf16x8*)(lds + PG8_SB(b, h) + boff + n * 2048 + k * 1024); } while (0)
; #define PG8_MMA(ai, bj, At, Bt) do { __builtin_amdgcn_s_setprio(1); _Pragma("unroll") for (int m = 0; m < 4; ++m) _Pragma("unroll") for (int n = 0; n < 2; ++n) _Pragma("unroll") for (int k = 0; k < 2; ++k) \
;         acc[ai][bj][m][n] = __builtin_amdgcn_mfma_f32_16x16x32_bf16(Bt[n][k], At[m][k], acc[ai][bj][m][n], 0, 0, 0); __builtin_amdgcn_s_setprio(0); } while (0)
; #define PG8_WAIT_V(n) asm volatile("s_waitcnt vmcnt(" #n ")" ::: "memory")
; #define PG8_WAIT_L(n) asm volatile("s_waitcnt lgkmcnt(" #n ")" ::: "memory")
; template <class Epi>
; __device__ __forceinline__ void gemm_phase(LAS unsigned char* lds, const Gemm g, const StaticOrder& S, const Epi& E) {
;     ...
;         const bool has_next = S.next(ui + 1, nxt);
;         const char* nA = has_next ? (const char*)g.A + (size_t)(nxt.pm >> 5) * aslab + (size_t)(nxt.pm & 31) * tstepA : cA; const char* nB = has_next ? (const char*)g.Bt + (size_t)nxt.pn * tstepB : cB;
;         for (int t = 0; t < nt; t += 2) {
;             const bool last = (t == nt - 2);
;             const char* a1 = cA + (size_t)(t + 1) * kstep;
;             const char* a2 = last ? nA : cA + (size_t)(t + 2) * kstep; const char* b2 = last ? nB : cB + (size_t)(t + 2) * kstep;
;             const char* a3 = a2 + kstep; const char* b3 = b2 + kstep;
;             PG8_LDB(B0, 0, 0); PG8_LDB(B1, 0, 1); PG8_SCHED; PG8_LDA(At, 0, 0); PG8_STAGE(PG8_SA(1, 1), a1 + hstepA, voffA);
;             PG8_WAIT_V(8); PG8_WAIT_L(0); PG8_BAR; PG8_MMA(0, 0, At, B0); PG8_MMA(0, 1, At, B1); PG8_BAR; PG8_SCHED;
;             PG8_LDA(At, 0, 1); PG8_STAGE(PG8_SB(0, 0), b2, voffB); PG8_STAGE(PG8_SB(0, 1), b2 + hstepB, voffB); PG8_STAGE(PG8_SA(0, 0), a2, voffA);
.LBB0_152:
	s_ashr_i32 s20, s56, 5
	s_ashr_i32 s21, s20, 31
	s_lshl_b64 s[20:21], s[20:21], 24
	v_readlane_b32 s22, v235, 38
	v_readlane_b32 s23, v235, 39
	s_add_u32 s19, s22, s20
	s_addc_u32 s21, s23, s21
	s_lshl_b32 s20, s56, 19
	s_and_b32 s20, s20, 0xf80000
	s_add_u32 s20, s19, s20
	s_addc_u32 s21, s21, 0
	s_and_b64 s[22:23], s[0:1], exec
	s_cselect_b32 s58, s21, s25
	s_cselect_b32 s59, s20, s24
	s_ashr_i32 s19, s18, 31
	s_lshl_b64 s[22:23], s[18:19], 19
	s_add_u32 s22, s6, s22
	s_addc_u32 s23, s7, s23
	s_and_b64 s[26:27], s[0:1], exec
	s_cselect_b32 s19, s23, s3
	s_cselect_b32 s60, s22, s2
	s_add_u32 s24, s24, 0x40080
	s_addc_u32 s25, s25, 0
	s_add_u32 s61, s2, 0x100
	s_addc_u32 s62, s3, 0
	s_mov_b32 s63, -2
	ds_read_b128 v[154:157], v149
	ds_read_b128 v[158:161], v149 offset:1024
	ds_read_b128 v[162:165], v149 offset:2048
	ds_read_b128 v[166:169], v149 offset:3072
	ds_read_b128 v[170:173], v150
	ds_read_b128 v[174:177], v150 offset:1024
	ds_read_b128 v[178:181], v150 offset:2048
	ds_read_b128 v[182:185], v150 offset:3072
	s_add_u32 s2, s24, 0xfffc0080
	s_addc_u32 s3, s25, -1
	s_cmp_eq_u32 s63, 12
	s_cselect_b32 s27, s58, s3
	s_cselect_b32 s26, s59, s2
	s_cselect_b32 s3, s19, s62
	s_cselect_b32 s2, s60, s61
	v_lshl_add_u64 v[144:145], s[24:25], 0, v[136:137]
	s_add_i32 m0, s42, 0xc000
	ds_read_b128 v[190:193], v151
	ds_read_b128 v[198:201], v151 offset:1024
	ds_read_b128 v[202:205], v151 offset:2048
	ds_read_b128 v[206:209], v151 offset:3072
	ds_read_b128 v[210:213], v151 offset:4096
	ds_read_b128 v[214:217], v151 offset:5120
	ds_read_b128 v[218:221], v151 offset:6144
	ds_read_b128 v[222:225], v151 offset:7168
	global_load_lds_dwordx4 v[144:145], off
	v_lshl_add_u64 v[144:145], s[24:25], 0, v[140:141]
	s_add_i32 m0, s42, 0xe000
	s_nop 0
	global_load_lds_dwordx4 v[144:145], off
	s_waitcnt vmcnt(8)
	s_waitcnt lgkmcnt(0)
	s_barrier
	s_waitcnt lgkmcnt(0)
	v_mfma_f32_16x16x32_bf16 v[116:119], v[154:157], v[190:193], 0
	v_mfma_f32_16x16x32_bf16 v[108:111], v[162:165], v[190:193], 0
	v_mfma_f32_16x16x32_bf16 v[104:107], v[154:157], v[202:205], 0
	v_mfma_f32_16x16x32_bf16 v[100:103], v[162:165], v[202:205], 0
	v_mfma_f32_16x16x32_bf16 v[92:95], v[154:157], v[210:213], 0
	v_mfma_f32_16x16x32_bf16 v[84:87], v[162:165], v[210:213], 0
	v_mfma_f32_16x16x32_bf16 v[76:79], v[154:157], v[218:221], 0
	v_mfma_f32_16x16x32_bf16 v[68:71], v[162:165], v[218:221], 0
	v_mfma_f32_16x16x32_bf16 v[116:119], v[158:161], v[198:201], v[116:119]
	v_mfma_f32_16x16x32_bf16 v[108:111], v[166:169], v[198:201], v[108:111]
	v_mfma_f32_16x16x32_bf16 v[104:107], v[158:161], v[206:209], v[104:107]
	v_mfma_f32_16x16x32_bf16 v[100:103], v[166:169], v[206:209], v[100:103]
	v_mfma_f32_16x16x32_bf16 v[92:95], v[158:161], v[214:217], v[92:95]
	v_mfma_f32_16x16x32_bf16 v[84:87], v[166:169], v[214:217], v[84:87]
	v_mfma_f32_16x16x32_bf16 v[76:79], v[158:161], v[222:225], v[76:79]
	v_mfma_f32_16x16x32_bf16 v[68:71], v[166:169], v[222:225], v[68:71]
	v_mfma_f32_16x16x32_bf16 v[124:127], v[170:173], v[190:193], 0
	v_mfma_f32_16x16x32_bf16 v[120:123], v[178:181], v[190:193], 0
	v_mfma_f32_16x16x32_bf16 v[112:115], v[170:173], v[202:205], 0
	v_mfma_f32_16x16x32_bf16 v[96:99], v[178:181], v[202:205], 0
	v_mfma_f32_16x16x32_bf16 v[88:91], v[170:173], v[210:213], 0
	v_mfma_f32_16x16x32_bf16 v[80:83], v[178:181], v[210:213], 0
	v_mfma_f32_16x16x32_bf16 v[72:75], v[170:173], v[218:221], 0
	v_mfma_f32_16x16x32_bf16 v[64:67], v[178:181], v[218:221], 0
	v_mfma_f32_16x16x32_bf16 v[124:127], v[174:177], v[198:201], v[124:127]
	v_mfma_f32_16x16x32_bf16 v[120:123], v[182:185], v[198:201], v[120:123]
	v_mfma_f32_16x16x32_bf16 v[112:115], v[174:177], v[206:209], v[112:115]
	v_mfma_f32_16x16x32_bf16 v[96:99], v[182:185], v[206:209], v[96:99]
	v_mfma_f32_16x16x32_bf16 v[88:91], v[174:177], v[214:217], v[88:91]
	v_mfma_f32_16x16x32_bf16 v[80:83], v[182:185], v[214:217], v[80:83]
	v_mfma_f32_16x16x32_bf16 v[72:75], v[174:177], v[222:225], v[72:75]
	v_mfma_f32_16x16x32_bf16 v[64:67], v[182:185], v[222:225], v[64:67]
	s_barrier
	s_add_i32 s64, s53, s40
	v_lshl_add_u64 v[144:145], s[2:3], 0, v[128:129]
	s_mov_b32 m0, s64
	ds_read_b128 v[190:193], v151 offset:16384
	ds_read_b128 v[198:201], v151 offset:17408
	ds_read_b128 v[202:205], v151 offset:18432
	ds_read_b128 v[206:209], v151 offset:19456
	ds_read_b128 v[210:213], v151 offset:20480
	ds_read_b128 v[214:217], v151 offset:21504
	ds_read_b128 v[218:221], v151 offset:22528
	ds_read_b128 v[222:225], v151 offset:23552
	global_load_lds_dwordx4 v[144:145], off
	s_add_i32 m0, s64, 0x2000
	s_add_u32 s64, s2, 0x40000
	v_lshl_add_u64 v[186:187], s[2:3], 0, v[130:131]
	s_addc_u32 s65, s3, 0
	s_add_i32 s66, s54, s40
	global_load_lds_dwordx4 v[186:187], off
	v_lshl_add_u64 v[194:195], s[64:65], 0, v[128:129]
	s_mov_b32 m0, s66
	v_lshl_add_u64 v[226:227], s[26:27], 0, v[132:133]
	global_load_lds_dwordx4 v[194:195], off
	v_lshl_add_u64 v[194:195], s[64:65], 0, v[130:131]
	s_add_i32 m0, s66, 0x2000
	s_nop 0
	global_load_lds_dwordx4 v[194:195], off
	v_lshl_add_u64 v[194:195], s[26:27], 0, v[134:135]
	s_mov_b32 m0, s42
	s_nop 0
	global_load_lds_dwordx4 v[194:195], off
	s_mov_b32 m0, s43
	s_nop 0
	global_load_lds_dwordx4 v[226:227], off
	s_waitcnt vmcnt(8)
	s_waitcnt lgkmcnt(0)
	s_barrier
; #define PG8_STAGE(bufoff, gbase, voff) do { _Pragma("unroll") for (int _i = 0; _i < 2; ++_i) \
;         __builtin_amdgcn_global_load_lds((const unsigned*)((const char*)(gbase) + (voff)[_i]), (LAS unsigned*)(lds + (bufoff) + ldsw + _i * 8192), 16, 0, 0); } while (0)
; #define PG8_LDA(dst, b, h) do { _Pragma("unroll") for (int m = 0; m < 4; ++m) _Pragma("unroll") for (int k = 0; k < 2; ++k) dst[m][k] = *(const LAS bf16x8*)(lds + PG8_SA(b, h) + aoff + m * 2048 + k * 1024); } while (0)
; #define PG8_LDB(dst, b, h) do { _Pragma("unroll") for (int n = 0; n < 2; ++n) _Pragma("unroll") for (int k = 0; k < 2; ++k) dst[n][k] = *(const LAS bf16x8*)(lds + PG8_SB(b, h) + boff + n * 2048 + k * 1024); } while (0)
; #define PG8_MMA(ai, bj, At, Bt) do { __builtin_amdgcn_s_setprio(1); _Pragma("unroll") for (int m = 0; m < 4; ++m) _Pragma("unroll") for (int n = 0; n < 2; ++n) _Pragma("unroll") for (int k = 0; k < 2; ++k) \
;         acc[ai][bj][m][n] = __builtin_amdgcn_mfma_f32_16x16x32_bf16(Bt[n][k], At[m][k], acc[ai][bj][m][n], 0, 0, 0); __builtin_amdgcn_s_setprio(0); } while (0)
; #define PG8_WAIT_V(n) asm volatile("s_waitcnt vmcnt(" #n ")" ::: "memory")
; #define PG8_WAIT_L(n) asm volatile("s_waitcnt lgkmcnt(" #n ")" ::: "memory")
; #define PG8_BAR __builtin_amdgcn_s_barrier()
; #define PG8_SCHED __builtin_amdgcn_sched_barrier(0)
; template <class Epi>
; __device__ __forceinline__ void gemm_phase(LAS unsigned char* lds, const Gemm g, const StaticOrder& S, const Epi& E) {
;     ...
;             PG8_WAIT_V(8); PG8_WAIT_L(0); PG8_BAR; PG8_MMA(1, 0, At, B0); PG8_MMA(1, 1, At, B1); PG8_BAR; PG8_SCHED;
;             PG8_LDB(B0, 1, 0); PG8_LDB(B1, 1, 1); PG8_SCHED; PG8_LDA(At, 1, 0); PG8_STAGE(PG8_SA(0, 1), a2 + hstepA, voffA);
;             PG8_WAIT_V(8); PG8_WAIT_L(0); PG8_BAR; PG8_MMA(0, 0, At, B0); PG8_MMA(0, 1, At, B1); PG8_BAR; PG8_SCHED;
	s_waitcnt lgkmcnt(0)
	v_mfma_f32_16x16x32_bf16 v[60:63], v[154:157], v[190:193], 0
	v_mfma_f32_16x16x32_bf16 v[52:55], v[162:165], v[190:193], 0
	v_mfma_f32_16x16x32_bf16 v[44:47], v[154:157], v[202:205], 0
	v_mfma_f32_16x16x32_bf16 v[36:39], v[162:165], v[202:205], 0
	v_mfma_f32_16x16x32_bf16 v[28:31], v[154:157], v[210:213], 0
	v_mfma_f32_16x16x32_bf16 v[20:23], v[162:165], v[210:213], 0
	v_mfma_f32_16x16x32_bf16 v[12:15], v[154:157], v[218:221], 0
	v_mfma_f32_16x16x32_bf16 v[4:7], v[162:165], v[218:221], 0
	v_mfma_f32_16x16x32_bf16 v[60:63], v[158:161], v[198:201], v[60:63]
	v_mfma_f32_16x16x32_bf16 v[52:55], v[166:169], v[198:201], v[52:55]
	v_mfma_f32_16x16x32_bf16 v[44:47], v[158:161], v[206:209], v[44:47]
	v_mfma_f32_16x16x32_bf16 v[36:39], v[166:169], v[206:209], v[36:39]
	v_mfma_f32_16x16x32_bf16 v[28:31], v[158:161], v[214:217], v[28:31]
	v_mfma_f32_16x16x32_bf16 v[20:23], v[166:169], v[214:217], v[20:23]
	v_mfma_f32_16x16x32_bf16 v[12:15], v[158:161], v[222:225], v[12:15]
	v_mfma_f32_16x16x32_bf16 v[4:7], v[166:169], v[222:225], v[4:7]
	v_mfma_f32_16x16x32_bf16 v[56:59], v[170:173], v[190:193], 0
	v_mfma_f32_16x16x32_bf16 v[48:51], v[178:181], v[190:193], 0
	v_mfma_f32_16x16x32_bf16 v[40:43], v[170:173], v[202:205], 0
	v_mfma_f32_16x16x32_bf16 v[32:35], v[178:181], v[202:205], 0
	v_mfma_f32_16x16x32_bf16 v[24:27], v[170:173], v[210:213], 0
	v_mfma_f32_16x16x32_bf16 v[16:19], v[178:181], v[210:213], 0
	v_mfma_f32_16x16x32_bf16 v[8:11], v[170:173], v[218:221], 0
	v_mfma_f32_16x16x32_bf16 v[0:3], v[178:181], v[218:221], 0
	v_mfma_f32_16x16x32_bf16 v[56:59], v[174:177], v[198:201], v[56:59]
	v_mfma_f32_16x16x32_bf16 v[48:51], v[182:185], v[198:201], v[48:51]
	v_mfma_f32_16x16x32_bf16 v[40:43], v[174:177], v[206:209], v[40:43]
	v_mfma_f32_16x16x32_bf16 v[32:35], v[182:185], v[206:209], v[32:35]
	v_mfma_f32_16x16x32_bf16 v[24:27], v[174:177], v[214:217], v[24:27]
	v_mfma_f32_16x16x32_bf16 v[16:19], v[182:185], v[214:217], v[16:19]
	v_mfma_f32_16x16x32_bf16 v[8:11], v[174:177], v[222:225], v[8:11]
	v_mfma_f32_16x16x32_bf16 v[0:3], v[182:185], v[222:225], v[0:3]
	s_barrier
	s_add_i32 s64, 0, 0x18000
	v_add_u32_e32 v138, s64, v147
	s_add_i32 s65, 0, 0x1c000
	ds_read_b128 v[154:157], v138
	ds_read_b128 v[158:161], v138 offset:1024
	ds_read_b128 v[162:165], v138 offset:2048
	ds_read_b128 v[166:169], v138 offset:3072
	v_add_u32_e32 v138, s65, v147
	ds_read_b128 v[170:173], v138
	ds_read_b128 v[174:177], v138 offset:1024
	ds_read_b128 v[178:181], v138 offset:2048
	ds_read_b128 v[182:185], v138 offset:3072
	s_add_u32 s26, s26, 0x40000
	s_addc_u32 s27, s27, 0
	s_mov_b32 m0, s44
	v_lshl_add_u64 v[228:229], s[26:27], 0, v[134:135]
	ds_read_b128 v[190:193], v151 offset:32768
	ds_read_b128 v[198:201], v151 offset:33792
	ds_read_b128 v[202:205], v151 offset:34816
	ds_read_b128 v[206:209], v151 offset:35840
	ds_read_b128 v[210:213], v151 offset:36864
	ds_read_b128 v[214:217], v151 offset:37888
	ds_read_b128 v[218:221], v151 offset:38912
	ds_read_b128 v[222:225], v151 offset:39936
	global_load_lds_dwordx4 v[228:229], off
	v_lshl_add_u64 v[228:229], s[26:27], 0, v[132:133]
	s_mov_b32 m0, s45
	s_nop 0
	global_load_lds_dwordx4 v[228:229], off
	s_waitcnt vmcnt(8)
	s_waitcnt lgkmcnt(0)
	s_barrier
	s_waitcnt lgkmcnt(0)
	v_mfma_f32_16x16x32_bf16 v[116:119], v[154:157], v[190:193], v[116:119]
	v_mfma_f32_16x16x32_bf16 v[108:111], v[162:165], v[190:193], v[108:111]
	v_mfma_f32_16x16x32_bf16 v[104:107], v[154:157], v[202:205], v[104:107]
	v_mfma_f32_16x16x32_bf16 v[100:103], v[162:165], v[202:205], v[100:103]
	v_mfma_f32_16x16x32_bf16 v[92:95], v[154:157], v[210:213], v[92:95]
	v_mfma_f32_16x16x32_bf16 v[84:87], v[162:165], v[210:213], v[84:87]
	v_mfma_f32_16x16x32_bf16 v[76:79], v[154:157], v[218:221], v[76:79]
	v_mfma_f32_16x16x32_bf16 v[68:71], v[162:165], v[218:221], v[68:71]
	v_mfma_f32_16x16x32_bf16 v[116:119], v[158:161], v[198:201], v[116:119]
	v_mfma_f32_16x16x32_bf16 v[108:111], v[166:169], v[198:201], v[108:111]
	v_mfma_f32_16x16x32_bf16 v[104:107], v[158:161], v[206:209], v[104:107]
	v_mfma_f32_16x16x32_bf16 v[100:103], v[166:169], v[206:209], v[100:103]
	v_mfma_f32_16x16x32_bf16 v[92:95], v[158:161], v[214:217], v[92:95]
	v_mfma_f32_16x16x32_bf16 v[84:87], v[166:169], v[214:217], v[84:87]
	v_mfma_f32_16x16x32_bf16 v[76:79], v[158:161], v[222:225], v[76:79]
	v_mfma_f32_16x16x32_bf16 v[68:71], v[166:169], v[222:225], v[68:71]
	v_mfma_f32_16x16x32_bf16 v[124:127], v[170:173], v[190:193], v[124:127]
	v_mfma_f32_16x16x32_bf16 v[120:123], v[178:181], v[190:193], v[120:123]
	v_mfma_f32_16x16x32_bf16 v[112:115], v[170:173], v[202:205], v[112:115]
	v_mfma_f32_16x16x32_bf16 v[96:99], v[178:181], v[202:205], v[96:99]
	v_mfma_f32_16x16x32_bf16 v[88:91], v[170:173], v[210:213], v[88:91]
	v_mfma_f32_16x16x32_bf16 v[80:83], v[178:181], v[210:213], v[80:83]
	v_mfma_f32_16x16x32_bf16 v[72:75], v[170:173], v[218:221], v[72:75]
	v_mfma_f32_16x16x32_bf16 v[64:67], v[178:181], v[218:221], v[64:67]
	v_mfma_f32_16x16x32_bf16 v[124:127], v[174:177], v[198:201], v[124:127]
	v_mfma_f32_16x16x32_bf16 v[120:123], v[182:185], v[198:201], v[120:123]
	v_mfma_f32_16x16x32_bf16 v[112:115], v[174:177], v[206:209], v[112:115]
	v_mfma_f32_16x16x32_bf16 v[96:99], v[182:185], v[206:209], v[96:99]
	v_mfma_f32_16x16x32_bf16 v[88:91], v[174:177], v[214:217], v[88:91]
	v_mfma_f32_16x16x32_bf16 v[80:83], v[182:185], v[214:217], v[80:83]
	v_mfma_f32_16x16x32_bf16 v[72:75], v[174:177], v[222:225], v[72:75]
	v_mfma_f32_16x16x32_bf16 v[64:67], v[182:185], v[222:225], v[64:67]
	s_barrier
; #define PG8_STAGE(bufoff, gbase, voff) do { _Pragma("unroll") for (int _i = 0; _i < 2; ++_i) \
;         __builtin_amdgcn_global_load_lds((const unsigned*)((const char*)(gbase) + (voff)[_i]), (LAS unsigned*)(lds + (bufoff) + ldsw + _i * 8192), 16, 0, 0); } while (0)
; #define PG8_LDA(dst, b, h) do { _Pragma("unroll") for (int m = 0; m < 4; ++m) _Pragma("unroll") for (int k = 0; k < 2; ++k) dst[m][k] = *(const LAS bf16x8*)(lds + PG8_SA(b, h) + aoff + m * 2048 + k * 1024); } while (0)
; #define PG8_MMA(ai, bj, At, Bt) do { __builtin_amdgcn_s_setprio(1); _Pragma("unroll") for (int m = 0; m < 4; ++m) _Pragma("unroll") for (int n = 0; n < 2; ++n) _Pragma("unroll") for (int k = 0; k < 2; ++k) \
;         acc[ai][bj][m][n] = __builtin_amdgcn_mfma_f32_16x16x32_bf16(Bt[n][k], At[m][k], acc[ai][bj][m][n], 0, 0, 0); __builtin_amdgcn_s_setprio(0); } while (0)
; #define PG8_WAIT_V(n) asm volatile("s_waitcnt vmcnt(" #n ")" ::: "memory")
; #define PG8_WAIT_L(n) asm volatile("s_waitcnt lgkmcnt(" #n ")" ::: "memory")
; #define PG8_BAR __builtin_amdgcn_s_barrier()
; #define PG8_SCHED __builtin_amdgcn_sched_barrier(0)
; template <class Epi>
; __device__ __forceinline__ void gemm_phase(LAS unsigned char* lds, const Gemm g, const StaticOrder& S, const Epi& E) {
;     ...
;             PG8_LDA(At, 1, 1); PG8_STAGE(PG8_SB(1, 0), b3, voffB); PG8_STAGE(PG8_SB(1, 1), b3 + hstepB, voffB); PG8_STAGE(PG8_SA(1, 0), a3, voffA);
;             PG8_WAIT_V(8); PG8_WAIT_L(0); PG8_BAR; PG8_MMA(1, 0, At, B0); PG8_MMA(1, 1, At, B1); PG8_BAR; PG8_SCHED;
;         }
	s_add_i32 s26, s64, s40
	v_lshl_add_u64 v[144:145], v[144:145], 0, s[14:15]
	s_mov_b32 m0, s26
	ds_read_b128 v[190:193], v151 offset:49152
	ds_read_b128 v[198:201], v151 offset:50176
	ds_read_b128 v[202:205], v151 offset:51200
	ds_read_b128 v[206:209], v151 offset:52224
	ds_read_b128 v[210:213], v151 offset:53248
	ds_read_b128 v[214:217], v151 offset:54272
	ds_read_b128 v[218:221], v151 offset:55296
	ds_read_b128 v[222:225], v151 offset:56320
	global_load_lds_dwordx4 v[144:145], off
	s_add_i32 m0, s26, 0x2000
	s_add_u32 s2, s2, 0x40080
	v_lshl_add_u64 v[144:145], v[186:187], 0, s[14:15]
	s_addc_u32 s3, s3, 0
	s_add_i32 s26, s65, s40
	global_load_lds_dwordx4 v[144:145], off
	v_lshl_add_u64 v[144:145], s[2:3], 0, v[128:129]
	s_mov_b32 m0, s26
	s_nop 0
	global_load_lds_dwordx4 v[144:145], off
	v_lshl_add_u64 v[144:145], s[2:3], 0, v[130:131]
	s_add_i32 m0, s26, 0x2000
	s_nop 0
	global_load_lds_dwordx4 v[144:145], off
	v_lshl_add_u64 v[144:145], v[194:195], 0, s[14:15]
	s_mov_b32 m0, s49
	s_nop 0
	global_load_lds_dwordx4 v[144:145], off
	v_lshl_add_u64 v[144:145], v[226:227], 0, s[14:15]
	s_mov_b32 m0, s50
	s_nop 0
	global_load_lds_dwordx4 v[144:145], off
	s_waitcnt vmcnt(8)
	s_waitcnt lgkmcnt(0)
	s_barrier
	s_waitcnt lgkmcnt(0)
	v_mfma_f32_16x16x32_bf16 v[60:63], v[154:157], v[190:193], v[60:63]
	v_mfma_f32_16x16x32_bf16 v[52:55], v[162:165], v[190:193], v[52:55]
	v_mfma_f32_16x16x32_bf16 v[44:47], v[154:157], v[202:205], v[44:47]
	v_mfma_f32_16x16x32_bf16 v[36:39], v[162:165], v[202:205], v[36:39]
	v_mfma_f32_16x16x32_bf16 v[28:31], v[154:157], v[210:213], v[28:31]
	v_mfma_f32_16x16x32_bf16 v[20:23], v[162:165], v[210:213], v[20:23]
	v_mfma_f32_16x16x32_bf16 v[12:15], v[154:157], v[218:221], v[12:15]
	v_mfma_f32_16x16x32_bf16 v[4:7], v[162:165], v[218:221], v[4:7]
	v_mfma_f32_16x16x32_bf16 v[60:63], v[158:161], v[198:201], v[60:63]
	v_mfma_f32_16x16x32_bf16 v[52:55], v[166:169], v[198:201], v[52:55]
	v_mfma_f32_16x16x32_bf16 v[44:47], v[158:161], v[206:209], v[44:47]
	v_mfma_f32_16x16x32_bf16 v[36:39], v[166:169], v[206:209], v[36:39]
	v_mfma_f32_16x16x32_bf16 v[28:31], v[158:161], v[214:217], v[28:31]
	v_mfma_f32_16x16x32_bf16 v[20:23], v[166:169], v[214:217], v[20:23]
	v_mfma_f32_16x16x32_bf16 v[12:15], v[158:161], v[222:225], v[12:15]
	v_mfma_f32_16x16x32_bf16 v[4:7], v[166:169], v[222:225], v[4:7]
	v_mfma_f32_16x16x32_bf16 v[56:59], v[170:173], v[190:193], v[56:59]
	v_mfma_f32_16x16x32_bf16 v[48:51], v[178:181], v[190:193], v[48:51]
	v_mfma_f32_16x16x32_bf16 v[40:43], v[170:173], v[202:205], v[40:43]
	v_mfma_f32_16x16x32_bf16 v[32:35], v[178:181], v[202:205], v[32:35]
	v_mfma_f32_16x16x32_bf16 v[24:27], v[170:173], v[210:213], v[24:27]
	v_mfma_f32_16x16x32_bf16 v[16:19], v[178:181], v[210:213], v[16:19]
	v_mfma_f32_16x16x32_bf16 v[8:11], v[170:173], v[218:221], v[8:11]
	v_mfma_f32_16x16x32_bf16 v[0:3], v[178:181], v[218:221], v[0:3]
	v_mfma_f32_16x16x32_bf16 v[56:59], v[174:177], v[198:201], v[56:59]
	v_mfma_f32_16x16x32_bf16 v[48:51], v[182:185], v[198:201], v[48:51]
	v_mfma_f32_16x16x32_bf16 v[40:43], v[174:177], v[206:209], v[40:43]
	v_mfma_f32_16x16x32_bf16 v[32:35], v[182:185], v[206:209], v[32:35]
	v_mfma_f32_16x16x32_bf16 v[24:27], v[174:177], v[214:217], v[24:27]
	v_mfma_f32_16x16x32_bf16 v[16:19], v[182:185], v[214:217], v[16:19]
	v_mfma_f32_16x16x32_bf16 v[8:11], v[174:177], v[222:225], v[8:11]
	v_mfma_f32_16x16x32_bf16 v[0:3], v[182:185], v[222:225], v[0:3]
	s_barrier
	s_add_i32 s63, s63, 2
	s_add_u32 s24, s24, 0x100
	s_addc_u32 s25, s25, 0
	s_add_u32 s61, s61, 0x100
	s_addc_u32 s62, s62, 0
	s_cmp_gt_u32 s63, 13
	s_cbranch_scc0 .LBB0_153

; #define PG8_STAGE(bufoff, gbase, voff) do { _Pragma("unroll") for (int _i = 0; _i < 2; ++_i) \
;         __builtin_amdgcn_global_load_lds((const unsigned*)((const char*)(gbase) + (voff)[_i]), (LAS unsigned*)(lds + (bufoff) + ldsw + _i * 8192), 16, 0, 0); } while (0)
; #define PG8_LDA(dst, b, h) do { _Pragma("unroll") for (int m = 0; m < 4; ++m) _Pragma("unroll") for (int k = 0; k < 2; ++k) dst[m][k] = *(const LAS bf16x8*)(lds + PG8_SA(b, h) + aoff + m * 2048 + k * 1024); } while (0)
; #define PG8_LDB(dst, b, h) do { _Pragma("unroll") for (int n = 0; n < 2; ++n) _Pragma("unroll") for (int k = 0; k < 2; ++k) dst[n][k] = *(const LAS bf16x8*)(lds + PG8_SB(b, h) + boff + n * 2048 + k * 1024); } while (0)
; #define PG8_MMA(ai, bj, At, Bt) do { __builtin_amdgcn_s_setprio(1); _Pragma("unroll") for (int m = 0; m < 4; ++m) _Pragma("unroll") for (int n = 0; n < 2; ++n) _Pragma("unroll") for (int k = 0; k < 2; ++k) \
;         acc[ai][bj][m][n] = __builtin_amdgcn_mfma_f32_16x16x32_bf16(Bt[n][k], At[m][k], acc[ai][bj][m][n], 0, 0, 0); __builtin_amdgcn_s_setprio(0); } while (0)
; #define PG8_WAIT_V(n) asm volatile("s_waitcnt vmcnt(" #n ")" ::: "memory")
; #define PG8_WAIT_L(n) asm volatile("s_waitcnt lgkmcnt(" #n ")" ::: "memory")
; template <class Epi>
; __device__ __forceinline__ void gemm_phase(LAS unsigned char* lds, const Gemm g, const StaticOrder& S, const Epi& E) {
;     ...
;         const bool has_next = S.next(ui + 1, nxt);
;         const char* nA = has_next ? (const char*)g.A + (size_t)(nxt.pm >> 5) * aslab + (size_t)(nxt.pm & 31) * tstepA : cA; const char* nB = has_next ? (const char*)g.Bt + (size_t)nxt.pn * tstepB : cB;
;         for (int t = 0; t < nt; t += 2) {
;             const bool last = (t == nt - 2);
;             const char* a1 = cA + (size_t)(t + 1) * kstep;
;             const char* a2 = last ? nA : cA + (size_t)(t + 2) * kstep; const char* b2 = last ? nB : cB + (size_t)(t + 2) * kstep;
;             const char* a3 = a2 + kstep; const char* b3 = b2 + kstep;
;             PG8_LDB(B0, 0, 0); PG8_LDB(B1, 0, 1); PG8_SCHED; PG8_LDA(At, 0, 0); PG8_STAGE(PG8_SA(1, 1), a1 + hstepA, voffA);
;             PG8_WAIT_V(8); PG8_WAIT_L(0); PG8_BAR; PG8_MMA(0, 0, At, B0); PG8_MMA(0, 1, At, B1); PG8_BAR; PG8_SCHED;
;             PG8_LDA(At, 0, 1); PG8_STAGE(PG8_SB(0, 0), b2, voffB); PG8_STAGE(PG8_SB(0, 1), b2 + hstepB, voffB); PG8_STAGE(PG8_SA(0, 0), a2, voffA);
.LBB0_256:
	s_add_u32 s50, s8, 0x100
	s_addc_u32 s51, s9, 0
	s_mov_b32 s52, -2
	s_waitcnt lgkmcnt(0)
	ds_read_b128 v[128:131], v187
	ds_read_b128 v[132:135], v187 offset:1024
	ds_read_b128 v[136:139], v187 offset:2048
	ds_read_b128 v[140:143], v187 offset:3072
	ds_read_b128 v[144:147], v188
	ds_read_b128 v[148:151], v188 offset:1024
	ds_read_b128 v[166:169], v188 offset:2048
	ds_read_b128 v[170:173], v188 offset:3072
	s_add_u32 s8, s2, 0x100
	s_addc_u32 s9, s3, 0
	s_cmp_eq_u32 s52, 40
	s_cselect_b32 s31, s1, s9
	s_cselect_b32 s30, s0, s8
	s_cselect_b32 s27, s25, s51
	s_cselect_b32 s26, s24, s50
	v_lshl_add_u64 v[182:183], s[2:3], 0, v[160:161]
	s_add_i32 m0, s35, 0xc000
	ds_read_b128 v[174:177], v190
	ds_read_b128 v[178:181], v190 offset:1024
	ds_read_b128 v[192:195], v190 offset:2048
	ds_read_b128 v[198:201], v190 offset:3072
	ds_read_b128 v[202:205], v190 offset:4096
	ds_read_b128 v[206:209], v190 offset:5120
	ds_read_b128 v[210:213], v190 offset:6144
	ds_read_b128 v[214:217], v190 offset:7168
	global_load_lds_dwordx4 v[182:183], off
	v_lshl_add_u64 v[182:183], s[2:3], 0, v[162:163]
	s_add_i32 m0, s35, 0xe000
	s_nop 0
	global_load_lds_dwordx4 v[182:183], off
	s_waitcnt vmcnt(8)
	s_waitcnt lgkmcnt(0)
	s_barrier
	s_waitcnt lgkmcnt(0)
	v_mfma_f32_16x16x32_bf16 v[124:127], v[128:131], v[174:177], 0
	v_mfma_f32_16x16x32_bf16 v[120:123], v[136:139], v[174:177], 0
	v_mfma_f32_16x16x32_bf16 v[108:111], v[128:131], v[192:195], 0
	v_mfma_f32_16x16x32_bf16 v[104:107], v[136:139], v[192:195], 0
	v_mfma_f32_16x16x32_bf16 v[92:95], v[128:131], v[202:205], 0
	v_mfma_f32_16x16x32_bf16 v[88:91], v[136:139], v[202:205], 0
	v_mfma_f32_16x16x32_bf16 v[76:79], v[128:131], v[210:213], 0
	v_mfma_f32_16x16x32_bf16 v[72:75], v[136:139], v[210:213], 0
	v_mfma_f32_16x16x32_bf16 v[124:127], v[132:135], v[178:181], v[124:127]
	v_mfma_f32_16x16x32_bf16 v[120:123], v[140:143], v[178:181], v[120:123]
	v_mfma_f32_16x16x32_bf16 v[108:111], v[132:135], v[198:201], v[108:111]
	v_mfma_f32_16x16x32_bf16 v[104:107], v[140:143], v[198:201], v[104:107]
	v_mfma_f32_16x16x32_bf16 v[92:95], v[132:135], v[206:209], v[92:95]
	v_mfma_f32_16x16x32_bf16 v[88:91], v[140:143], v[206:209], v[88:91]
	v_mfma_f32_16x16x32_bf16 v[76:79], v[132:135], v[214:217], v[76:79]
	v_mfma_f32_16x16x32_bf16 v[72:75], v[140:143], v[214:217], v[72:75]
	v_mfma_f32_16x16x32_bf16 v[116:119], v[144:147], v[174:177], 0
	v_mfma_f32_16x16x32_bf16 v[112:115], v[166:169], v[174:177], 0
	v_mfma_f32_16x16x32_bf16 v[100:103], v[144:147], v[192:195], 0
	v_mfma_f32_16x16x32_bf16 v[96:99], v[166:169], v[192:195], 0
	v_mfma_f32_16x16x32_bf16 v[84:87], v[144:147], v[202:205], 0
	v_mfma_f32_16x16x32_bf16 v[80:83], v[166:169], v[202:205], 0
	v_mfma_f32_16x16x32_bf16 v[68:71], v[144:147], v[210:213], 0
	v_mfma_f32_16x16x32_bf16 v[64:67], v[166:169], v[210:213], 0
	v_mfma_f32_16x16x32_bf16 v[116:119], v[148:151], v[178:181], v[116:119]
	v_mfma_f32_16x16x32_bf16 v[112:115], v[170:173], v[178:181], v[112:115]
	v_mfma_f32_16x16x32_bf16 v[100:103], v[148:151], v[198:201], v[100:103]
	v_mfma_f32_16x16x32_bf16 v[96:99], v[170:173], v[198:201], v[96:99]
	v_mfma_f32_16x16x32_bf16 v[84:87], v[148:151], v[206:209], v[84:87]
	v_mfma_f32_16x16x32_bf16 v[80:83], v[170:173], v[206:209], v[80:83]
	v_mfma_f32_16x16x32_bf16 v[68:71], v[148:151], v[214:217], v[68:71]
	v_mfma_f32_16x16x32_bf16 v[64:67], v[170:173], v[214:217], v[64:67]
	s_barrier
	s_add_i32 s2, s45, s34
	v_lshl_add_u64 v[182:183], s[26:27], 0, v[154:155]
	s_mov_b32 m0, s2
	ds_read_b128 v[174:177], v190 offset:16384
	ds_read_b128 v[178:181], v190 offset:17408
	ds_read_b128 v[192:195], v190 offset:18432
	ds_read_b128 v[198:201], v190 offset:19456
	ds_read_b128 v[202:205], v190 offset:20480
	ds_read_b128 v[206:209], v190 offset:21504
	ds_read_b128 v[210:213], v190 offset:22528
	ds_read_b128 v[214:217], v190 offset:23552
	global_load_lds_dwordx4 v[182:183], off
	s_add_i32 m0, s2, 0x2000
	s_add_u32 s2, s26, 0xb0000
	v_lshl_add_u64 v[218:219], s[26:27], 0, v[158:159]
	s_addc_u32 s3, s27, 0
	s_add_i32 s53, s46, s34
	global_load_lds_dwordx4 v[218:219], off
	v_lshl_add_u64 v[220:221], s[2:3], 0, v[154:155]
	s_mov_b32 m0, s53
	v_lshl_add_u64 v[222:223], s[30:31], 0, v[156:157]
	global_load_lds_dwordx4 v[220:221], off
	v_lshl_add_u64 v[220:221], s[2:3], 0, v[158:159]
	s_add_i32 m0, s53, 0x2000
	s_nop 0
	global_load_lds_dwordx4 v[220:221], off
	v_lshl_add_u64 v[220:221], s[30:31], 0, v[152:153]
	s_mov_b32 m0, s35
	s_nop 0
	global_load_lds_dwordx4 v[220:221], off
	s_mov_b32 m0, s36
	s_nop 0
	global_load_lds_dwordx4 v[222:223], off
	s_waitcnt vmcnt(8)
	s_waitcnt lgkmcnt(0)
	s_barrier
; #define PG8_STAGE(bufoff, gbase, voff) do { _Pragma("unroll") for (int _i = 0; _i < 2; ++_i) \
;         __builtin_amdgcn_global_load_lds((const unsigned*)((const char*)(gbase) + (voff)[_i]), (LAS unsigned*)(lds + (bufoff) + ldsw + _i * 8192), 16, 0, 0); } while (0)
; #define PG8_LDA(dst, b, h) do { _Pragma("unroll") for (int m = 0; m < 4; ++m) _Pragma("unroll") for (int k = 0; k < 2; ++k) dst[m][k] = *(const LAS bf16x8*)(lds + PG8_SA(b, h) + aoff + m * 2048 + k * 1024); } while (0)
; #define PG8_LDB(dst, b, h) do { _Pragma("unroll") for (int n = 0; n < 2; ++n) _Pragma("unroll") for (int k = 0; k < 2; ++k) dst[n][k] = *(const LAS bf16x8*)(lds + PG8_SB(b, h) + boff + n * 2048 + k * 1024); } while (0)
; #define PG8_MMA(ai, bj, At, Bt) do { __builtin_amdgcn_s_setprio(1); _Pragma("unroll") for (int m = 0; m < 4; ++m) _Pragma("unroll") for (int n = 0; n < 2; ++n) _Pragma("unroll") for (int k = 0; k < 2; ++k) \
;         acc[ai][bj][m][n] = __builtin_amdgcn_mfma_f32_16x16x32_bf16(Bt[n][k], At[m][k], acc[ai][bj][m][n], 0, 0, 0); __builtin_amdgcn_s_setprio(0); } while (0)
; #define PG8_WAIT_V(n) asm volatile("s_waitcnt vmcnt(" #n ")" ::: "memory")
; #define PG8_WAIT_L(n) asm volatile("s_waitcnt lgkmcnt(" #n ")" ::: "memory")
; #define PG8_BAR __builtin_amdgcn_s_barrier()
; #define PG8_SCHED __builtin_amdgcn_sched_barrier(0)
; template <class Epi>
; __device__ __forceinline__ void gemm_phase(LAS unsigned char* lds, const Gemm g, const StaticOrder& S, const Epi& E) {
;     ...
;             PG8_WAIT_V(8); PG8_WAIT_L(0); PG8_BAR; PG8_MMA(1, 0, At, B0); PG8_MMA(1, 1, At, B1); PG8_BAR; PG8_SCHED;
;             PG8_LDB(B0, 1, 0); PG8_LDB(B1, 1, 1); PG8_SCHED; PG8_LDA(At, 1, 0); PG8_STAGE(PG8_SA(0, 1), a2 + hstepA, voffA);
;             PG8_WAIT_V(8); PG8_WAIT_L(0); PG8_BAR; PG8_MMA(0, 0, At, B0); PG8_MMA(0, 1, At, B1); PG8_BAR; PG8_SCHED;
	s_waitcnt lgkmcnt(0)
	v_mfma_f32_16x16x32_bf16 v[60:63], v[128:131], v[174:177], 0
	v_mfma_f32_16x16x32_bf16 v[56:59], v[136:139], v[174:177], 0
	v_mfma_f32_16x16x32_bf16 v[44:47], v[128:131], v[192:195], 0
	v_mfma_f32_16x16x32_bf16 v[40:43], v[136:139], v[192:195], 0
	v_mfma_f32_16x16x32_bf16 v[28:31], v[128:131], v[202:205], 0
	v_mfma_f32_16x16x32_bf16 v[24:27], v[136:139], v[202:205], 0
	v_mfma_f32_16x16x32_bf16 v[12:15], v[128:131], v[210:213], 0
	v_mfma_f32_16x16x32_bf16 v[8:11], v[136:139], v[210:213], 0
	v_mfma_f32_16x16x32_bf16 v[60:63], v[132:135], v[178:181], v[60:63]
	v_mfma_f32_16x16x32_bf16 v[56:59], v[140:143], v[178:181], v[56:59]
	v_mfma_f32_16x16x32_bf16 v[44:47], v[132:135], v[198:201], v[44:47]
	v_mfma_f32_16x16x32_bf16 v[40:43], v[140:143], v[198:201], v[40:43]
	v_mfma_f32_16x16x32_bf16 v[28:31], v[132:135], v[206:209], v[28:31]
	v_mfma_f32_16x16x32_bf16 v[24:27], v[140:143], v[206:209], v[24:27]
	v_mfma_f32_16x16x32_bf16 v[12:15], v[132:135], v[214:217], v[12:15]
	v_mfma_f32_16x16x32_bf16 v[8:11], v[140:143], v[214:217], v[8:11]
	v_mfma_f32_16x16x32_bf16 v[52:55], v[144:147], v[174:177], 0
	v_mfma_f32_16x16x32_bf16 v[48:51], v[166:169], v[174:177], 0
	v_mfma_f32_16x16x32_bf16 v[36:39], v[144:147], v[192:195], 0
	v_mfma_f32_16x16x32_bf16 v[32:35], v[166:169], v[192:195], 0
	v_mfma_f32_16x16x32_bf16 v[20:23], v[144:147], v[202:205], 0
	v_mfma_f32_16x16x32_bf16 v[16:19], v[166:169], v[202:205], 0
	v_mfma_f32_16x16x32_bf16 v[4:7], v[144:147], v[210:213], 0
	v_mfma_f32_16x16x32_bf16 v[0:3], v[166:169], v[210:213], 0
	v_mfma_f32_16x16x32_bf16 v[52:55], v[148:151], v[178:181], v[52:55]
	v_mfma_f32_16x16x32_bf16 v[48:51], v[170:173], v[178:181], v[48:51]
	v_mfma_f32_16x16x32_bf16 v[36:39], v[148:151], v[198:201], v[36:39]
	v_mfma_f32_16x16x32_bf16 v[32:35], v[170:173], v[198:201], v[32:35]
	v_mfma_f32_16x16x32_bf16 v[20:23], v[148:151], v[206:209], v[20:23]
	v_mfma_f32_16x16x32_bf16 v[16:19], v[170:173], v[206:209], v[16:19]
	v_mfma_f32_16x16x32_bf16 v[4:7], v[148:151], v[214:217], v[4:7]
	v_mfma_f32_16x16x32_bf16 v[0:3], v[170:173], v[214:217], v[0:3]
	s_barrier
	s_add_i32 s53, 0, 0x18000
	s_add_i32 s54, 0, 0x1c000
	v_add_u32_e32 v140, s53, v185
	v_add_u32_e32 v170, s54, v185
	ds_read_b128 v[128:131], v140
	ds_read_b128 v[132:135], v140 offset:1024
	ds_read_b128 v[136:139], v140 offset:2048
	ds_read_b128 v[140:143], v140 offset:3072
	ds_read_b128 v[144:147], v170
	ds_read_b128 v[148:151], v170 offset:1024
	ds_read_b128 v[166:169], v170 offset:2048
	ds_read_b128 v[170:173], v170 offset:3072
	s_add_u32 s2, s30, 0xb4000
	s_addc_u32 s3, s31, 0
	s_mov_b32 m0, s37
	v_lshl_add_u64 v[224:225], s[2:3], 0, v[152:153]
	ds_read_b128 v[174:177], v190 offset:32768
	ds_read_b128 v[178:181], v190 offset:33792
	ds_read_b128 v[192:195], v190 offset:34816
	ds_read_b128 v[198:201], v190 offset:35840
	ds_read_b128 v[202:205], v190 offset:36864
	ds_read_b128 v[206:209], v190 offset:37888
	ds_read_b128 v[210:213], v190 offset:38912
	ds_read_b128 v[214:217], v190 offset:39936
	global_load_lds_dwordx4 v[224:225], off
	v_lshl_add_u64 v[224:225], s[2:3], 0, v[156:157]
	s_mov_b32 m0, s38
	s_nop 0
	global_load_lds_dwordx4 v[224:225], off
	s_waitcnt vmcnt(8)
	s_waitcnt lgkmcnt(0)
	s_barrier
	s_waitcnt lgkmcnt(0)
	v_mfma_f32_16x16x32_bf16 v[124:127], v[128:131], v[174:177], v[124:127]
	v_mfma_f32_16x16x32_bf16 v[120:123], v[136:139], v[174:177], v[120:123]
	v_mfma_f32_16x16x32_bf16 v[108:111], v[128:131], v[192:195], v[108:111]
	v_mfma_f32_16x16x32_bf16 v[104:107], v[136:139], v[192:195], v[104:107]
	v_mfma_f32_16x16x32_bf16 v[92:95], v[128:131], v[202:205], v[92:95]
	v_mfma_f32_16x16x32_bf16 v[88:91], v[136:139], v[202:205], v[88:91]
	v_mfma_f32_16x16x32_bf16 v[76:79], v[128:131], v[210:213], v[76:79]
	v_mfma_f32_16x16x32_bf16 v[72:75], v[136:139], v[210:213], v[72:75]
	v_mfma_f32_16x16x32_bf16 v[124:127], v[132:135], v[178:181], v[124:127]
	v_mfma_f32_16x16x32_bf16 v[120:123], v[140:143], v[178:181], v[120:123]
	v_mfma_f32_16x16x32_bf16 v[108:111], v[132:135], v[198:201], v[108:111]
	v_mfma_f32_16x16x32_bf16 v[104:107], v[140:143], v[198:201], v[104:107]
	v_mfma_f32_16x16x32_bf16 v[92:95], v[132:135], v[206:209], v[92:95]
	v_mfma_f32_16x16x32_bf16 v[88:91], v[140:143], v[206:209], v[88:91]
	v_mfma_f32_16x16x32_bf16 v[76:79], v[132:135], v[214:217], v[76:79]
	v_mfma_f32_16x16x32_bf16 v[72:75], v[140:143], v[214:217], v[72:75]
	v_mfma_f32_16x16x32_bf16 v[116:119], v[144:147], v[174:177], v[116:119]
	v_mfma_f32_16x16x32_bf16 v[112:115], v[166:169], v[174:177], v[112:115]
	v_mfma_f32_16x16x32_bf16 v[100:103], v[144:147], v[192:195], v[100:103]
	v_mfma_f32_16x16x32_bf16 v[96:99], v[166:169], v[192:195], v[96:99]
	v_mfma_f32_16x16x32_bf16 v[84:87], v[144:147], v[202:205], v[84:87]
	v_mfma_f32_16x16x32_bf16 v[80:83], v[166:169], v[202:205], v[80:83]
	v_mfma_f32_16x16x32_bf16 v[68:71], v[144:147], v[210:213], v[68:71]
	v_mfma_f32_16x16x32_bf16 v[64:67], v[166:169], v[210:213], v[64:67]
	v_mfma_f32_16x16x32_bf16 v[116:119], v[148:151], v[178:181], v[116:119]
	v_mfma_f32_16x16x32_bf16 v[112:115], v[170:173], v[178:181], v[112:115]
	v_mfma_f32_16x16x32_bf16 v[100:103], v[148:151], v[198:201], v[100:103]
	v_mfma_f32_16x16x32_bf16 v[96:99], v[170:173], v[198:201], v[96:99]
	v_mfma_f32_16x16x32_bf16 v[84:87], v[148:151], v[206:209], v[84:87]
	v_mfma_f32_16x16x32_bf16 v[80:83], v[170:173], v[206:209], v[80:83]
	v_mfma_f32_16x16x32_bf16 v[68:71], v[148:151], v[214:217], v[68:71]
	v_mfma_f32_16x16x32_bf16 v[64:67], v[170:173], v[214:217], v[64:67]
	s_barrier
; #define PG8_STAGE(bufoff, gbase, voff) do { _Pragma("unroll") for (int _i = 0; _i < 2; ++_i) \
;         __builtin_amdgcn_global_load_lds((const unsigned*)((const char*)(gbase) + (voff)[_i]), (LAS unsigned*)(lds + (bufoff) + ldsw + _i * 8192), 16, 0, 0); } while (0)
; #define PG8_LDA(dst, b, h) do { _Pragma("unroll") for (int m = 0; m < 4; ++m) _Pragma("unroll") for (int k = 0; k < 2; ++k) dst[m][k] = *(const LAS bf16x8*)(lds + PG8_SA(b, h) + aoff + m * 2048 + k * 1024); } while (0)
; #define PG8_MMA(ai, bj, At, Bt) do { __builtin_amdgcn_s_setprio(1); _Pragma("unroll") for (int m = 0; m < 4; ++m) _Pragma("unroll") for (int n = 0; n < 2; ++n) _Pragma("unroll") for (int k = 0; k < 2; ++k) \
;         acc[ai][bj][m][n] = __builtin_amdgcn_mfma_f32_16x16x32_bf16(Bt[n][k], At[m][k], acc[ai][bj][m][n], 0, 0, 0); __builtin_amdgcn_s_setprio(0); } while (0)
; #define PG8_WAIT_V(n) asm volatile("s_waitcnt vmcnt(" #n ")" ::: "memory")
; #define PG8_WAIT_L(n) asm volatile("s_waitcnt lgkmcnt(" #n ")" ::: "memory")
; #define PG8_BAR __builtin_amdgcn_s_barrier()
; #define PG8_SCHED __builtin_amdgcn_sched_barrier(0)
; template <class Epi>
; __device__ __forceinline__ void gemm_phase(LAS unsigned char* lds, const Gemm g, const StaticOrder& S, const Epi& E) {
;     ...
;             PG8_LDA(At, 1, 1); PG8_STAGE(PG8_SB(1, 0), b3, voffB); PG8_STAGE(PG8_SB(1, 1), b3 + hstepB, voffB); PG8_STAGE(PG8_SA(1, 0), a3, voffA);
;             PG8_WAIT_V(8); PG8_WAIT_L(0); PG8_BAR; PG8_MMA(1, 0, At, B0); PG8_MMA(1, 1, At, B1); PG8_BAR; PG8_SCHED;
;         }
	s_add_i32 s2, s53, s34
	v_lshl_add_u64 v[182:183], v[182:183], 0, s[20:21]
	s_mov_b32 m0, s2
	ds_read_b128 v[174:177], v190 offset:49152
	ds_read_b128 v[178:181], v190 offset:50176
	ds_read_b128 v[192:195], v190 offset:51200
	ds_read_b128 v[198:201], v190 offset:52224
	ds_read_b128 v[202:205], v190 offset:53248
	ds_read_b128 v[206:209], v190 offset:54272
	ds_read_b128 v[210:213], v190 offset:55296
	ds_read_b128 v[214:217], v190 offset:56320
	global_load_lds_dwordx4 v[182:183], off
	s_add_i32 m0, s2, 0x2000
	s_add_u32 s2, s26, 0xb0080
	v_lshl_add_u64 v[182:183], v[218:219], 0, s[20:21]
	s_addc_u32 s3, s27, 0
	s_add_i32 s26, s54, s34
	global_load_lds_dwordx4 v[182:183], off
	v_lshl_add_u64 v[182:183], s[2:3], 0, v[154:155]
	s_mov_b32 m0, s26
	s_nop 0
	global_load_lds_dwordx4 v[182:183], off
	v_lshl_add_u64 v[182:183], s[2:3], 0, v[158:159]
	s_add_i32 m0, s26, 0x2000
	s_nop 0
	global_load_lds_dwordx4 v[182:183], off
	v_lshl_add_u64 v[182:183], v[220:221], 0, s[20:21]
	s_mov_b32 m0, s40
	s_nop 0
	global_load_lds_dwordx4 v[182:183], off
	v_lshl_add_u64 v[182:183], v[222:223], 0, s[20:21]
	s_mov_b32 m0, s41
	s_nop 0
	global_load_lds_dwordx4 v[182:183], off
	s_waitcnt vmcnt(8)
	s_waitcnt lgkmcnt(0)
	s_barrier
	s_waitcnt lgkmcnt(0)
	v_mfma_f32_16x16x32_bf16 v[60:63], v[128:131], v[174:177], v[60:63]
	v_mfma_f32_16x16x32_bf16 v[56:59], v[136:139], v[174:177], v[56:59]
	v_mfma_f32_16x16x32_bf16 v[44:47], v[128:131], v[192:195], v[44:47]
	v_mfma_f32_16x16x32_bf16 v[40:43], v[136:139], v[192:195], v[40:43]
	v_mfma_f32_16x16x32_bf16 v[28:31], v[128:131], v[202:205], v[28:31]
	v_mfma_f32_16x16x32_bf16 v[24:27], v[136:139], v[202:205], v[24:27]
	v_mfma_f32_16x16x32_bf16 v[12:15], v[128:131], v[210:213], v[12:15]
	v_mfma_f32_16x16x32_bf16 v[8:11], v[136:139], v[210:213], v[8:11]
	v_mfma_f32_16x16x32_bf16 v[60:63], v[132:135], v[178:181], v[60:63]
	v_mfma_f32_16x16x32_bf16 v[56:59], v[140:143], v[178:181], v[56:59]
	v_mfma_f32_16x16x32_bf16 v[44:47], v[132:135], v[198:201], v[44:47]
	v_mfma_f32_16x16x32_bf16 v[40:43], v[140:143], v[198:201], v[40:43]
	v_mfma_f32_16x16x32_bf16 v[28:31], v[132:135], v[206:209], v[28:31]
	v_mfma_f32_16x16x32_bf16 v[24:27], v[140:143], v[206:209], v[24:27]
	v_mfma_f32_16x16x32_bf16 v[12:15], v[132:135], v[214:217], v[12:15]
	v_mfma_f32_16x16x32_bf16 v[8:11], v[140:143], v[214:217], v[8:11]
	v_mfma_f32_16x16x32_bf16 v[52:55], v[144:147], v[174:177], v[52:55]
	v_mfma_f32_16x16x32_bf16 v[48:51], v[166:169], v[174:177], v[48:51]
	v_mfma_f32_16x16x32_bf16 v[36:39], v[144:147], v[192:195], v[36:39]
	v_mfma_f32_16x16x32_bf16 v[32:35], v[166:169], v[192:195], v[32:35]
	v_mfma_f32_16x16x32_bf16 v[20:23], v[144:147], v[202:205], v[20:23]
	v_mfma_f32_16x16x32_bf16 v[16:19], v[166:169], v[202:205], v[16:19]
	v_mfma_f32_16x16x32_bf16 v[4:7], v[144:147], v[210:213], v[4:7]
	v_mfma_f32_16x16x32_bf16 v[0:3], v[166:169], v[210:213], v[0:3]
	v_mfma_f32_16x16x32_bf16 v[52:55], v[148:151], v[178:181], v[52:55]
	v_mfma_f32_16x16x32_bf16 v[48:51], v[170:173], v[178:181], v[48:51]
	v_mfma_f32_16x16x32_bf16 v[36:39], v[148:151], v[198:201], v[36:39]
	v_mfma_f32_16x16x32_bf16 v[32:35], v[170:173], v[198:201], v[32:35]
	v_mfma_f32_16x16x32_bf16 v[20:23], v[148:151], v[206:209], v[20:23]
	v_mfma_f32_16x16x32_bf16 v[16:19], v[170:173], v[206:209], v[16:19]
	v_mfma_f32_16x16x32_bf16 v[4:7], v[148:151], v[214:217], v[4:7]
	v_mfma_f32_16x16x32_bf16 v[0:3], v[170:173], v[214:217], v[0:3]
	s_barrier
	s_add_i32 s52, s52, 2
	s_add_u32 s50, s50, 0x100
	s_addc_u32 s51, s51, 0
	s_cmp_gt_u32 s52, 41
	s_mov_b64 s[2:3], s[8:9]
	s_cbranch_scc0 .LBB0_257

; #define PG8_STAGE(bufoff, gbase, voff) do { _Pragma("unroll") for (int _i = 0; _i < 2; ++_i) \
;         __builtin_amdgcn_global_load_lds((const unsigned*)((const char*)(gbase) + (voff)[_i]), (LAS unsigned*)(lds + (bufoff) + ldsw + _i * 8192), 16, 0, 0); } while (0)
; #define PG8_LDA(dst, b, h) do { _Pragma("unroll") for (int m = 0; m < 4; ++m) _Pragma("unroll") for (int k = 0; k < 2; ++k) dst[m][k] = *(const LAS bf16x8*)(lds + PG8_SA(b, h) + aoff + m * 2048 + k * 1024); } while (0)
; #define PG8_LDB(dst, b, h) do { _Pragma("unroll") for (int n = 0; n < 2; ++n) _Pragma("unroll") for (int k = 0; k < 2; ++k) dst[n][k] = *(const LAS bf16x8*)(lds + PG8_SB(b, h) + boff + n * 2048 + k * 1024); } while (0)
; #define PG8_MMA(ai, bj, At, Bt) do { __builtin_amdgcn_s_setprio(1); _Pragma("unroll") for (int m = 0; m < 4; ++m) _Pragma("unroll") for (int n = 0; n < 2; ++n) _Pragma("unroll") for (int k = 0; k < 2; ++k) \
;         acc[ai][bj][m][n] = __builtin_amdgcn_mfma_f32_16x16x32_bf16(Bt[n][k], At[m][k], acc[ai][bj][m][n], 0, 0, 0); __builtin_amdgcn_s_setprio(0); } while (0)
; #define PG8_WAIT_V(n) asm volatile("s_waitcnt vmcnt(" #n ")" ::: "memory")
; #define PG8_WAIT_L(n) asm volatile("s_waitcnt lgkmcnt(" #n ")" ::: "memory")
; template <class Epi>
; __device__ __forceinline__ void gemm_phase(LAS unsigned char* lds, const Gemm g, const StaticOrder& S, const Epi& E) {
;     ...
;         const bool has_next = S.next(ui + 1, nxt);
;         const char* nA = has_next ? (const char*)g.A + (size_t)(nxt.pm >> 5) * aslab + (size_t)(nxt.pm & 31) * tstepA : cA; const char* nB = has_next ? (const char*)g.Bt + (size_t)nxt.pn * tstepB : cB;
;         for (int t = 0; t < nt; t += 2) {
;             const bool last = (t == nt - 2);
;             const char* a1 = cA + (size_t)(t + 1) * kstep;
;             const char* a2 = last ? nA : cA + (size_t)(t + 2) * kstep; const char* b2 = last ? nB : cB + (size_t)(t + 2) * kstep;
;             const char* a3 = a2 + kstep; const char* b3 = b2 + kstep;
;             PG8_LDB(B0, 0, 0); PG8_LDB(B1, 0, 1); PG8_SCHED; PG8_LDA(At, 0, 0); PG8_STAGE(PG8_SA(1, 1), a1 + hstepA, voffA);
;             PG8_WAIT_V(8); PG8_WAIT_L(0); PG8_BAR; PG8_MMA(0, 0, At, B0); PG8_MMA(0, 1, At, B1); PG8_BAR; PG8_SCHED;
;             PG8_LDA(At, 0, 1); PG8_STAGE(PG8_SB(0, 0), b2, voffB); PG8_STAGE(PG8_SB(0, 1), b2 + hstepB, voffB); PG8_STAGE(PG8_SA(0, 0), a2, voffA);
.LBB0_378:
	s_ashr_i32 s18, s42, 5
	s_ashr_i32 s19, s18, 31
	s_lshl_b64 s[18:19], s[18:19], 24
	v_readlane_b32 s20, v235, 38
	v_readlane_b32 s21, v235, 39
	s_add_u32 s17, s20, s18
	s_addc_u32 s19, s21, s19
	s_lshl_b32 s18, s42, 19
	s_and_b32 s18, s18, 0xf80000
	s_add_u32 s18, s17, s18
	s_addc_u32 s19, s19, 0
	s_and_b64 s[20:21], s[4:5], exec
	s_cselect_b32 s44, s19, s23
	s_cselect_b32 s45, s18, s22
	s_ashr_i32 s17, s16, 31
	s_lshl_b64 s[20:21], s[16:17], 19
	s_add_u32 s20, s10, s20
	s_addc_u32 s21, s11, s21
	s_and_b64 s[24:25], s[4:5], exec
	s_cselect_b32 s17, s21, s3
	s_cselect_b32 s46, s20, s2
	s_add_u32 s22, s22, 0x40080
	s_addc_u32 s23, s23, 0
	s_add_u32 s47, s2, 0x100
	s_addc_u32 s48, s3, 0
	s_mov_b32 s49, -2
	ds_read_b128 v[128:131], v198
	ds_read_b128 v[132:135], v198 offset:1024
	ds_read_b128 v[136:139], v198 offset:2048
	ds_read_b128 v[140:143], v198 offset:3072
	ds_read_b128 v[144:147], v199
	ds_read_b128 v[148:151], v199 offset:1024
	ds_read_b128 v[170:173], v199 offset:2048
	ds_read_b128 v[174:177], v199 offset:3072
	s_add_u32 s2, s22, 0xfffc0080
	s_addc_u32 s3, s23, -1
	s_cmp_eq_u32 s49, 12
	s_cselect_b32 s25, s44, s3
	s_cselect_b32 s24, s45, s2
	s_cselect_b32 s3, s17, s48
	s_cselect_b32 s2, s46, s47
	v_lshl_add_u64 v[186:187], s[22:23], 0, v[164:165]
	s_add_i32 m0, s28, 0xc000
	ds_read_b128 v[178:181], v200
	ds_read_b128 v[182:185], v200 offset:1024
	ds_read_b128 v[204:207], v200 offset:2048
	ds_read_b128 v[208:211], v200 offset:3072
	ds_read_b128 v[212:215], v200 offset:4096
	ds_read_b128 v[216:219], v200 offset:5120
	ds_read_b128 v[220:223], v200 offset:6144
	ds_read_b128 v[224:227], v200 offset:7168
	global_load_lds_dwordx4 v[186:187], off
	v_lshl_add_u64 v[186:187], s[22:23], 0, v[166:167]
	s_add_i32 m0, s28, 0xe000
	s_nop 0
	global_load_lds_dwordx4 v[186:187], off
	s_waitcnt vmcnt(8)
	s_waitcnt lgkmcnt(0)
	s_barrier
	s_waitcnt lgkmcnt(0)
	v_mfma_f32_16x16x32_bf16 v[124:127], v[128:131], v[178:181], 0
	v_mfma_f32_16x16x32_bf16 v[120:123], v[136:139], v[178:181], 0
	v_mfma_f32_16x16x32_bf16 v[108:111], v[128:131], v[204:207], 0
	v_mfma_f32_16x16x32_bf16 v[104:107], v[136:139], v[204:207], 0
	v_mfma_f32_16x16x32_bf16 v[92:95], v[128:131], v[212:215], 0
	v_mfma_f32_16x16x32_bf16 v[88:91], v[136:139], v[212:215], 0
	v_mfma_f32_16x16x32_bf16 v[76:79], v[128:131], v[220:223], 0
	v_mfma_f32_16x16x32_bf16 v[72:75], v[136:139], v[220:223], 0
	v_mfma_f32_16x16x32_bf16 v[124:127], v[132:135], v[182:185], v[124:127]
	v_mfma_f32_16x16x32_bf16 v[120:123], v[140:143], v[182:185], v[120:123]
	v_mfma_f32_16x16x32_bf16 v[108:111], v[132:135], v[208:211], v[108:111]
	v_mfma_f32_16x16x32_bf16 v[104:107], v[140:143], v[208:211], v[104:107]
	v_mfma_f32_16x16x32_bf16 v[92:95], v[132:135], v[216:219], v[92:95]
	v_mfma_f32_16x16x32_bf16 v[88:91], v[140:143], v[216:219], v[88:91]
	v_mfma_f32_16x16x32_bf16 v[76:79], v[132:135], v[224:227], v[76:79]
	v_mfma_f32_16x16x32_bf16 v[72:75], v[140:143], v[224:227], v[72:75]
	v_mfma_f32_16x16x32_bf16 v[116:119], v[144:147], v[178:181], 0
	v_mfma_f32_16x16x32_bf16 v[112:115], v[170:173], v[178:181], 0
	v_mfma_f32_16x16x32_bf16 v[100:103], v[144:147], v[204:207], 0
	v_mfma_f32_16x16x32_bf16 v[96:99], v[170:173], v[204:207], 0
	v_mfma_f32_16x16x32_bf16 v[84:87], v[144:147], v[212:215], 0
	v_mfma_f32_16x16x32_bf16 v[80:83], v[170:173], v[212:215], 0
	v_mfma_f32_16x16x32_bf16 v[68:71], v[144:147], v[220:223], 0
	v_mfma_f32_16x16x32_bf16 v[64:67], v[170:173], v[220:223], 0
	v_mfma_f32_16x16x32_bf16 v[116:119], v[148:151], v[182:185], v[116:119]
	v_mfma_f32_16x16x32_bf16 v[112:115], v[174:177], v[182:185], v[112:115]
	v_mfma_f32_16x16x32_bf16 v[100:103], v[148:151], v[208:211], v[100:103]
	v_mfma_f32_16x16x32_bf16 v[96:99], v[174:177], v[208:211], v[96:99]
	v_mfma_f32_16x16x32_bf16 v[84:87], v[148:151], v[216:219], v[84:87]
	v_mfma_f32_16x16x32_bf16 v[80:83], v[174:177], v[216:219], v[80:83]
	v_mfma_f32_16x16x32_bf16 v[68:71], v[148:151], v[224:227], v[68:71]
	v_mfma_f32_16x16x32_bf16 v[64:67], v[174:177], v[224:227], v[64:67]
	s_barrier
	s_add_i32 s50, s39, s26
	v_lshl_add_u64 v[186:187], s[2:3], 0, v[156:157]
	s_mov_b32 m0, s50
	ds_read_b128 v[178:181], v200 offset:16384
	ds_read_b128 v[182:185], v200 offset:17408
	ds_read_b128 v[204:207], v200 offset:18432
	ds_read_b128 v[208:211], v200 offset:19456
	ds_read_b128 v[212:215], v200 offset:20480
	ds_read_b128 v[216:219], v200 offset:21504
	ds_read_b128 v[220:223], v200 offset:22528
	ds_read_b128 v[224:227], v200 offset:23552
	global_load_lds_dwordx4 v[186:187], off
	s_add_i32 m0, s50, 0x2000
	s_add_u32 s50, s2, 0x40000
	v_lshl_add_u64 v[190:191], s[2:3], 0, v[152:153]
	s_addc_u32 s51, s3, 0
	s_add_i32 s52, s40, s26
	global_load_lds_dwordx4 v[190:191], off
	v_lshl_add_u64 v[228:229], s[50:51], 0, v[156:157]
	s_mov_b32 m0, s52
	v_lshl_add_u64 v[230:231], s[24:25], 0, v[154:155]
	global_load_lds_dwordx4 v[228:229], off
	v_lshl_add_u64 v[228:229], s[50:51], 0, v[152:153]
	s_add_i32 m0, s52, 0x2000
	s_nop 0
	global_load_lds_dwordx4 v[228:229], off
	v_lshl_add_u64 v[228:229], s[24:25], 0, v[158:159]
	s_mov_b32 m0, s28
	s_nop 0
	global_load_lds_dwordx4 v[228:229], off
	s_mov_b32 m0, s29
	s_nop 0
	global_load_lds_dwordx4 v[230:231], off
	s_waitcnt vmcnt(8)
	s_waitcnt lgkmcnt(0)
	s_barrier
; #define PG8_STAGE(bufoff, gbase, voff) do { _Pragma("unroll") for (int _i = 0; _i < 2; ++_i) \
;         __builtin_amdgcn_global_load_lds((const unsigned*)((const char*)(gbase) + (voff)[_i]), (LAS unsigned*)(lds + (bufoff) + ldsw + _i * 8192), 16, 0, 0); } while (0)
; #define PG8_LDA(dst, b, h) do { _Pragma("unroll") for (int m = 0; m < 4; ++m) _Pragma("unroll") for (int k = 0; k < 2; ++k) dst[m][k] = *(const LAS bf16x8*)(lds + PG8_SA(b, h) + aoff + m * 2048 + k * 1024); } while (0)
; #define PG8_LDB(dst, b, h) do { _Pragma("unroll") for (int n = 0; n < 2; ++n) _Pragma("unroll") for (int k = 0; k < 2; ++k) dst[n][k] = *(const LAS bf16x8*)(lds + PG8_SB(b, h) + boff + n * 2048 + k * 1024); } while (0)
; #define PG8_MMA(ai, bj, At, Bt) do { __builtin_amdgcn_s_setprio(1); _Pragma("unroll") for (int m = 0; m < 4; ++m) _Pragma("unroll") for (int n = 0; n < 2; ++n) _Pragma("unroll") for (int k = 0; k < 2; ++k) \
;         acc[ai][bj][m][n] = __builtin_amdgcn_mfma_f32_16x16x32_bf16(Bt[n][k], At[m][k], acc[ai][bj][m][n], 0, 0, 0); __builtin_amdgcn_s_setprio(0); } while (0)
; #define PG8_WAIT_V(n) asm volatile("s_waitcnt vmcnt(" #n ")" ::: "memory")
; #define PG8_WAIT_L(n) asm volatile("s_waitcnt lgkmcnt(" #n ")" ::: "memory")
; #define PG8_BAR __builtin_amdgcn_s_barrier()
; #define PG8_SCHED __builtin_amdgcn_sched_barrier(0)
; template <class Epi>
; __device__ __forceinline__ void gemm_phase(LAS unsigned char* lds, const Gemm g, const StaticOrder& S, const Epi& E) {
;     ...
;             PG8_WAIT_V(8); PG8_WAIT_L(0); PG8_BAR; PG8_MMA(1, 0, At, B0); PG8_MMA(1, 1, At, B1); PG8_BAR; PG8_SCHED;
;             PG8_LDB(B0, 1, 0); PG8_LDB(B1, 1, 1); PG8_SCHED; PG8_LDA(At, 1, 0); PG8_STAGE(PG8_SA(0, 1), a2 + hstepA, voffA);
;             PG8_WAIT_V(8); PG8_WAIT_L(0); PG8_BAR; PG8_MMA(0, 0, At, B0); PG8_MMA(0, 1, At, B1); PG8_BAR; PG8_SCHED;
	s_waitcnt lgkmcnt(0)
	v_mfma_f32_16x16x32_bf16 v[60:63], v[128:131], v[178:181], 0
	v_mfma_f32_16x16x32_bf16 v[56:59], v[136:139], v[178:181], 0
	v_mfma_f32_16x16x32_bf16 v[44:47], v[128:131], v[204:207], 0
	v_mfma_f32_16x16x32_bf16 v[40:43], v[136:139], v[204:207], 0
	v_mfma_f32_16x16x32_bf16 v[28:31], v[128:131], v[212:215], 0
	v_mfma_f32_16x16x32_bf16 v[24:27], v[136:139], v[212:215], 0
	v_mfma_f32_16x16x32_bf16 v[12:15], v[128:131], v[220:223], 0
	v_mfma_f32_16x16x32_bf16 v[8:11], v[136:139], v[220:223], 0
	v_mfma_f32_16x16x32_bf16 v[60:63], v[132:135], v[182:185], v[60:63]
	v_mfma_f32_16x16x32_bf16 v[56:59], v[140:143], v[182:185], v[56:59]
	v_mfma_f32_16x16x32_bf16 v[44:47], v[132:135], v[208:211], v[44:47]
	v_mfma_f32_16x16x32_bf16 v[40:43], v[140:143], v[208:211], v[40:43]
	v_mfma_f32_16x16x32_bf16 v[28:31], v[132:135], v[216:219], v[28:31]
	v_mfma_f32_16x16x32_bf16 v[24:27], v[140:143], v[216:219], v[24:27]
	v_mfma_f32_16x16x32_bf16 v[12:15], v[132:135], v[224:227], v[12:15]
	v_mfma_f32_16x16x32_bf16 v[8:11], v[140:143], v[224:227], v[8:11]
	v_mfma_f32_16x16x32_bf16 v[52:55], v[144:147], v[178:181], 0
	v_mfma_f32_16x16x32_bf16 v[48:51], v[170:173], v[178:181], 0
	v_mfma_f32_16x16x32_bf16 v[36:39], v[144:147], v[204:207], 0
	v_mfma_f32_16x16x32_bf16 v[32:35], v[170:173], v[204:207], 0
	v_mfma_f32_16x16x32_bf16 v[20:23], v[144:147], v[212:215], 0
	v_mfma_f32_16x16x32_bf16 v[16:19], v[170:173], v[212:215], 0
	v_mfma_f32_16x16x32_bf16 v[4:7], v[144:147], v[220:223], 0
	v_mfma_f32_16x16x32_bf16 v[0:3], v[170:173], v[220:223], 0
	v_mfma_f32_16x16x32_bf16 v[52:55], v[148:151], v[182:185], v[52:55]
	v_mfma_f32_16x16x32_bf16 v[48:51], v[174:177], v[182:185], v[48:51]
	v_mfma_f32_16x16x32_bf16 v[36:39], v[148:151], v[208:211], v[36:39]
	v_mfma_f32_16x16x32_bf16 v[32:35], v[174:177], v[208:211], v[32:35]
	v_mfma_f32_16x16x32_bf16 v[20:23], v[148:151], v[216:219], v[20:23]
	v_mfma_f32_16x16x32_bf16 v[16:19], v[174:177], v[216:219], v[16:19]
	v_mfma_f32_16x16x32_bf16 v[4:7], v[148:151], v[224:227], v[4:7]
	v_mfma_f32_16x16x32_bf16 v[0:3], v[174:177], v[224:227], v[0:3]
	s_barrier
	s_add_i32 s50, 0, 0x18000
	s_add_i32 s51, 0, 0x1c000
	v_add_u32_e32 v140, s50, v195
	v_add_u32_e32 v160, s51, v195
	ds_read_b128 v[128:131], v140
	ds_read_b128 v[132:135], v140 offset:1024
	ds_read_b128 v[136:139], v140 offset:2048
	ds_read_b128 v[140:143], v140 offset:3072
	ds_read_b128 v[144:147], v160
	ds_read_b128 v[148:151], v160 offset:1024
	ds_read_b128 v[170:173], v160 offset:2048
	ds_read_b128 v[174:177], v160 offset:3072
	s_add_u32 s24, s24, 0x40000
	s_addc_u32 s25, s25, 0
	s_mov_b32 m0, s30
	v_lshl_add_u64 v[232:233], s[24:25], 0, v[158:159]
	ds_read_b128 v[178:181], v200 offset:32768
	ds_read_b128 v[182:185], v200 offset:33792
	ds_read_b128 v[204:207], v200 offset:34816
	ds_read_b128 v[208:211], v200 offset:35840
	ds_read_b128 v[212:215], v200 offset:36864
	ds_read_b128 v[216:219], v200 offset:37888
	ds_read_b128 v[220:223], v200 offset:38912
	ds_read_b128 v[224:227], v200 offset:39936
	global_load_lds_dwordx4 v[232:233], off
	v_lshl_add_u64 v[232:233], s[24:25], 0, v[154:155]
	s_mov_b32 m0, s31
	s_nop 0
	global_load_lds_dwordx4 v[232:233], off
	s_waitcnt vmcnt(8)
	s_waitcnt lgkmcnt(0)
	s_barrier
	s_waitcnt lgkmcnt(0)
	v_mfma_f32_16x16x32_bf16 v[124:127], v[128:131], v[178:181], v[124:127]
	v_mfma_f32_16x16x32_bf16 v[120:123], v[136:139], v[178:181], v[120:123]
	v_mfma_f32_16x16x32_bf16 v[108:111], v[128:131], v[204:207], v[108:111]
	v_mfma_f32_16x16x32_bf16 v[104:107], v[136:139], v[204:207], v[104:107]
	v_mfma_f32_16x16x32_bf16 v[92:95], v[128:131], v[212:215], v[92:95]
	v_mfma_f32_16x16x32_bf16 v[88:91], v[136:139], v[212:215], v[88:91]
	v_mfma_f32_16x16x32_bf16 v[76:79], v[128:131], v[220:223], v[76:79]
	v_mfma_f32_16x16x32_bf16 v[72:75], v[136:139], v[220:223], v[72:75]
	v_mfma_f32_16x16x32_bf16 v[124:127], v[132:135], v[182:185], v[124:127]
	v_mfma_f32_16x16x32_bf16 v[120:123], v[140:143], v[182:185], v[120:123]
	v_mfma_f32_16x16x32_bf16 v[108:111], v[132:135], v[208:211], v[108:111]
	v_mfma_f32_16x16x32_bf16 v[104:107], v[140:143], v[208:211], v[104:107]
	v_mfma_f32_16x16x32_bf16 v[92:95], v[132:135], v[216:219], v[92:95]
	v_mfma_f32_16x16x32_bf16 v[88:91], v[140:143], v[216:219], v[88:91]
	v_mfma_f32_16x16x32_bf16 v[76:79], v[132:135], v[224:227], v[76:79]
	v_mfma_f32_16x16x32_bf16 v[72:75], v[140:143], v[224:227], v[72:75]
	v_mfma_f32_16x16x32_bf16 v[116:119], v[144:147], v[178:181], v[116:119]
	v_mfma_f32_16x16x32_bf16 v[112:115], v[170:173], v[178:181], v[112:115]
	v_mfma_f32_16x16x32_bf16 v[100:103], v[144:147], v[204:207], v[100:103]
	v_mfma_f32_16x16x32_bf16 v[96:99], v[170:173], v[204:207], v[96:99]
	v_mfma_f32_16x16x32_bf16 v[84:87], v[144:147], v[212:215], v[84:87]
	v_mfma_f32_16x16x32_bf16 v[80:83], v[170:173], v[212:215], v[80:83]
	v_mfma_f32_16x16x32_bf16 v[68:71], v[144:147], v[220:223], v[68:71]
	v_mfma_f32_16x16x32_bf16 v[64:67], v[170:173], v[220:223], v[64:67]
	v_mfma_f32_16x16x32_bf16 v[116:119], v[148:151], v[182:185], v[116:119]
	v_mfma_f32_16x16x32_bf16 v[112:115], v[174:177], v[182:185], v[112:115]
	v_mfma_f32_16x16x32_bf16 v[100:103], v[148:151], v[208:211], v[100:103]
	v_mfma_f32_16x16x32_bf16 v[96:99], v[174:177], v[208:211], v[96:99]
	v_mfma_f32_16x16x32_bf16 v[84:87], v[148:151], v[216:219], v[84:87]
	v_mfma_f32_16x16x32_bf16 v[80:83], v[174:177], v[216:219], v[80:83]
	v_mfma_f32_16x16x32_bf16 v[68:71], v[148:151], v[224:227], v[68:71]
	v_mfma_f32_16x16x32_bf16 v[64:67], v[174:177], v[224:227], v[64:67]
	s_barrier
; #define PG8_STAGE(bufoff, gbase, voff) do { _Pragma("unroll") for (int _i = 0; _i < 2; ++_i) \
;         __builtin_amdgcn_global_load_lds((const unsigned*)((const char*)(gbase) + (voff)[_i]), (LAS unsigned*)(lds + (bufoff) + ldsw + _i * 8192), 16, 0, 0); } while (0)
; #define PG8_LDA(dst, b, h) do { _Pragma("unroll") for (int m = 0; m < 4; ++m) _Pragma("unroll") for (int k = 0; k < 2; ++k) dst[m][k] = *(const LAS bf16x8*)(lds + PG8_SA(b, h) + aoff + m * 2048 + k * 1024); } while (0)
; #define PG8_MMA(ai, bj, At, Bt) do { __builtin_amdgcn_s_setprio(1); _Pragma("unroll") for (int m = 0; m < 4; ++m) _Pragma("unroll") for (int n = 0; n < 2; ++n) _Pragma("unroll") for (int k = 0; k < 2; ++k) \
;         acc[ai][bj][m][n] = __builtin_amdgcn_mfma_f32_16x16x32_bf16(Bt[n][k], At[m][k], acc[ai][bj][m][n], 0, 0, 0); __builtin_amdgcn_s_setprio(0); } while (0)
; #define PG8_WAIT_V(n) asm volatile("s_waitcnt vmcnt(" #n ")" ::: "memory")
; #define PG8_WAIT_L(n) asm volatile("s_waitcnt lgkmcnt(" #n ")" ::: "memory")
; #define PG8_BAR __builtin_amdgcn_s_barrier()
; #define PG8_SCHED __builtin_amdgcn_sched_barrier(0)
; template <class Epi>
; __device__ __forceinline__ void gemm_phase(LAS unsigned char* lds, const Gemm g, const StaticOrder& S, const Epi& E) {
;     ...
;             PG8_LDA(At, 1, 1); PG8_STAGE(PG8_SB(1, 0), b3, voffB); PG8_STAGE(PG8_SB(1, 1), b3 + hstepB, voffB); PG8_STAGE(PG8_SA(1, 0), a3, voffA);
;             PG8_WAIT_V(8); PG8_WAIT_L(0); PG8_BAR; PG8_MMA(1, 0, At, B0); PG8_MMA(1, 1, At, B1); PG8_BAR; PG8_SCHED;
;         }
	s_add_i32 s24, s50, s26
	v_lshl_add_u64 v[186:187], v[186:187], 0, s[6:7]
	s_mov_b32 m0, s24
	ds_read_b128 v[178:181], v200 offset:49152
	ds_read_b128 v[182:185], v200 offset:50176
	ds_read_b128 v[204:207], v200 offset:51200
	ds_read_b128 v[208:211], v200 offset:52224
	ds_read_b128 v[212:215], v200 offset:53248
	ds_read_b128 v[216:219], v200 offset:54272
	ds_read_b128 v[220:223], v200 offset:55296
	ds_read_b128 v[224:227], v200 offset:56320
	global_load_lds_dwordx4 v[186:187], off
	s_add_i32 m0, s24, 0x2000
	s_add_u32 s2, s2, 0x40080
	v_lshl_add_u64 v[186:187], v[190:191], 0, s[6:7]
	s_addc_u32 s3, s3, 0
	s_add_i32 s24, s51, s26
	global_load_lds_dwordx4 v[186:187], off
	v_lshl_add_u64 v[186:187], s[2:3], 0, v[156:157]
	s_mov_b32 m0, s24
	s_nop 0
	global_load_lds_dwordx4 v[186:187], off
	v_lshl_add_u64 v[186:187], s[2:3], 0, v[152:153]
	s_add_i32 m0, s24, 0x2000
	s_nop 0
	global_load_lds_dwordx4 v[186:187], off
	v_lshl_add_u64 v[186:187], v[228:229], 0, s[6:7]
	s_mov_b32 m0, s35
	s_nop 0
	global_load_lds_dwordx4 v[186:187], off
	v_lshl_add_u64 v[186:187], v[230:231], 0, s[6:7]
	s_mov_b32 m0, s36
	s_nop 0
	global_load_lds_dwordx4 v[186:187], off
	s_waitcnt vmcnt(8)
	s_waitcnt lgkmcnt(0)
	s_barrier
	s_waitcnt lgkmcnt(0)
	v_mfma_f32_16x16x32_bf16 v[60:63], v[128:131], v[178:181], v[60:63]
	v_mfma_f32_16x16x32_bf16 v[56:59], v[136:139], v[178:181], v[56:59]
	v_mfma_f32_16x16x32_bf16 v[44:47], v[128:131], v[204:207], v[44:47]
	v_mfma_f32_16x16x32_bf16 v[40:43], v[136:139], v[204:207], v[40:43]
	v_mfma_f32_16x16x32_bf16 v[28:31], v[128:131], v[212:215], v[28:31]
	v_mfma_f32_16x16x32_bf16 v[24:27], v[136:139], v[212:215], v[24:27]
	v_mfma_f32_16x16x32_bf16 v[12:15], v[128:131], v[220:223], v[12:15]
	v_mfma_f32_16x16x32_bf16 v[8:11], v[136:139], v[220:223], v[8:11]
	v_mfma_f32_16x16x32_bf16 v[60:63], v[132:135], v[182:185], v[60:63]
	v_mfma_f32_16x16x32_bf16 v[56:59], v[140:143], v[182:185], v[56:59]
	v_mfma_f32_16x16x32_bf16 v[44:47], v[132:135], v[208:211], v[44:47]
	v_mfma_f32_16x16x32_bf16 v[40:43], v[140:143], v[208:211], v[40:43]
	v_mfma_f32_16x16x32_bf16 v[28:31], v[132:135], v[216:219], v[28:31]
	v_mfma_f32_16x16x32_bf16 v[24:27], v[140:143], v[216:219], v[24:27]
	v_mfma_f32_16x16x32_bf16 v[12:15], v[132:135], v[224:227], v[12:15]
	v_mfma_f32_16x16x32_bf16 v[8:11], v[140:143], v[224:227], v[8:11]
	v_mfma_f32_16x16x32_bf16 v[52:55], v[144:147], v[178:181], v[52:55]
	v_mfma_f32_16x16x32_bf16 v[48:51], v[170:173], v[178:181], v[48:51]
	v_mfma_f32_16x16x32_bf16 v[36:39], v[144:147], v[204:207], v[36:39]
	v_mfma_f32_16x16x32_bf16 v[32:35], v[170:173], v[204:207], v[32:35]
	v_mfma_f32_16x16x32_bf16 v[20:23], v[144:147], v[212:215], v[20:23]
	v_mfma_f32_16x16x32_bf16 v[16:19], v[170:173], v[212:215], v[16:19]
	v_mfma_f32_16x16x32_bf16 v[4:7], v[144:147], v[220:223], v[4:7]
	v_mfma_f32_16x16x32_bf16 v[0:3], v[170:173], v[220:223], v[0:3]
	v_mfma_f32_16x16x32_bf16 v[52:55], v[148:151], v[182:185], v[52:55]
	v_mfma_f32_16x16x32_bf16 v[48:51], v[174:177], v[182:185], v[48:51]
	v_mfma_f32_16x16x32_bf16 v[36:39], v[148:151], v[208:211], v[36:39]
	v_mfma_f32_16x16x32_bf16 v[32:35], v[174:177], v[208:211], v[32:35]
	v_mfma_f32_16x16x32_bf16 v[20:23], v[148:151], v[216:219], v[20:23]
	v_mfma_f32_16x16x32_bf16 v[16:19], v[174:177], v[216:219], v[16:19]
	v_mfma_f32_16x16x32_bf16 v[4:7], v[148:151], v[224:227], v[4:7]
	v_mfma_f32_16x16x32_bf16 v[0:3], v[174:177], v[224:227], v[0:3]
	s_barrier
	s_add_i32 s49, s49, 2
	s_add_u32 s22, s22, 0x100
	s_addc_u32 s23, s23, 0
	s_add_u32 s47, s47, 0x100
	s_addc_u32 s48, s48, 0
	s_cmp_gt_u32 s49, 13
	s_cbranch_scc0 .LBB0_379

; #define PG8_STAGE(bufoff, gbase, voff) do { _Pragma("unroll") for (int _i = 0; _i < 2; ++_i) \
;         __builtin_amdgcn_global_load_lds((const unsigned*)((const char*)(gbase) + (voff)[_i]), (LAS unsigned*)(lds + (bufoff) + ldsw + _i * 8192), 16, 0, 0); } while (0)
; #define PG8_LDA(dst, b, h) do { _Pragma("unroll") for (int m = 0; m < 4; ++m) _Pragma("unroll") for (int k = 0; k < 2; ++k) dst[m][k] = *(const LAS bf16x8*)(lds + PG8_SA(b, h) + aoff + m * 2048 + k * 1024); } while (0)
; #define PG8_LDB(dst, b, h) do { _Pragma("unroll") for (int n = 0; n < 2; ++n) _Pragma("unroll") for (int k = 0; k < 2; ++k) dst[n][k] = *(const LAS bf16x8*)(lds + PG8_SB(b, h) + boff + n * 2048 + k * 1024); } while (0)
; #define PG8_MMA(ai, bj, At, Bt) do { __builtin_amdgcn_s_setprio(1); _Pragma("unroll") for (int m = 0; m < 4; ++m) _Pragma("unroll") for (int n = 0; n < 2; ++n) _Pragma("unroll") for (int k = 0; k < 2; ++k) \
;         acc[ai][bj][m][n] = __builtin_amdgcn_mfma_f32_16x16x32_bf16(Bt[n][k], At[m][k], acc[ai][bj][m][n], 0, 0, 0); __builtin_amdgcn_s_setprio(0); } while (0)
; #define PG8_WAIT_V(n) asm volatile("s_waitcnt vmcnt(" #n ")" ::: "memory")
; #define PG8_WAIT_L(n) asm volatile("s_waitcnt lgkmcnt(" #n ")" ::: "memory")
; template <class Epi>
; __device__ __forceinline__ void gemm_phase(LAS unsigned char* lds, const Gemm g, const StaticOrder& S, const Epi& E) {
;     ...
;         const bool has_next = S.next(ui + 1, nxt);
;         const char* nA = has_next ? (const char*)g.A + (size_t)(nxt.pm >> 5) * aslab + (size_t)(nxt.pm & 31) * tstepA : cA; const char* nB = has_next ? (const char*)g.Bt + (size_t)nxt.pn * tstepB : cB;
;         for (int t = 0; t < nt; t += 2) {
;             const bool last = (t == nt - 2);
;             const char* a1 = cA + (size_t)(t + 1) * kstep;
;             const char* a2 = last ? nA : cA + (size_t)(t + 2) * kstep; const char* b2 = last ? nB : cB + (size_t)(t + 2) * kstep;
;             const char* a3 = a2 + kstep; const char* b3 = b2 + kstep;
;             PG8_LDB(B0, 0, 0); PG8_LDB(B1, 0, 1); PG8_SCHED; PG8_LDA(At, 0, 0); PG8_STAGE(PG8_SA(1, 1), a1 + hstepA, voffA);
;             PG8_WAIT_V(8); PG8_WAIT_L(0); PG8_BAR; PG8_MMA(0, 0, At, B0); PG8_MMA(0, 1, At, B1); PG8_BAR; PG8_SCHED;
;             PG8_LDA(At, 0, 1); PG8_STAGE(PG8_SB(0, 0), b2, voffB); PG8_STAGE(PG8_SB(0, 1), b2 + hstepB, voffB); PG8_STAGE(PG8_SA(0, 0), a2, voffA);
.LBB0_696:
	s_ashr_i32 s14, s38, 5
	s_ashr_i32 s15, s14, 31
	s_lshl_b64 s[14:15], s[14:15], 24
	s_add_u32 s13, s24, s14
	s_addc_u32 s15, s25, s15
	s_lshl_b32 s14, s38, 19
	s_and_b32 s14, s14, 0xf80000
	s_add_u32 s14, s13, s14
	s_addc_u32 s15, s15, 0
	s_and_b64 s[16:17], s[4:5], exec
	s_cselect_b32 s41, s15, s19
	s_cselect_b32 s42, s14, s18
	s_ashr_i32 s13, s12, 31
	s_lshl_b64 s[16:17], s[12:13], 18
	v_readlane_b32 s20, v235, 25
	v_readlane_b32 s21, v235, 26
	s_add_u32 s16, s20, s16
	s_addc_u32 s17, s21, s17
	s_and_b64 s[20:21], s[4:5], exec
	s_cselect_b32 s13, s17, s3
	s_cselect_b32 s43, s16, s2
	s_add_u32 s18, s18, 0x40080
	s_addc_u32 s19, s19, 0
	s_add_u32 s44, s2, 0x100
	s_addc_u32 s45, s3, 0
	s_mov_b32 s46, -2
	s_waitcnt vmcnt(0)
	ds_read_b128 v[142:145], v151
	ds_read_b128 v[154:157], v151 offset:1024
	ds_read_b128 v[158:161], v151 offset:2048
	ds_read_b128 v[162:165], v151 offset:3072
	ds_read_b128 v[166:169], v152
	ds_read_b128 v[170:173], v152 offset:1024
	ds_read_b128 v[174:177], v152 offset:2048
	ds_read_b128 v[178:181], v152 offset:3072
	s_add_u32 s2, s18, 0xfffc0080
	s_addc_u32 s3, s19, -1
	s_cmp_eq_u32 s46, 4
	s_cselect_b32 s21, s41, s3
	s_cselect_b32 s20, s42, s2
	s_cselect_b32 s3, s13, s45
	s_cselect_b32 s2, s43, s44
	v_lshl_add_u64 v[146:147], s[18:19], 0, v[136:137]
	s_add_i32 m0, s23, 0xc000
	ds_read_b128 v[182:185], v153
	ds_read_b128 v[190:193], v153 offset:1024
	ds_read_b128 v[198:201], v153 offset:2048
	ds_read_b128 v[202:205], v153 offset:3072
	ds_read_b128 v[206:209], v153 offset:4096
	ds_read_b128 v[210:213], v153 offset:5120
	ds_read_b128 v[214:217], v153 offset:6144
	ds_read_b128 v[218:221], v153 offset:7168
	global_load_lds_dwordx4 v[146:147], off
	v_lshl_add_u64 v[146:147], s[18:19], 0, v[138:139]
	s_add_i32 m0, s23, 0xe000
	s_nop 0
	global_load_lds_dwordx4 v[146:147], off
	s_waitcnt vmcnt(8)
	s_waitcnt lgkmcnt(0)
	s_barrier
	s_waitcnt lgkmcnt(0)
	v_mfma_f32_16x16x32_bf16 v[124:127], v[142:145], v[182:185], 0
	v_mfma_f32_16x16x32_bf16 v[120:123], v[158:161], v[182:185], 0
	v_mfma_f32_16x16x32_bf16 v[116:119], v[142:145], v[198:201], 0
	v_mfma_f32_16x16x32_bf16 v[112:115], v[158:161], v[198:201], 0
	v_mfma_f32_16x16x32_bf16 v[96:99], v[142:145], v[206:209], 0
	v_mfma_f32_16x16x32_bf16 v[88:91], v[158:161], v[206:209], 0
	v_mfma_f32_16x16x32_bf16 v[80:83], v[142:145], v[214:217], 0
	v_mfma_f32_16x16x32_bf16 v[72:75], v[158:161], v[214:217], 0
	v_mfma_f32_16x16x32_bf16 v[124:127], v[154:157], v[190:193], v[124:127]
	v_mfma_f32_16x16x32_bf16 v[120:123], v[162:165], v[190:193], v[120:123]
	v_mfma_f32_16x16x32_bf16 v[116:119], v[154:157], v[202:205], v[116:119]
	v_mfma_f32_16x16x32_bf16 v[112:115], v[162:165], v[202:205], v[112:115]
	v_mfma_f32_16x16x32_bf16 v[96:99], v[154:157], v[210:213], v[96:99]
	v_mfma_f32_16x16x32_bf16 v[88:91], v[162:165], v[210:213], v[88:91]
	v_mfma_f32_16x16x32_bf16 v[80:83], v[154:157], v[218:221], v[80:83]
	v_mfma_f32_16x16x32_bf16 v[72:75], v[162:165], v[218:221], v[72:75]
	v_mfma_f32_16x16x32_bf16 v[108:111], v[166:169], v[182:185], 0
	v_mfma_f32_16x16x32_bf16 v[104:107], v[174:177], v[182:185], 0
	v_mfma_f32_16x16x32_bf16 v[100:103], v[166:169], v[198:201], 0
	v_mfma_f32_16x16x32_bf16 v[92:95], v[174:177], v[198:201], 0
	v_mfma_f32_16x16x32_bf16 v[84:87], v[166:169], v[206:209], 0
	v_mfma_f32_16x16x32_bf16 v[76:79], v[174:177], v[206:209], 0
	v_mfma_f32_16x16x32_bf16 v[68:71], v[166:169], v[214:217], 0
	v_mfma_f32_16x16x32_bf16 v[64:67], v[174:177], v[214:217], 0
	v_mfma_f32_16x16x32_bf16 v[108:111], v[170:173], v[190:193], v[108:111]
	v_mfma_f32_16x16x32_bf16 v[104:107], v[178:181], v[190:193], v[104:107]
	v_mfma_f32_16x16x32_bf16 v[100:103], v[170:173], v[202:205], v[100:103]
	v_mfma_f32_16x16x32_bf16 v[92:95], v[178:181], v[202:205], v[92:95]
	v_mfma_f32_16x16x32_bf16 v[84:87], v[170:173], v[210:213], v[84:87]
	v_mfma_f32_16x16x32_bf16 v[76:79], v[178:181], v[210:213], v[76:79]
	v_mfma_f32_16x16x32_bf16 v[68:71], v[170:173], v[218:221], v[68:71]
	v_mfma_f32_16x16x32_bf16 v[64:67], v[178:181], v[218:221], v[64:67]
	s_barrier
	s_add_i32 s47, s35, s22
	v_lshl_add_u64 v[146:147], s[2:3], 0, v[130:131]
	s_mov_b32 m0, s47
	ds_read_b128 v[182:185], v153 offset:16384
	ds_read_b128 v[190:193], v153 offset:17408
	ds_read_b128 v[198:201], v153 offset:18432
	ds_read_b128 v[202:205], v153 offset:19456
	ds_read_b128 v[206:209], v153 offset:20480
	ds_read_b128 v[210:213], v153 offset:21504
	ds_read_b128 v[214:217], v153 offset:22528
	ds_read_b128 v[218:221], v153 offset:23552
	global_load_lds_dwordx4 v[146:147], off
	s_add_i32 m0, s47, 0x2000
	s_add_u32 s48, s2, 0x20000
	v_lshl_add_u64 v[186:187], s[2:3], 0, v[134:135]
	s_addc_u32 s49, s3, 0
	s_add_i32 s47, s36, s22
	global_load_lds_dwordx4 v[186:187], off
	v_lshl_add_u64 v[194:195], s[48:49], 0, v[130:131]
	s_mov_b32 m0, s47
	v_lshl_add_u64 v[222:223], s[20:21], 0, v[132:133]
	global_load_lds_dwordx4 v[194:195], off
	v_lshl_add_u64 v[194:195], s[48:49], 0, v[134:135]
	s_add_i32 m0, s47, 0x2000
	s_nop 0
	global_load_lds_dwordx4 v[194:195], off
	v_lshl_add_u64 v[194:195], s[20:21], 0, v[128:129]
	s_mov_b32 m0, s23
	s_nop 0
	global_load_lds_dwordx4 v[194:195], off
	s_mov_b32 m0, s26
	s_nop 0
	global_load_lds_dwordx4 v[222:223], off
	s_waitcnt vmcnt(8)
	s_waitcnt lgkmcnt(0)
	s_barrier
; #define PG8_STAGE(bufoff, gbase, voff) do { _Pragma("unroll") for (int _i = 0; _i < 2; ++_i) \
;         __builtin_amdgcn_global_load_lds((const unsigned*)((const char*)(gbase) + (voff)[_i]), (LAS unsigned*)(lds + (bufoff) + ldsw + _i * 8192), 16, 0, 0); } while (0)
; #define PG8_LDA(dst, b, h) do { _Pragma("unroll") for (int m = 0; m < 4; ++m) _Pragma("unroll") for (int k = 0; k < 2; ++k) dst[m][k] = *(const LAS bf16x8*)(lds + PG8_SA(b, h) + aoff + m * 2048 + k * 1024); } while (0)
; #define PG8_LDB(dst, b, h) do { _Pragma("unroll") for (int n = 0; n < 2; ++n) _Pragma("unroll") for (int k = 0; k < 2; ++k) dst[n][k] = *(const LAS bf16x8*)(lds + PG8_SB(b, h) + boff + n * 2048 + k * 1024); } while (0)
; #define PG8_MMA(ai, bj, At, Bt) do { __builtin_amdgcn_s_setprio(1); _Pragma("unroll") for (int m = 0; m < 4; ++m) _Pragma("unroll") for (int n = 0; n < 2; ++n) _Pragma("unroll") for (int k = 0; k < 2; ++k) \
;         acc[ai][bj][m][n] = __builtin_amdgcn_mfma_f32_16x16x32_bf16(Bt[n][k], At[m][k], acc[ai][bj][m][n], 0, 0, 0); __builtin_amdgcn_s_setprio(0); } while (0)
; #define PG8_WAIT_V(n) asm volatile("s_waitcnt vmcnt(" #n ")" ::: "memory")
; #define PG8_WAIT_L(n) asm volatile("s_waitcnt lgkmcnt(" #n ")" ::: "memory")
; #define PG8_BAR __builtin_amdgcn_s_barrier()
; #define PG8_SCHED __builtin_amdgcn_sched_barrier(0)
; template <class Epi>
; __device__ __forceinline__ void gemm_phase(LAS unsigned char* lds, const Gemm g, const StaticOrder& S, const Epi& E) {
;     ...
;             PG8_WAIT_V(8); PG8_WAIT_L(0); PG8_BAR; PG8_MMA(1, 0, At, B0); PG8_MMA(1, 1, At, B1); PG8_BAR; PG8_SCHED;
;             PG8_LDB(B0, 1, 0); PG8_LDB(B1, 1, 1); PG8_SCHED; PG8_LDA(At, 1, 0); PG8_STAGE(PG8_SA(0, 1), a2 + hstepA, voffA);
;             PG8_WAIT_V(8); PG8_WAIT_L(0); PG8_BAR; PG8_MMA(0, 0, At, B0); PG8_MMA(0, 1, At, B1); PG8_BAR; PG8_SCHED;
	s_waitcnt lgkmcnt(0)
	v_mfma_f32_16x16x32_bf16 v[60:63], v[142:145], v[182:185], 0
	v_mfma_f32_16x16x32_bf16 v[56:59], v[158:161], v[182:185], 0
	v_mfma_f32_16x16x32_bf16 v[48:51], v[142:145], v[198:201], 0
	v_mfma_f32_16x16x32_bf16 v[40:43], v[158:161], v[198:201], 0
	v_mfma_f32_16x16x32_bf16 v[32:35], v[142:145], v[206:209], 0
	v_mfma_f32_16x16x32_bf16 v[24:27], v[158:161], v[206:209], 0
	v_mfma_f32_16x16x32_bf16 v[16:19], v[142:145], v[214:217], 0
	v_mfma_f32_16x16x32_bf16 v[8:11], v[158:161], v[214:217], 0
	v_mfma_f32_16x16x32_bf16 v[60:63], v[154:157], v[190:193], v[60:63]
	v_mfma_f32_16x16x32_bf16 v[56:59], v[162:165], v[190:193], v[56:59]
	v_mfma_f32_16x16x32_bf16 v[48:51], v[154:157], v[202:205], v[48:51]
	v_mfma_f32_16x16x32_bf16 v[40:43], v[162:165], v[202:205], v[40:43]
	v_mfma_f32_16x16x32_bf16 v[32:35], v[154:157], v[210:213], v[32:35]
	v_mfma_f32_16x16x32_bf16 v[24:27], v[162:165], v[210:213], v[24:27]
	v_mfma_f32_16x16x32_bf16 v[16:19], v[154:157], v[218:221], v[16:19]
	v_mfma_f32_16x16x32_bf16 v[8:11], v[162:165], v[218:221], v[8:11]
	v_mfma_f32_16x16x32_bf16 v[52:55], v[166:169], v[182:185], 0
	v_mfma_f32_16x16x32_bf16 v[44:47], v[174:177], v[182:185], 0
	v_mfma_f32_16x16x32_bf16 v[36:39], v[166:169], v[198:201], 0
	v_mfma_f32_16x16x32_bf16 v[28:31], v[174:177], v[198:201], 0
	v_mfma_f32_16x16x32_bf16 v[20:23], v[166:169], v[206:209], 0
	v_mfma_f32_16x16x32_bf16 v[12:15], v[174:177], v[206:209], 0
	v_mfma_f32_16x16x32_bf16 v[4:7], v[166:169], v[214:217], 0
	v_mfma_f32_16x16x32_bf16 v[0:3], v[174:177], v[214:217], 0
	v_mfma_f32_16x16x32_bf16 v[52:55], v[170:173], v[190:193], v[52:55]
	v_mfma_f32_16x16x32_bf16 v[44:47], v[178:181], v[190:193], v[44:47]
	v_mfma_f32_16x16x32_bf16 v[36:39], v[170:173], v[202:205], v[36:39]
	v_mfma_f32_16x16x32_bf16 v[28:31], v[178:181], v[202:205], v[28:31]
	v_mfma_f32_16x16x32_bf16 v[20:23], v[170:173], v[210:213], v[20:23]
	v_mfma_f32_16x16x32_bf16 v[12:15], v[178:181], v[210:213], v[12:15]
	v_mfma_f32_16x16x32_bf16 v[4:7], v[170:173], v[218:221], v[4:7]
	v_mfma_f32_16x16x32_bf16 v[0:3], v[178:181], v[218:221], v[0:3]
	s_barrier
	s_add_i32 s47, 0, 0x18000
	s_add_i32 s48, 0, 0x1c000
	v_add_u32_e32 v162, s47, v149
	v_add_u32_e32 v178, s48, v149
	ds_read_b128 v[142:145], v162
	ds_read_b128 v[154:157], v162 offset:1024
	ds_read_b128 v[158:161], v162 offset:2048
	ds_read_b128 v[162:165], v162 offset:3072
	ds_read_b128 v[166:169], v178
	ds_read_b128 v[170:173], v178 offset:1024
	ds_read_b128 v[174:177], v178 offset:2048
	ds_read_b128 v[178:181], v178 offset:3072
	s_add_u32 s20, s20, 0x40000
	s_addc_u32 s21, s21, 0
	s_mov_b32 m0, s27
	v_lshl_add_u64 v[224:225], s[20:21], 0, v[128:129]
	ds_read_b128 v[182:185], v153 offset:32768
	ds_read_b128 v[190:193], v153 offset:33792
	ds_read_b128 v[198:201], v153 offset:34816
	ds_read_b128 v[202:205], v153 offset:35840
	ds_read_b128 v[206:209], v153 offset:36864
	ds_read_b128 v[210:213], v153 offset:37888
	ds_read_b128 v[214:217], v153 offset:38912
	ds_read_b128 v[218:221], v153 offset:39936
	global_load_lds_dwordx4 v[224:225], off
	v_lshl_add_u64 v[224:225], s[20:21], 0, v[132:133]
	s_mov_b32 m0, s28
	s_nop 0
	global_load_lds_dwordx4 v[224:225], off
	s_waitcnt vmcnt(8)
	s_waitcnt lgkmcnt(0)
	s_barrier
	s_waitcnt lgkmcnt(0)
	v_mfma_f32_16x16x32_bf16 v[124:127], v[142:145], v[182:185], v[124:127]
	v_mfma_f32_16x16x32_bf16 v[120:123], v[158:161], v[182:185], v[120:123]
	v_mfma_f32_16x16x32_bf16 v[116:119], v[142:145], v[198:201], v[116:119]
	v_mfma_f32_16x16x32_bf16 v[112:115], v[158:161], v[198:201], v[112:115]
	v_mfma_f32_16x16x32_bf16 v[96:99], v[142:145], v[206:209], v[96:99]
	v_mfma_f32_16x16x32_bf16 v[88:91], v[158:161], v[206:209], v[88:91]
	v_mfma_f32_16x16x32_bf16 v[80:83], v[142:145], v[214:217], v[80:83]
	v_mfma_f32_16x16x32_bf16 v[72:75], v[158:161], v[214:217], v[72:75]
	v_mfma_f32_16x16x32_bf16 v[124:127], v[154:157], v[190:193], v[124:127]
	v_mfma_f32_16x16x32_bf16 v[120:123], v[162:165], v[190:193], v[120:123]
	v_mfma_f32_16x16x32_bf16 v[116:119], v[154:157], v[202:205], v[116:119]
	v_mfma_f32_16x16x32_bf16 v[112:115], v[162:165], v[202:205], v[112:115]
	v_mfma_f32_16x16x32_bf16 v[96:99], v[154:157], v[210:213], v[96:99]
	v_mfma_f32_16x16x32_bf16 v[88:91], v[162:165], v[210:213], v[88:91]
	v_mfma_f32_16x16x32_bf16 v[80:83], v[154:157], v[218:221], v[80:83]
	v_mfma_f32_16x16x32_bf16 v[72:75], v[162:165], v[218:221], v[72:75]
	v_mfma_f32_16x16x32_bf16 v[108:111], v[166:169], v[182:185], v[108:111]
	v_mfma_f32_16x16x32_bf16 v[104:107], v[174:177], v[182:185], v[104:107]
	v_mfma_f32_16x16x32_bf16 v[100:103], v[166:169], v[198:201], v[100:103]
	v_mfma_f32_16x16x32_bf16 v[92:95], v[174:177], v[198:201], v[92:95]
	v_mfma_f32_16x16x32_bf16 v[84:87], v[166:169], v[206:209], v[84:87]
	v_mfma_f32_16x16x32_bf16 v[76:79], v[174:177], v[206:209], v[76:79]
	v_mfma_f32_16x16x32_bf16 v[68:71], v[166:169], v[214:217], v[68:71]
	v_mfma_f32_16x16x32_bf16 v[64:67], v[174:177], v[214:217], v[64:67]
	v_mfma_f32_16x16x32_bf16 v[108:111], v[170:173], v[190:193], v[108:111]
	v_mfma_f32_16x16x32_bf16 v[104:107], v[178:181], v[190:193], v[104:107]
	v_mfma_f32_16x16x32_bf16 v[100:103], v[170:173], v[202:205], v[100:103]
	v_mfma_f32_16x16x32_bf16 v[92:95], v[178:181], v[202:205], v[92:95]
	v_mfma_f32_16x16x32_bf16 v[84:87], v[170:173], v[210:213], v[84:87]
	v_mfma_f32_16x16x32_bf16 v[76:79], v[178:181], v[210:213], v[76:79]
	v_mfma_f32_16x16x32_bf16 v[68:71], v[170:173], v[218:221], v[68:71]
	v_mfma_f32_16x16x32_bf16 v[64:67], v[178:181], v[218:221], v[64:67]
	s_barrier
; #define PG8_STAGE(bufoff, gbase, voff) do { _Pragma("unroll") for (int _i = 0; _i < 2; ++_i) \
;         __builtin_amdgcn_global_load_lds((const unsigned*)((const char*)(gbase) + (voff)[_i]), (LAS unsigned*)(lds + (bufoff) + ldsw + _i * 8192), 16, 0, 0); } while (0)
; #define PG8_LDA(dst, b, h) do { _Pragma("unroll") for (int m = 0; m < 4; ++m) _Pragma("unroll") for (int k = 0; k < 2; ++k) dst[m][k] = *(const LAS bf16x8*)(lds + PG8_SA(b, h) + aoff + m * 2048 + k * 1024); } while (0)
; #define PG8_MMA(ai, bj, At, Bt) do { __builtin_amdgcn_s_setprio(1); _Pragma("unroll") for (int m = 0; m < 4; ++m) _Pragma("unroll") for (int n = 0; n < 2; ++n) _Pragma("unroll") for (int k = 0; k < 2; ++k) \
;         acc[ai][bj][m][n] = __builtin_amdgcn_mfma_f32_16x16x32_bf16(Bt[n][k], At[m][k], acc[ai][bj][m][n], 0, 0, 0); __builtin_amdgcn_s_setprio(0); } while (0)
; #define PG8_WAIT_V(n) asm volatile("s_waitcnt vmcnt(" #n ")" ::: "memory")
; #define PG8_WAIT_L(n) asm volatile("s_waitcnt lgkmcnt(" #n ")" ::: "memory")
; #define PG8_BAR __builtin_amdgcn_s_barrier()
; #define PG8_SCHED __builtin_amdgcn_sched_barrier(0)
; template <class Epi>
; __device__ __forceinline__ void gemm_phase(LAS unsigned char* lds, const Gemm g, const StaticOrder& S, const Epi& E) {
;     ...
;             PG8_LDA(At, 1, 1); PG8_STAGE(PG8_SB(1, 0), b3, voffB); PG8_STAGE(PG8_SB(1, 1), b3 + hstepB, voffB); PG8_STAGE(PG8_SA(1, 0), a3, voffA);
;             PG8_WAIT_V(8); PG8_WAIT_L(0); PG8_BAR; PG8_MMA(1, 0, At, B0); PG8_MMA(1, 1, At, B1); PG8_BAR; PG8_SCHED;
;         }
	s_add_i32 s20, s47, s22
	v_lshl_add_u64 v[146:147], v[146:147], 0, s[8:9]
	s_mov_b32 m0, s20
	ds_read_b128 v[182:185], v153 offset:49152
	ds_read_b128 v[190:193], v153 offset:50176
	ds_read_b128 v[198:201], v153 offset:51200
	ds_read_b128 v[202:205], v153 offset:52224
	ds_read_b128 v[206:209], v153 offset:53248
	ds_read_b128 v[210:213], v153 offset:54272
	ds_read_b128 v[214:217], v153 offset:55296
	ds_read_b128 v[218:221], v153 offset:56320
	global_load_lds_dwordx4 v[146:147], off
	s_add_i32 m0, s20, 0x2000
	s_add_u32 s2, s2, 0x20080
	v_lshl_add_u64 v[146:147], v[186:187], 0, s[8:9]
	s_addc_u32 s3, s3, 0
	s_add_i32 s20, s48, s22
	global_load_lds_dwordx4 v[146:147], off
	v_lshl_add_u64 v[146:147], s[2:3], 0, v[130:131]
	s_mov_b32 m0, s20
	s_nop 0
	global_load_lds_dwordx4 v[146:147], off
	v_lshl_add_u64 v[146:147], s[2:3], 0, v[134:135]
	s_add_i32 m0, s20, 0x2000
	s_nop 0
	global_load_lds_dwordx4 v[146:147], off
	v_lshl_add_u64 v[146:147], v[194:195], 0, s[8:9]
	s_mov_b32 m0, s30
	s_nop 0
	global_load_lds_dwordx4 v[146:147], off
	v_lshl_add_u64 v[146:147], v[222:223], 0, s[8:9]
	s_mov_b32 m0, s31
	s_nop 0
	global_load_lds_dwordx4 v[146:147], off
	s_waitcnt vmcnt(8)
	s_waitcnt lgkmcnt(0)
	s_barrier
	s_waitcnt lgkmcnt(0)
	v_mfma_f32_16x16x32_bf16 v[60:63], v[142:145], v[182:185], v[60:63]
	v_mfma_f32_16x16x32_bf16 v[56:59], v[158:161], v[182:185], v[56:59]
	v_mfma_f32_16x16x32_bf16 v[48:51], v[142:145], v[198:201], v[48:51]
	v_mfma_f32_16x16x32_bf16 v[40:43], v[158:161], v[198:201], v[40:43]
	v_mfma_f32_16x16x32_bf16 v[32:35], v[142:145], v[206:209], v[32:35]
	v_mfma_f32_16x16x32_bf16 v[24:27], v[158:161], v[206:209], v[24:27]
	v_mfma_f32_16x16x32_bf16 v[16:19], v[142:145], v[214:217], v[16:19]
	v_mfma_f32_16x16x32_bf16 v[8:11], v[158:161], v[214:217], v[8:11]
	v_mfma_f32_16x16x32_bf16 v[60:63], v[154:157], v[190:193], v[60:63]
	v_mfma_f32_16x16x32_bf16 v[56:59], v[162:165], v[190:193], v[56:59]
	v_mfma_f32_16x16x32_bf16 v[48:51], v[154:157], v[202:205], v[48:51]
	v_mfma_f32_16x16x32_bf16 v[40:43], v[162:165], v[202:205], v[40:43]
	v_mfma_f32_16x16x32_bf16 v[32:35], v[154:157], v[210:213], v[32:35]
	v_mfma_f32_16x16x32_bf16 v[24:27], v[162:165], v[210:213], v[24:27]
	v_mfma_f32_16x16x32_bf16 v[16:19], v[154:157], v[218:221], v[16:19]
	v_mfma_f32_16x16x32_bf16 v[8:11], v[162:165], v[218:221], v[8:11]
	v_mfma_f32_16x16x32_bf16 v[52:55], v[166:169], v[182:185], v[52:55]
	v_mfma_f32_16x16x32_bf16 v[44:47], v[174:177], v[182:185], v[44:47]
	v_mfma_f32_16x16x32_bf16 v[36:39], v[166:169], v[198:201], v[36:39]
	v_mfma_f32_16x16x32_bf16 v[28:31], v[174:177], v[198:201], v[28:31]
	v_mfma_f32_16x16x32_bf16 v[20:23], v[166:169], v[206:209], v[20:23]
	v_mfma_f32_16x16x32_bf16 v[12:15], v[174:177], v[206:209], v[12:15]
	v_mfma_f32_16x16x32_bf16 v[4:7], v[166:169], v[214:217], v[4:7]
	v_mfma_f32_16x16x32_bf16 v[0:3], v[174:177], v[214:217], v[0:3]
	v_mfma_f32_16x16x32_bf16 v[52:55], v[170:173], v[190:193], v[52:55]
	v_mfma_f32_16x16x32_bf16 v[44:47], v[178:181], v[190:193], v[44:47]
	v_mfma_f32_16x16x32_bf16 v[36:39], v[170:173], v[202:205], v[36:39]
	v_mfma_f32_16x16x32_bf16 v[28:31], v[178:181], v[202:205], v[28:31]
	v_mfma_f32_16x16x32_bf16 v[20:23], v[170:173], v[210:213], v[20:23]
	v_mfma_f32_16x16x32_bf16 v[12:15], v[178:181], v[210:213], v[12:15]
	v_mfma_f32_16x16x32_bf16 v[4:7], v[170:173], v[218:221], v[4:7]
	v_mfma_f32_16x16x32_bf16 v[0:3], v[178:181], v[218:221], v[0:3]
	s_barrier
	s_add_i32 s46, s46, 2
	s_add_u32 s18, s18, 0x100
	s_addc_u32 s19, s19, 0
	s_add_u32 s44, s44, 0x100
	s_addc_u32 s45, s45, 0
	s_cmp_gt_u32 s46, 5
	s_cbranch_scc0 .LBB0_697

; #define PG8_STAGE(bufoff, gbase, voff) do { _Pragma("unroll") for (int _i = 0; _i < 2; ++_i) \
;         __builtin_amdgcn_global_load_lds((const unsigned*)((const char*)(gbase) + (voff)[_i]), (LAS unsigned*)(lds + (bufoff) + ldsw + _i * 8192), 16, 0, 0); } while (0)
; #define PG8_LDA(dst, b, h) do { _Pragma("unroll") for (int m = 0; m < 4; ++m) _Pragma("unroll") for (int k = 0; k < 2; ++k) dst[m][k] = *(const LAS bf16x8*)(lds + PG8_SA(b, h) + aoff + m * 2048 + k * 1024); } while (0)
; #define PG8_LDB(dst, b, h) do { _Pragma("unroll") for (int n = 0; n < 2; ++n) _Pragma("unroll") for (int k = 0; k < 2; ++k) dst[n][k] = *(const LAS bf16x8*)(lds + PG8_SB(b, h) + boff + n * 2048 + k * 1024); } while (0)
; #define PG8_MMA(ai, bj, At, Bt) do { __builtin_amdgcn_s_setprio(1); _Pragma("unroll") for (int m = 0; m < 4; ++m) _Pragma("unroll") for (int n = 0; n < 2; ++n) _Pragma("unroll") for (int k = 0; k < 2; ++k) \
;         acc[ai][bj][m][n] = __builtin_amdgcn_mfma_f32_16x16x32_bf16(Bt[n][k], At[m][k], acc[ai][bj][m][n], 0, 0, 0); __builtin_amdgcn_s_setprio(0); } while (0)
; #define PG8_WAIT_V(n) asm volatile("s_waitcnt vmcnt(" #n ")" ::: "memory")
; #define PG8_WAIT_L(n) asm volatile("s_waitcnt lgkmcnt(" #n ")" ::: "memory")
; template <class Epi>
; __device__ __forceinline__ void gemm_phase(LAS unsigned char* lds, const Gemm g, const StaticOrder& S, const Epi& E) {
;     ...
;         const bool has_next = S.next(ui + 1, nxt);
;         const char* nA = has_next ? (const char*)g.A + (size_t)(nxt.pm >> 5) * aslab + (size_t)(nxt.pm & 31) * tstepA : cA; const char* nB = has_next ? (const char*)g.Bt + (size_t)nxt.pn * tstepB : cB;
;         for (int t = 0; t < nt; t += 2) {
;             const bool last = (t == nt - 2);
;             const char* a1 = cA + (size_t)(t + 1) * kstep;
;             const char* a2 = last ? nA : cA + (size_t)(t + 2) * kstep; const char* b2 = last ? nB : cB + (size_t)(t + 2) * kstep;
;             const char* a3 = a2 + kstep; const char* b3 = b2 + kstep;
;             PG8_LDB(B0, 0, 0); PG8_LDB(B1, 0, 1); PG8_SCHED; PG8_LDA(At, 0, 0); PG8_STAGE(PG8_SA(1, 1), a1 + hstepA, voffA);
;             PG8_WAIT_V(8); PG8_WAIT_L(0); PG8_BAR; PG8_MMA(0, 0, At, B0); PG8_MMA(0, 1, At, B1); PG8_BAR; PG8_SCHED;
;             PG8_LDA(At, 0, 1); PG8_STAGE(PG8_SB(0, 0), b2, voffB); PG8_STAGE(PG8_SB(0, 1), b2 + hstepB, voffB); PG8_STAGE(PG8_SA(0, 0), a2, voffA);
.LBB0_720:
	s_ashr_i32 s16, s41, 5
	s_ashr_i32 s17, s16, 31
	s_lshl_b64 s[16:17], s[16:17], 24
	s_add_u32 s15, s24, s16
	s_addc_u32 s17, s25, s17
	s_lshl_b32 s16, s41, 19
	s_and_b32 s16, s16, 0xf80000
	s_add_u32 s16, s15, s16
	s_addc_u32 s17, s17, 0
	s_and_b64 s[18:19], s[4:5], exec
	s_cselect_b32 s44, s17, s21
	s_cselect_b32 s45, s16, s20
	s_ashr_i32 s15, s14, 31
	s_lshl_b64 s[18:19], s[14:15], 18
	v_readlane_b32 s22, v235, 27
	v_readlane_b32 s23, v235, 28
	s_add_u32 s18, s22, s18
	s_addc_u32 s19, s23, s19
	s_and_b64 s[22:23], s[4:5], exec
	s_cselect_b32 s15, s19, s3
	s_cselect_b32 s46, s18, s2
	s_add_u32 s20, s20, 0x40080
	s_addc_u32 s21, s21, 0
	s_add_u32 s47, s2, 0x100
	s_addc_u32 s48, s3, 0
	s_mov_b32 s49, -2
	s_waitcnt vmcnt(0)
	ds_read_b128 v[128:131], v167
	ds_read_b128 v[132:135], v167 offset:1024
	ds_read_b128 v[136:139], v167 offset:2048
	ds_read_b128 v[140:143], v167 offset:3072
	ds_read_b128 v[158:161], v168
	ds_read_b128 v[170:173], v168 offset:1024
	ds_read_b128 v[174:177], v168 offset:2048
	ds_read_b128 v[178:181], v168 offset:3072
	s_add_u32 s2, s20, 0xfffc0080
	s_addc_u32 s3, s21, -1
	s_cmp_eq_u32 s49, 4
	s_cselect_b32 s23, s44, s3
	s_cselect_b32 s22, s45, s2
	s_cselect_b32 s3, s15, s48
	s_cselect_b32 s2, s46, s47
	v_lshl_add_u64 v[162:163], s[20:21], 0, v[152:153]
	s_add_i32 m0, s27, 0xc000
	ds_read_b128 v[182:185], v169
	ds_read_b128 v[190:193], v169 offset:1024
	ds_read_b128 v[198:201], v169 offset:2048
	ds_read_b128 v[202:205], v169 offset:3072
	ds_read_b128 v[206:209], v169 offset:4096
	ds_read_b128 v[210:213], v169 offset:5120
	ds_read_b128 v[214:217], v169 offset:6144
	ds_read_b128 v[218:221], v169 offset:7168
	global_load_lds_dwordx4 v[162:163], off
	v_lshl_add_u64 v[162:163], s[20:21], 0, v[154:155]
	s_add_i32 m0, s27, 0xe000
	s_nop 0
	global_load_lds_dwordx4 v[162:163], off
	s_waitcnt vmcnt(8)
	s_waitcnt lgkmcnt(0)
	s_barrier
	s_waitcnt lgkmcnt(0)
	v_mfma_f32_16x16x32_bf16 v[124:127], v[128:131], v[182:185], 0
	v_mfma_f32_16x16x32_bf16 v[120:123], v[136:139], v[182:185], 0
	v_mfma_f32_16x16x32_bf16 v[112:115], v[128:131], v[198:201], 0
	v_mfma_f32_16x16x32_bf16 v[104:107], v[136:139], v[198:201], 0
	v_mfma_f32_16x16x32_bf16 v[96:99], v[128:131], v[206:209], 0
	v_mfma_f32_16x16x32_bf16 v[88:91], v[136:139], v[206:209], 0
	v_mfma_f32_16x16x32_bf16 v[80:83], v[128:131], v[214:217], 0
	v_mfma_f32_16x16x32_bf16 v[72:75], v[136:139], v[214:217], 0
	v_mfma_f32_16x16x32_bf16 v[124:127], v[132:135], v[190:193], v[124:127]
	v_mfma_f32_16x16x32_bf16 v[120:123], v[140:143], v[190:193], v[120:123]
	v_mfma_f32_16x16x32_bf16 v[112:115], v[132:135], v[202:205], v[112:115]
	v_mfma_f32_16x16x32_bf16 v[104:107], v[140:143], v[202:205], v[104:107]
	v_mfma_f32_16x16x32_bf16 v[96:99], v[132:135], v[210:213], v[96:99]
	v_mfma_f32_16x16x32_bf16 v[88:91], v[140:143], v[210:213], v[88:91]
	v_mfma_f32_16x16x32_bf16 v[80:83], v[132:135], v[218:221], v[80:83]
	v_mfma_f32_16x16x32_bf16 v[72:75], v[140:143], v[218:221], v[72:75]
	v_mfma_f32_16x16x32_bf16 v[116:119], v[158:161], v[182:185], 0
	v_mfma_f32_16x16x32_bf16 v[108:111], v[174:177], v[182:185], 0
	v_mfma_f32_16x16x32_bf16 v[100:103], v[158:161], v[198:201], 0
	v_mfma_f32_16x16x32_bf16 v[92:95], v[174:177], v[198:201], 0
	v_mfma_f32_16x16x32_bf16 v[84:87], v[158:161], v[206:209], 0
	v_mfma_f32_16x16x32_bf16 v[76:79], v[174:177], v[206:209], 0
	v_mfma_f32_16x16x32_bf16 v[68:71], v[158:161], v[214:217], 0
	v_mfma_f32_16x16x32_bf16 v[64:67], v[174:177], v[214:217], 0
	v_mfma_f32_16x16x32_bf16 v[116:119], v[170:173], v[190:193], v[116:119]
	v_mfma_f32_16x16x32_bf16 v[108:111], v[178:181], v[190:193], v[108:111]
	v_mfma_f32_16x16x32_bf16 v[100:103], v[170:173], v[202:205], v[100:103]
	v_mfma_f32_16x16x32_bf16 v[92:95], v[178:181], v[202:205], v[92:95]
	v_mfma_f32_16x16x32_bf16 v[84:87], v[170:173], v[210:213], v[84:87]
	v_mfma_f32_16x16x32_bf16 v[76:79], v[178:181], v[210:213], v[76:79]
	v_mfma_f32_16x16x32_bf16 v[68:71], v[170:173], v[218:221], v[68:71]
	v_mfma_f32_16x16x32_bf16 v[64:67], v[178:181], v[218:221], v[64:67]
	s_barrier
	s_add_i32 s50, s37, s26
	v_lshl_add_u64 v[162:163], s[2:3], 0, v[146:147]
	s_mov_b32 m0, s50
	ds_read_b128 v[182:185], v169 offset:16384
	ds_read_b128 v[190:193], v169 offset:17408
	ds_read_b128 v[198:201], v169 offset:18432
	ds_read_b128 v[202:205], v169 offset:19456
	ds_read_b128 v[206:209], v169 offset:20480
	ds_read_b128 v[210:213], v169 offset:21504
	ds_read_b128 v[214:217], v169 offset:22528
	ds_read_b128 v[218:221], v169 offset:23552
	global_load_lds_dwordx4 v[162:163], off
	s_add_i32 m0, s50, 0x2000
	s_add_u32 s50, s2, 0x20000
	v_lshl_add_u64 v[186:187], s[2:3], 0, v[150:151]
	s_addc_u32 s51, s3, 0
	s_add_i32 s52, s38, s26
	global_load_lds_dwordx4 v[186:187], off
	v_lshl_add_u64 v[194:195], s[50:51], 0, v[146:147]
	s_mov_b32 m0, s52
	v_lshl_add_u64 v[222:223], s[22:23], 0, v[148:149]
	global_load_lds_dwordx4 v[194:195], off
	v_lshl_add_u64 v[194:195], s[50:51], 0, v[150:151]
	s_add_i32 m0, s52, 0x2000
	s_nop 0
	global_load_lds_dwordx4 v[194:195], off
	v_lshl_add_u64 v[194:195], s[22:23], 0, v[144:145]
	s_mov_b32 m0, s27
	s_nop 0
	global_load_lds_dwordx4 v[194:195], off
	s_mov_b32 m0, s28
	s_nop 0
	global_load_lds_dwordx4 v[222:223], off
	s_waitcnt vmcnt(8)
	s_waitcnt lgkmcnt(0)
	s_barrier
; #define PG8_STAGE(bufoff, gbase, voff) do { _Pragma("unroll") for (int _i = 0; _i < 2; ++_i) \
;         __builtin_amdgcn_global_load_lds((const unsigned*)((const char*)(gbase) + (voff)[_i]), (LAS unsigned*)(lds + (bufoff) + ldsw + _i * 8192), 16, 0, 0); } while (0)
; #define PG8_LDA(dst, b, h) do { _Pragma("unroll") for (int m = 0; m < 4; ++m) _Pragma("unroll") for (int k = 0; k < 2; ++k) dst[m][k] = *(const LAS bf16x8*)(lds + PG8_SA(b, h) + aoff + m * 2048 + k * 1024); } while (0)
; #define PG8_LDB(dst, b, h) do { _Pragma("unroll") for (int n = 0; n < 2; ++n) _Pragma("unroll") for (int k = 0; k < 2; ++k) dst[n][k] = *(const LAS bf16x8*)(lds + PG8_SB(b, h) + boff + n * 2048 + k * 1024); } while (0)
; #define PG8_MMA(ai, bj, At, Bt) do { __builtin_amdgcn_s_setprio(1); _Pragma("unroll") for (int m = 0; m < 4; ++m) _Pragma("unroll") for (int n = 0; n < 2; ++n) _Pragma("unroll") for (int k = 0; k < 2; ++k) \
;         acc[ai][bj][m][n] = __builtin_amdgcn_mfma_f32_16x16x32_bf16(Bt[n][k], At[m][k], acc[ai][bj][m][n], 0, 0, 0); __builtin_amdgcn_s_setprio(0); } while (0)
; #define PG8_WAIT_V(n) asm volatile("s_waitcnt vmcnt(" #n ")" ::: "memory")
; #define PG8_WAIT_L(n) asm volatile("s_waitcnt lgkmcnt(" #n ")" ::: "memory")
; #define PG8_BAR __builtin_amdgcn_s_barrier()
; #define PG8_SCHED __builtin_amdgcn_sched_barrier(0)
; template <class Epi>
; __device__ __forceinline__ void gemm_phase(LAS unsigned char* lds, const Gemm g, const StaticOrder& S, const Epi& E) {
;     ...
;             PG8_WAIT_V(8); PG8_WAIT_L(0); PG8_BAR; PG8_MMA(1, 0, At, B0); PG8_MMA(1, 1, At, B1); PG8_BAR; PG8_SCHED;
;             PG8_LDB(B0, 1, 0); PG8_LDB(B1, 1, 1); PG8_SCHED; PG8_LDA(At, 1, 0); PG8_STAGE(PG8_SA(0, 1), a2 + hstepA, voffA);
;             PG8_WAIT_V(8); PG8_WAIT_L(0); PG8_BAR; PG8_MMA(0, 0, At, B0); PG8_MMA(0, 1, At, B1); PG8_BAR; PG8_SCHED;
	s_waitcnt lgkmcnt(0)
	v_mfma_f32_16x16x32_bf16 v[60:63], v[128:131], v[182:185], 0
	v_mfma_f32_16x16x32_bf16 v[56:59], v[136:139], v[182:185], 0
	v_mfma_f32_16x16x32_bf16 v[48:51], v[128:131], v[198:201], 0
	v_mfma_f32_16x16x32_bf16 v[40:43], v[136:139], v[198:201], 0
	v_mfma_f32_16x16x32_bf16 v[32:35], v[128:131], v[206:209], 0
	v_mfma_f32_16x16x32_bf16 v[24:27], v[136:139], v[206:209], 0
	v_mfma_f32_16x16x32_bf16 v[16:19], v[128:131], v[214:217], 0
	v_mfma_f32_16x16x32_bf16 v[8:11], v[136:139], v[214:217], 0
	v_mfma_f32_16x16x32_bf16 v[60:63], v[132:135], v[190:193], v[60:63]
	v_mfma_f32_16x16x32_bf16 v[56:59], v[140:143], v[190:193], v[56:59]
	v_mfma_f32_16x16x32_bf16 v[48:51], v[132:135], v[202:205], v[48:51]
	v_mfma_f32_16x16x32_bf16 v[40:43], v[140:143], v[202:205], v[40:43]
	v_mfma_f32_16x16x32_bf16 v[32:35], v[132:135], v[210:213], v[32:35]
	v_mfma_f32_16x16x32_bf16 v[24:27], v[140:143], v[210:213], v[24:27]
	v_mfma_f32_16x16x32_bf16 v[16:19], v[132:135], v[218:221], v[16:19]
	v_mfma_f32_16x16x32_bf16 v[8:11], v[140:143], v[218:221], v[8:11]
	v_mfma_f32_16x16x32_bf16 v[52:55], v[158:161], v[182:185], 0
	v_mfma_f32_16x16x32_bf16 v[44:47], v[174:177], v[182:185], 0
	v_mfma_f32_16x16x32_bf16 v[36:39], v[158:161], v[198:201], 0
	v_mfma_f32_16x16x32_bf16 v[28:31], v[174:177], v[198:201], 0
	v_mfma_f32_16x16x32_bf16 v[20:23], v[158:161], v[206:209], 0
	v_mfma_f32_16x16x32_bf16 v[12:15], v[174:177], v[206:209], 0
	v_mfma_f32_16x16x32_bf16 v[4:7], v[158:161], v[214:217], 0
	v_mfma_f32_16x16x32_bf16 v[0:3], v[174:177], v[214:217], 0
	v_mfma_f32_16x16x32_bf16 v[52:55], v[170:173], v[190:193], v[52:55]
	v_mfma_f32_16x16x32_bf16 v[44:47], v[178:181], v[190:193], v[44:47]
	v_mfma_f32_16x16x32_bf16 v[36:39], v[170:173], v[202:205], v[36:39]
	v_mfma_f32_16x16x32_bf16 v[28:31], v[178:181], v[202:205], v[28:31]
	v_mfma_f32_16x16x32_bf16 v[20:23], v[170:173], v[210:213], v[20:23]
	v_mfma_f32_16x16x32_bf16 v[12:15], v[178:181], v[210:213], v[12:15]
	v_mfma_f32_16x16x32_bf16 v[4:7], v[170:173], v[218:221], v[4:7]
	v_mfma_f32_16x16x32_bf16 v[0:3], v[178:181], v[218:221], v[0:3]
	s_barrier
	s_add_i32 s50, 0, 0x18000
	s_add_i32 s51, 0, 0x1c000
	v_add_u32_e32 v140, s50, v165
	v_add_u32_e32 v178, s51, v165
	ds_read_b128 v[128:131], v140
	ds_read_b128 v[132:135], v140 offset:1024
	ds_read_b128 v[136:139], v140 offset:2048
	ds_read_b128 v[140:143], v140 offset:3072
	ds_read_b128 v[158:161], v178
	ds_read_b128 v[170:173], v178 offset:1024
	ds_read_b128 v[174:177], v178 offset:2048
	ds_read_b128 v[178:181], v178 offset:3072
	s_add_u32 s22, s22, 0x40000
	s_addc_u32 s23, s23, 0
	s_mov_b32 m0, s29
	v_lshl_add_u64 v[224:225], s[22:23], 0, v[144:145]
	ds_read_b128 v[182:185], v169 offset:32768
	ds_read_b128 v[190:193], v169 offset:33792
	ds_read_b128 v[198:201], v169 offset:34816
	ds_read_b128 v[202:205], v169 offset:35840
	ds_read_b128 v[206:209], v169 offset:36864
	ds_read_b128 v[210:213], v169 offset:37888
	ds_read_b128 v[214:217], v169 offset:38912
	ds_read_b128 v[218:221], v169 offset:39936
	global_load_lds_dwordx4 v[224:225], off
	v_lshl_add_u64 v[224:225], s[22:23], 0, v[148:149]
	s_mov_b32 m0, s30
	s_nop 0
	global_load_lds_dwordx4 v[224:225], off
	s_waitcnt vmcnt(8)
	s_waitcnt lgkmcnt(0)
	s_barrier
	s_waitcnt lgkmcnt(0)
	v_mfma_f32_16x16x32_bf16 v[124:127], v[128:131], v[182:185], v[124:127]
	v_mfma_f32_16x16x32_bf16 v[120:123], v[136:139], v[182:185], v[120:123]
	v_mfma_f32_16x16x32_bf16 v[112:115], v[128:131], v[198:201], v[112:115]
	v_mfma_f32_16x16x32_bf16 v[104:107], v[136:139], v[198:201], v[104:107]
	v_mfma_f32_16x16x32_bf16 v[96:99], v[128:131], v[206:209], v[96:99]
	v_mfma_f32_16x16x32_bf16 v[88:91], v[136:139], v[206:209], v[88:91]
	v_mfma_f32_16x16x32_bf16 v[80:83], v[128:131], v[214:217], v[80:83]
	v_mfma_f32_16x16x32_bf16 v[72:75], v[136:139], v[214:217], v[72:75]
	v_mfma_f32_16x16x32_bf16 v[124:127], v[132:135], v[190:193], v[124:127]
	v_mfma_f32_16x16x32_bf16 v[120:123], v[140:143], v[190:193], v[120:123]
	v_mfma_f32_16x16x32_bf16 v[112:115], v[132:135], v[202:205], v[112:115]
	v_mfma_f32_16x16x32_bf16 v[104:107], v[140:143], v[202:205], v[104:107]
	v_mfma_f32_16x16x32_bf16 v[96:99], v[132:135], v[210:213], v[96:99]
	v_mfma_f32_16x16x32_bf16 v[88:91], v[140:143], v[210:213], v[88:91]
	v_mfma_f32_16x16x32_bf16 v[80:83], v[132:135], v[218:221], v[80:83]
	v_mfma_f32_16x16x32_bf16 v[72:75], v[140:143], v[218:221], v[72:75]
	v_mfma_f32_16x16x32_bf16 v[116:119], v[158:161], v[182:185], v[116:119]
	v_mfma_f32_16x16x32_bf16 v[108:111], v[174:177], v[182:185], v[108:111]
	v_mfma_f32_16x16x32_bf16 v[100:103], v[158:161], v[198:201], v[100:103]
	v_mfma_f32_16x16x32_bf16 v[92:95], v[174:177], v[198:201], v[92:95]
	v_mfma_f32_16x16x32_bf16 v[84:87], v[158:161], v[206:209], v[84:87]
	v_mfma_f32_16x16x32_bf16 v[76:79], v[174:177], v[206:209], v[76:79]
	v_mfma_f32_16x16x32_bf16 v[68:71], v[158:161], v[214:217], v[68:71]
	v_mfma_f32_16x16x32_bf16 v[64:67], v[174:177], v[214:217], v[64:67]
	v_mfma_f32_16x16x32_bf16 v[116:119], v[170:173], v[190:193], v[116:119]
	v_mfma_f32_16x16x32_bf16 v[108:111], v[178:181], v[190:193], v[108:111]
	v_mfma_f32_16x16x32_bf16 v[100:103], v[170:173], v[202:205], v[100:103]
	v_mfma_f32_16x16x32_bf16 v[92:95], v[178:181], v[202:205], v[92:95]
	v_mfma_f32_16x16x32_bf16 v[84:87], v[170:173], v[210:213], v[84:87]
	v_mfma_f32_16x16x32_bf16 v[76:79], v[178:181], v[210:213], v[76:79]
	v_mfma_f32_16x16x32_bf16 v[68:71], v[170:173], v[218:221], v[68:71]
	v_mfma_f32_16x16x32_bf16 v[64:67], v[178:181], v[218:221], v[64:67]
	s_barrier
; #define PG8_STAGE(bufoff, gbase, voff) do { _Pragma("unroll") for (int _i = 0; _i < 2; ++_i) \
;         __builtin_amdgcn_global_load_lds((const unsigned*)((const char*)(gbase) + (voff)[_i]), (LAS unsigned*)(lds + (bufoff) + ldsw + _i * 8192), 16, 0, 0); } while (0)
; #define PG8_LDA(dst, b, h) do { _Pragma("unroll") for (int m = 0; m < 4; ++m) _Pragma("unroll") for (int k = 0; k < 2; ++k) dst[m][k] = *(const LAS bf16x8*)(lds + PG8_SA(b, h) + aoff + m * 2048 + k * 1024); } while (0)
; #define PG8_MMA(ai, bj, At, Bt) do { __builtin_amdgcn_s_setprio(1); _Pragma("unroll") for (int m = 0; m < 4; ++m) _Pragma("unroll") for (int n = 0; n < 2; ++n) _Pragma("unroll") for (int k = 0; k < 2; ++k) \
;         acc[ai][bj][m][n] = __builtin_amdgcn_mfma_f32_16x16x32_bf16(Bt[n][k], At[m][k], acc[ai][bj][m][n], 0, 0, 0); __builtin_amdgcn_s_setprio(0); } while (0)
; #define PG8_WAIT_V(n) asm volatile("s_waitcnt vmcnt(" #n ")" ::: "memory")
; #define PG8_WAIT_L(n) asm volatile("s_waitcnt lgkmcnt(" #n ")" ::: "memory")
; #define PG8_BAR __builtin_amdgcn_s_barrier()
; #define PG8_SCHED __builtin_amdgcn_sched_barrier(0)
; template <class Epi>
; __device__ __forceinline__ void gemm_phase(LAS unsigned char* lds, const Gemm g, const StaticOrder& S, const Epi& E) {
;     ...
;             PG8_LDA(At, 1, 1); PG8_STAGE(PG8_SB(1, 0), b3, voffB); PG8_STAGE(PG8_SB(1, 1), b3 + hstepB, voffB); PG8_STAGE(PG8_SA(1, 0), a3, voffA);
;             PG8_WAIT_V(8); PG8_WAIT_L(0); PG8_BAR; PG8_MMA(1, 0, At, B0); PG8_MMA(1, 1, At, B1); PG8_BAR; PG8_SCHED;
;         }
	s_add_i32 s22, s50, s26
	v_lshl_add_u64 v[162:163], v[162:163], 0, s[10:11]
	s_mov_b32 m0, s22
	ds_read_b128 v[182:185], v169 offset:49152
	ds_read_b128 v[190:193], v169 offset:50176
	ds_read_b128 v[198:201], v169 offset:51200
	ds_read_b128 v[202:205], v169 offset:52224
	ds_read_b128 v[206:209], v169 offset:53248
	ds_read_b128 v[210:213], v169 offset:54272
	ds_read_b128 v[214:217], v169 offset:55296
	ds_read_b128 v[218:221], v169 offset:56320
	global_load_lds_dwordx4 v[162:163], off
	s_add_i32 m0, s22, 0x2000
	s_add_u32 s2, s2, 0x20080
	v_lshl_add_u64 v[162:163], v[186:187], 0, s[10:11]
	s_addc_u32 s3, s3, 0
	s_add_i32 s22, s51, s26
	global_load_lds_dwordx4 v[162:163], off
	v_lshl_add_u64 v[162:163], s[2:3], 0, v[146:147]
	s_mov_b32 m0, s22
	s_nop 0
	global_load_lds_dwordx4 v[162:163], off
	v_lshl_add_u64 v[162:163], s[2:3], 0, v[150:151]
	s_add_i32 m0, s22, 0x2000
	s_nop 0
	global_load_lds_dwordx4 v[162:163], off
	v_lshl_add_u64 v[162:163], v[194:195], 0, s[10:11]
	s_mov_b32 m0, s33
	s_nop 0
	global_load_lds_dwordx4 v[162:163], off
	v_lshl_add_u64 v[162:163], v[222:223], 0, s[10:11]
	s_mov_b32 m0, s34
	s_nop 0
	global_load_lds_dwordx4 v[162:163], off
	s_waitcnt vmcnt(8)
	s_waitcnt lgkmcnt(0)
	s_barrier
	s_waitcnt lgkmcnt(0)
	v_mfma_f32_16x16x32_bf16 v[60:63], v[128:131], v[182:185], v[60:63]
	v_mfma_f32_16x16x32_bf16 v[56:59], v[136:139], v[182:185], v[56:59]
	v_mfma_f32_16x16x32_bf16 v[48:51], v[128:131], v[198:201], v[48:51]
	v_mfma_f32_16x16x32_bf16 v[40:43], v[136:139], v[198:201], v[40:43]
	v_mfma_f32_16x16x32_bf16 v[32:35], v[128:131], v[206:209], v[32:35]
	v_mfma_f32_16x16x32_bf16 v[24:27], v[136:139], v[206:209], v[24:27]
	v_mfma_f32_16x16x32_bf16 v[16:19], v[128:131], v[214:217], v[16:19]
	v_mfma_f32_16x16x32_bf16 v[8:11], v[136:139], v[214:217], v[8:11]
	v_mfma_f32_16x16x32_bf16 v[60:63], v[132:135], v[190:193], v[60:63]
	v_mfma_f32_16x16x32_bf16 v[56:59], v[140:143], v[190:193], v[56:59]
	v_mfma_f32_16x16x32_bf16 v[48:51], v[132:135], v[202:205], v[48:51]
	v_mfma_f32_16x16x32_bf16 v[40:43], v[140:143], v[202:205], v[40:43]
	v_mfma_f32_16x16x32_bf16 v[32:35], v[132:135], v[210:213], v[32:35]
	v_mfma_f32_16x16x32_bf16 v[24:27], v[140:143], v[210:213], v[24:27]
	v_mfma_f32_16x16x32_bf16 v[16:19], v[132:135], v[218:221], v[16:19]
	v_mfma_f32_16x16x32_bf16 v[8:11], v[140:143], v[218:221], v[8:11]
	v_mfma_f32_16x16x32_bf16 v[52:55], v[158:161], v[182:185], v[52:55]
	v_mfma_f32_16x16x32_bf16 v[44:47], v[174:177], v[182:185], v[44:47]
	v_mfma_f32_16x16x32_bf16 v[36:39], v[158:161], v[198:201], v[36:39]
	v_mfma_f32_16x16x32_bf16 v[28:31], v[174:177], v[198:201], v[28:31]
	v_mfma_f32_16x16x32_bf16 v[20:23], v[158:161], v[206:209], v[20:23]
	v_mfma_f32_16x16x32_bf16 v[12:15], v[174:177], v[206:209], v[12:15]
	v_mfma_f32_16x16x32_bf16 v[4:7], v[158:161], v[214:217], v[4:7]
	v_mfma_f32_16x16x32_bf16 v[0:3], v[174:177], v[214:217], v[0:3]
	v_mfma_f32_16x16x32_bf16 v[52:55], v[170:173], v[190:193], v[52:55]
	v_mfma_f32_16x16x32_bf16 v[44:47], v[178:181], v[190:193], v[44:47]
	v_mfma_f32_16x16x32_bf16 v[36:39], v[170:173], v[202:205], v[36:39]
	v_mfma_f32_16x16x32_bf16 v[28:31], v[178:181], v[202:205], v[28:31]
	v_mfma_f32_16x16x32_bf16 v[20:23], v[170:173], v[210:213], v[20:23]
	v_mfma_f32_16x16x32_bf16 v[12:15], v[178:181], v[210:213], v[12:15]
	v_mfma_f32_16x16x32_bf16 v[4:7], v[170:173], v[218:221], v[4:7]
	v_mfma_f32_16x16x32_bf16 v[0:3], v[178:181], v[218:221], v[0:3]
	s_barrier
	s_add_i32 s49, s49, 2
	s_add_u32 s20, s20, 0x100
	s_addc_u32 s21, s21, 0
	s_add_u32 s47, s47, 0x100
	s_addc_u32 s48, s48, 0
	s_cmp_gt_u32 s49, 5
	s_cbranch_scc0 .LBB0_721

; #define PG8_STAGE(bufoff, gbase, voff) do { _Pragma("unroll") for (int _i = 0; _i < 2; ++_i) \
;         __builtin_amdgcn_global_load_lds((const unsigned*)((const char*)(gbase) + (voff)[_i]), (LAS unsigned*)(lds + (bufoff) + ldsw + _i * 8192), 16, 0, 0); } while (0)
; #define PG8_LDA(dst, b, h) do { _Pragma("unroll") for (int m = 0; m < 4; ++m) _Pragma("unroll") for (int k = 0; k < 2; ++k) dst[m][k] = *(const LAS bf16x8*)(lds + PG8_SA(b, h) + aoff + m * 2048 + k * 1024); } while (0)
; #define PG8_LDB(dst, b, h) do { _Pragma("unroll") for (int n = 0; n < 2; ++n) _Pragma("unroll") for (int k = 0; k < 2; ++k) dst[n][k] = *(const LAS bf16x8*)(lds + PG8_SB(b, h) + boff + n * 2048 + k * 1024); } while (0)
; #define PG8_MMA(ai, bj, At, Bt) do { __builtin_amdgcn_s_setprio(1); _Pragma("unroll") for (int m = 0; m < 4; ++m) _Pragma("unroll") for (int n = 0; n < 2; ++n) _Pragma("unroll") for (int k = 0; k < 2; ++k) \
;         acc[ai][bj][m][n] = __builtin_amdgcn_mfma_f32_16x16x32_bf16(Bt[n][k], At[m][k], acc[ai][bj][m][n], 0, 0, 0); __builtin_amdgcn_s_setprio(0); } while (0)
; #define PG8_WAIT_V(n) asm volatile("s_waitcnt vmcnt(" #n ")" ::: "memory")
; #define PG8_WAIT_L(n) asm volatile("s_waitcnt lgkmcnt(" #n ")" ::: "memory")
; template <class Epi>
; __device__ __forceinline__ void gemm_phase(LAS unsigned char* lds, const Gemm g, const StaticOrder& S, const Epi& E) {
;     ...
;         const bool has_next = S.next(ui + 1, nxt);
;         const char* nA = has_next ? (const char*)g.A + (size_t)(nxt.pm >> 5) * aslab + (size_t)(nxt.pm & 31) * tstepA : cA; const char* nB = has_next ? (const char*)g.Bt + (size_t)nxt.pn * tstepB : cB;
;         for (int t = 0; t < nt; t += 2) {
;             const bool last = (t == nt - 2);
;             const char* a1 = cA + (size_t)(t + 1) * kstep;
;             const char* a2 = last ? nA : cA + (size_t)(t + 2) * kstep; const char* b2 = last ? nB : cB + (size_t)(t + 2) * kstep;
;             const char* a3 = a2 + kstep; const char* b3 = b2 + kstep;
;             PG8_LDB(B0, 0, 0); PG8_LDB(B1, 0, 1); PG8_SCHED; PG8_LDA(At, 0, 0); PG8_STAGE(PG8_SA(1, 1), a1 + hstepA, voffA);
;             PG8_WAIT_V(8); PG8_WAIT_L(0); PG8_BAR; PG8_MMA(0, 0, At, B0); PG8_MMA(0, 1, At, B1); PG8_BAR; PG8_SCHED;
;             PG8_LDA(At, 0, 1); PG8_STAGE(PG8_SB(0, 0), b2, voffB); PG8_STAGE(PG8_SB(0, 1), b2 + hstepB, voffB); PG8_STAGE(PG8_SA(0, 0), a2, voffA);
.LBB0_822:
	s_ashr_i32 s21, s20, 31
	s_lshl_b64 s[24:25], s[20:21], 19
	v_readlane_b32 s28, v235, 29
	v_readlane_b32 s29, v235, 30
	s_add_u32 s24, s28, s24
	s_addc_u32 s25, s29, s25
	s_and_b64 s[8:9], s[8:9], exec
	s_cselect_b32 s21, s25, s27
	s_cselect_b32 s46, s24, s26
	s_add_u32 s47, s26, 0x100
	s_addc_u32 s48, s27, 0
	s_mov_b32 s49, -2
	s_waitcnt lgkmcnt(0)
	s_waitcnt vmcnt(0)
	ds_read_b128 v[128:131], v187
	ds_read_b128 v[132:135], v187 offset:1024
	ds_read_b128 v[136:139], v187 offset:2048
	ds_read_b128 v[140:143], v187 offset:3072
	ds_read_b128 v[144:147], v188
	ds_read_b128 v[148:151], v188 offset:1024
	ds_read_b128 v[166:169], v188 offset:2048
	ds_read_b128 v[170:173], v188 offset:3072
	s_add_u32 s8, s2, 0x100
	s_addc_u32 s9, s3, 0
	s_cmp_eq_u32 s49, 12
	s_cselect_b32 s29, s23, s9
	s_cselect_b32 s28, s22, s8
	s_cselect_b32 s27, s21, s48
	s_cselect_b32 s26, s46, s47
	v_lshl_add_u64 v[182:183], s[2:3], 0, v[160:161]
	s_add_i32 m0, s31, 0xc000
	ds_read_b128 v[174:177], v190
	ds_read_b128 v[178:181], v190 offset:1024
	ds_read_b128 v[192:195], v190 offset:2048
	ds_read_b128 v[198:201], v190 offset:3072
	ds_read_b128 v[202:205], v190 offset:4096
	ds_read_b128 v[206:209], v190 offset:5120
	ds_read_b128 v[210:213], v190 offset:6144
	ds_read_b128 v[214:217], v190 offset:7168
	global_load_lds_dwordx4 v[182:183], off
	v_lshl_add_u64 v[182:183], s[2:3], 0, v[162:163]
	s_add_i32 m0, s31, 0xe000
	s_nop 0
	global_load_lds_dwordx4 v[182:183], off
	s_waitcnt vmcnt(8)
	s_waitcnt lgkmcnt(0)
	s_barrier
	s_waitcnt lgkmcnt(0)
	v_mfma_f32_16x16x32_bf16 v[124:127], v[128:131], v[174:177], 0
	v_mfma_f32_16x16x32_bf16 v[120:123], v[136:139], v[174:177], 0
	v_mfma_f32_16x16x32_bf16 v[108:111], v[128:131], v[192:195], 0
	v_mfma_f32_16x16x32_bf16 v[104:107], v[136:139], v[192:195], 0
	v_mfma_f32_16x16x32_bf16 v[92:95], v[128:131], v[202:205], 0
	v_mfma_f32_16x16x32_bf16 v[88:91], v[136:139], v[202:205], 0
	v_mfma_f32_16x16x32_bf16 v[76:79], v[128:131], v[210:213], 0
	v_mfma_f32_16x16x32_bf16 v[72:75], v[136:139], v[210:213], 0
	v_mfma_f32_16x16x32_bf16 v[124:127], v[132:135], v[178:181], v[124:127]
	v_mfma_f32_16x16x32_bf16 v[120:123], v[140:143], v[178:181], v[120:123]
	v_mfma_f32_16x16x32_bf16 v[108:111], v[132:135], v[198:201], v[108:111]
	v_mfma_f32_16x16x32_bf16 v[104:107], v[140:143], v[198:201], v[104:107]
	v_mfma_f32_16x16x32_bf16 v[92:95], v[132:135], v[206:209], v[92:95]
	v_mfma_f32_16x16x32_bf16 v[88:91], v[140:143], v[206:209], v[88:91]
	v_mfma_f32_16x16x32_bf16 v[76:79], v[132:135], v[214:217], v[76:79]
	v_mfma_f32_16x16x32_bf16 v[72:75], v[140:143], v[214:217], v[72:75]
	v_mfma_f32_16x16x32_bf16 v[116:119], v[144:147], v[174:177], 0
	v_mfma_f32_16x16x32_bf16 v[112:115], v[166:169], v[174:177], 0
	v_mfma_f32_16x16x32_bf16 v[100:103], v[144:147], v[192:195], 0
	v_mfma_f32_16x16x32_bf16 v[96:99], v[166:169], v[192:195], 0
	v_mfma_f32_16x16x32_bf16 v[84:87], v[144:147], v[202:205], 0
	v_mfma_f32_16x16x32_bf16 v[80:83], v[166:169], v[202:205], 0
	v_mfma_f32_16x16x32_bf16 v[68:71], v[144:147], v[210:213], 0
	v_mfma_f32_16x16x32_bf16 v[64:67], v[166:169], v[210:213], 0
	v_mfma_f32_16x16x32_bf16 v[116:119], v[148:151], v[178:181], v[116:119]
	v_mfma_f32_16x16x32_bf16 v[112:115], v[170:173], v[178:181], v[112:115]
	v_mfma_f32_16x16x32_bf16 v[100:103], v[148:151], v[198:201], v[100:103]
	v_mfma_f32_16x16x32_bf16 v[96:99], v[170:173], v[198:201], v[96:99]
	v_mfma_f32_16x16x32_bf16 v[84:87], v[148:151], v[206:209], v[84:87]
	v_mfma_f32_16x16x32_bf16 v[80:83], v[170:173], v[206:209], v[80:83]
	v_mfma_f32_16x16x32_bf16 v[68:71], v[148:151], v[214:217], v[68:71]
	v_mfma_f32_16x16x32_bf16 v[64:67], v[170:173], v[214:217], v[64:67]
	s_barrier
	s_add_i32 s2, s41, s30
	v_lshl_add_u64 v[182:183], s[26:27], 0, v[154:155]
	s_mov_b32 m0, s2
	ds_read_b128 v[174:177], v190 offset:16384
	ds_read_b128 v[178:181], v190 offset:17408
	ds_read_b128 v[192:195], v190 offset:18432
	ds_read_b128 v[198:201], v190 offset:19456
	ds_read_b128 v[202:205], v190 offset:20480
	ds_read_b128 v[206:209], v190 offset:21504
	ds_read_b128 v[210:213], v190 offset:22528
	ds_read_b128 v[214:217], v190 offset:23552
	global_load_lds_dwordx4 v[182:183], off
	s_add_i32 m0, s2, 0x2000
	s_add_u32 s2, s26, 0x40000
	v_lshl_add_u64 v[218:219], s[26:27], 0, v[158:159]
	s_addc_u32 s3, s27, 0
	s_add_i32 s50, s42, s30
	global_load_lds_dwordx4 v[218:219], off
	v_lshl_add_u64 v[220:221], s[2:3], 0, v[154:155]
	s_mov_b32 m0, s50
	v_lshl_add_u64 v[222:223], s[28:29], 0, v[156:157]
	global_load_lds_dwordx4 v[220:221], off
	v_lshl_add_u64 v[220:221], s[2:3], 0, v[158:159]
	s_add_i32 m0, s50, 0x2000
	s_nop 0
	global_load_lds_dwordx4 v[220:221], off
	v_lshl_add_u64 v[220:221], s[28:29], 0, v[152:153]
	s_mov_b32 m0, s31
	s_nop 0
	global_load_lds_dwordx4 v[220:221], off
	s_mov_b32 m0, s33
	s_nop 0
	global_load_lds_dwordx4 v[222:223], off
	s_waitcnt vmcnt(8)
	s_waitcnt lgkmcnt(0)
	s_barrier
; #define PG8_STAGE(bufoff, gbase, voff) do { _Pragma("unroll") for (int _i = 0; _i < 2; ++_i) \
;         __builtin_amdgcn_global_load_lds((const unsigned*)((const char*)(gbase) + (voff)[_i]), (LAS unsigned*)(lds + (bufoff) + ldsw + _i * 8192), 16, 0, 0); } while (0)
; #define PG8_LDA(dst, b, h) do { _Pragma("unroll") for (int m = 0; m < 4; ++m) _Pragma("unroll") for (int k = 0; k < 2; ++k) dst[m][k] = *(const LAS bf16x8*)(lds + PG8_SA(b, h) + aoff + m * 2048 + k * 1024); } while (0)
; #define PG8_LDB(dst, b, h) do { _Pragma("unroll") for (int n = 0; n < 2; ++n) _Pragma("unroll") for (int k = 0; k < 2; ++k) dst[n][k] = *(const LAS bf16x8*)(lds + PG8_SB(b, h) + boff + n * 2048 + k * 1024); } while (0)
; #define PG8_MMA(ai, bj, At, Bt) do { __builtin_amdgcn_s_setprio(1); _Pragma("unroll") for (int m = 0; m < 4; ++m) _Pragma("unroll") for (int n = 0; n < 2; ++n) _Pragma("unroll") for (int k = 0; k < 2; ++k) \
;         acc[ai][bj][m][n] = __builtin_amdgcn_mfma_f32_16x16x32_bf16(Bt[n][k], At[m][k], acc[ai][bj][m][n], 0, 0, 0); __builtin_amdgcn_s_setprio(0); } while (0)
; #define PG8_WAIT_V(n) asm volatile("s_waitcnt vmcnt(" #n ")" ::: "memory")
; #define PG8_WAIT_L(n) asm volatile("s_waitcnt lgkmcnt(" #n ")" ::: "memory")
; #define PG8_BAR __builtin_amdgcn_s_barrier()
; #define PG8_SCHED __builtin_amdgcn_sched_barrier(0)
; template <class Epi>
; __device__ __forceinline__ void gemm_phase(LAS unsigned char* lds, const Gemm g, const StaticOrder& S, const Epi& E) {
;     ...
;             PG8_WAIT_V(8); PG8_WAIT_L(0); PG8_BAR; PG8_MMA(1, 0, At, B0); PG8_MMA(1, 1, At, B1); PG8_BAR; PG8_SCHED;
;             PG8_LDB(B0, 1, 0); PG8_LDB(B1, 1, 1); PG8_SCHED; PG8_LDA(At, 1, 0); PG8_STAGE(PG8_SA(0, 1), a2 + hstepA, voffA);
;             PG8_WAIT_V(8); PG8_WAIT_L(0); PG8_BAR; PG8_MMA(0, 0, At, B0); PG8_MMA(0, 1, At, B1); PG8_BAR; PG8_SCHED;
	s_waitcnt lgkmcnt(0)
	v_mfma_f32_16x16x32_bf16 v[60:63], v[128:131], v[174:177], 0
	v_mfma_f32_16x16x32_bf16 v[56:59], v[136:139], v[174:177], 0
	v_mfma_f32_16x16x32_bf16 v[44:47], v[128:131], v[192:195], 0
	v_mfma_f32_16x16x32_bf16 v[40:43], v[136:139], v[192:195], 0
	v_mfma_f32_16x16x32_bf16 v[28:31], v[128:131], v[202:205], 0
	v_mfma_f32_16x16x32_bf16 v[24:27], v[136:139], v[202:205], 0
	v_mfma_f32_16x16x32_bf16 v[12:15], v[128:131], v[210:213], 0
	v_mfma_f32_16x16x32_bf16 v[8:11], v[136:139], v[210:213], 0
	v_mfma_f32_16x16x32_bf16 v[60:63], v[132:135], v[178:181], v[60:63]
	v_mfma_f32_16x16x32_bf16 v[56:59], v[140:143], v[178:181], v[56:59]
	v_mfma_f32_16x16x32_bf16 v[44:47], v[132:135], v[198:201], v[44:47]
	v_mfma_f32_16x16x32_bf16 v[40:43], v[140:143], v[198:201], v[40:43]
	v_mfma_f32_16x16x32_bf16 v[28:31], v[132:135], v[206:209], v[28:31]
	v_mfma_f32_16x16x32_bf16 v[24:27], v[140:143], v[206:209], v[24:27]
	v_mfma_f32_16x16x32_bf16 v[12:15], v[132:135], v[214:217], v[12:15]
	v_mfma_f32_16x16x32_bf16 v[8:11], v[140:143], v[214:217], v[8:11]
	v_mfma_f32_16x16x32_bf16 v[52:55], v[144:147], v[174:177], 0
	v_mfma_f32_16x16x32_bf16 v[48:51], v[166:169], v[174:177], 0
	v_mfma_f32_16x16x32_bf16 v[36:39], v[144:147], v[192:195], 0
	v_mfma_f32_16x16x32_bf16 v[32:35], v[166:169], v[192:195], 0
	v_mfma_f32_16x16x32_bf16 v[20:23], v[144:147], v[202:205], 0
	v_mfma_f32_16x16x32_bf16 v[16:19], v[166:169], v[202:205], 0
	v_mfma_f32_16x16x32_bf16 v[4:7], v[144:147], v[210:213], 0
	v_mfma_f32_16x16x32_bf16 v[0:3], v[166:169], v[210:213], 0
	v_mfma_f32_16x16x32_bf16 v[52:55], v[148:151], v[178:181], v[52:55]
	v_mfma_f32_16x16x32_bf16 v[48:51], v[170:173], v[178:181], v[48:51]
	v_mfma_f32_16x16x32_bf16 v[36:39], v[148:151], v[198:201], v[36:39]
	v_mfma_f32_16x16x32_bf16 v[32:35], v[170:173], v[198:201], v[32:35]
	v_mfma_f32_16x16x32_bf16 v[20:23], v[148:151], v[206:209], v[20:23]
	v_mfma_f32_16x16x32_bf16 v[16:19], v[170:173], v[206:209], v[16:19]
	v_mfma_f32_16x16x32_bf16 v[4:7], v[148:151], v[214:217], v[4:7]
	v_mfma_f32_16x16x32_bf16 v[0:3], v[170:173], v[214:217], v[0:3]
	s_barrier
	s_add_i32 s50, 0, 0x18000
	s_add_i32 s51, 0, 0x1c000
	v_add_u32_e32 v140, s50, v185
	v_add_u32_e32 v170, s51, v185
	ds_read_b128 v[128:131], v140
	ds_read_b128 v[132:135], v140 offset:1024
	ds_read_b128 v[136:139], v140 offset:2048
	ds_read_b128 v[140:143], v140 offset:3072
	ds_read_b128 v[144:147], v170
	ds_read_b128 v[148:151], v170 offset:1024
	ds_read_b128 v[166:169], v170 offset:2048
	ds_read_b128 v[170:173], v170 offset:3072
	s_add_u32 s2, s28, 0x110000
	s_addc_u32 s3, s29, 0
	s_mov_b32 m0, s34
	v_lshl_add_u64 v[224:225], s[2:3], 0, v[152:153]
	ds_read_b128 v[174:177], v190 offset:32768
	ds_read_b128 v[178:181], v190 offset:33792
	ds_read_b128 v[192:195], v190 offset:34816
	ds_read_b128 v[198:201], v190 offset:35840
	ds_read_b128 v[202:205], v190 offset:36864
	ds_read_b128 v[206:209], v190 offset:37888
	ds_read_b128 v[210:213], v190 offset:38912
	ds_read_b128 v[214:217], v190 offset:39936
	global_load_lds_dwordx4 v[224:225], off
	v_lshl_add_u64 v[224:225], s[2:3], 0, v[156:157]
	s_mov_b32 m0, s35
	s_nop 0
	global_load_lds_dwordx4 v[224:225], off
	s_waitcnt vmcnt(8)
	s_waitcnt lgkmcnt(0)
	s_barrier
	s_waitcnt lgkmcnt(0)
	v_mfma_f32_16x16x32_bf16 v[124:127], v[128:131], v[174:177], v[124:127]
	v_mfma_f32_16x16x32_bf16 v[120:123], v[136:139], v[174:177], v[120:123]
	v_mfma_f32_16x16x32_bf16 v[108:111], v[128:131], v[192:195], v[108:111]
	v_mfma_f32_16x16x32_bf16 v[104:107], v[136:139], v[192:195], v[104:107]
	v_mfma_f32_16x16x32_bf16 v[92:95], v[128:131], v[202:205], v[92:95]
	v_mfma_f32_16x16x32_bf16 v[88:91], v[136:139], v[202:205], v[88:91]
	v_mfma_f32_16x16x32_bf16 v[76:79], v[128:131], v[210:213], v[76:79]
	v_mfma_f32_16x16x32_bf16 v[72:75], v[136:139], v[210:213], v[72:75]
	v_mfma_f32_16x16x32_bf16 v[124:127], v[132:135], v[178:181], v[124:127]
	v_mfma_f32_16x16x32_bf16 v[120:123], v[140:143], v[178:181], v[120:123]
	v_mfma_f32_16x16x32_bf16 v[108:111], v[132:135], v[198:201], v[108:111]
	v_mfma_f32_16x16x32_bf16 v[104:107], v[140:143], v[198:201], v[104:107]
	v_mfma_f32_16x16x32_bf16 v[92:95], v[132:135], v[206:209], v[92:95]
	v_mfma_f32_16x16x32_bf16 v[88:91], v[140:143], v[206:209], v[88:91]
	v_mfma_f32_16x16x32_bf16 v[76:79], v[132:135], v[214:217], v[76:79]
	v_mfma_f32_16x16x32_bf16 v[72:75], v[140:143], v[214:217], v[72:75]
	v_mfma_f32_16x16x32_bf16 v[116:119], v[144:147], v[174:177], v[116:119]
	v_mfma_f32_16x16x32_bf16 v[112:115], v[166:169], v[174:177], v[112:115]
	v_mfma_f32_16x16x32_bf16 v[100:103], v[144:147], v[192:195], v[100:103]
	v_mfma_f32_16x16x32_bf16 v[96:99], v[166:169], v[192:195], v[96:99]
	v_mfma_f32_16x16x32_bf16 v[84:87], v[144:147], v[202:205], v[84:87]
	v_mfma_f32_16x16x32_bf16 v[80:83], v[166:169], v[202:205], v[80:83]
	v_mfma_f32_16x16x32_bf16 v[68:71], v[144:147], v[210:213], v[68:71]
	v_mfma_f32_16x16x32_bf16 v[64:67], v[166:169], v[210:213], v[64:67]
	v_mfma_f32_16x16x32_bf16 v[116:119], v[148:151], v[178:181], v[116:119]
	v_mfma_f32_16x16x32_bf16 v[112:115], v[170:173], v[178:181], v[112:115]
	v_mfma_f32_16x16x32_bf16 v[100:103], v[148:151], v[198:201], v[100:103]
	v_mfma_f32_16x16x32_bf16 v[96:99], v[170:173], v[198:201], v[96:99]
	v_mfma_f32_16x16x32_bf16 v[84:87], v[148:151], v[206:209], v[84:87]
	v_mfma_f32_16x16x32_bf16 v[80:83], v[170:173], v[206:209], v[80:83]
	v_mfma_f32_16x16x32_bf16 v[68:71], v[148:151], v[214:217], v[68:71]
	v_mfma_f32_16x16x32_bf16 v[64:67], v[170:173], v[214:217], v[64:67]
	s_barrier
; #define PG8_STAGE(bufoff, gbase, voff) do { _Pragma("unroll") for (int _i = 0; _i < 2; ++_i) \
;         __builtin_amdgcn_global_load_lds((const unsigned*)((const char*)(gbase) + (voff)[_i]), (LAS unsigned*)(lds + (bufoff) + ldsw + _i * 8192), 16, 0, 0); } while (0)
; #define PG8_LDA(dst, b, h) do { _Pragma("unroll") for (int m = 0; m < 4; ++m) _Pragma("unroll") for (int k = 0; k < 2; ++k) dst[m][k] = *(const LAS bf16x8*)(lds + PG8_SA(b, h) + aoff + m * 2048 + k * 1024); } while (0)
; #define PG8_MMA(ai, bj, At, Bt) do { __builtin_amdgcn_s_setprio(1); _Pragma("unroll") for (int m = 0; m < 4; ++m) _Pragma("unroll") for (int n = 0; n < 2; ++n) _Pragma("unroll") for (int k = 0; k < 2; ++k) \
;         acc[ai][bj][m][n] = __builtin_amdgcn_mfma_f32_16x16x32_bf16(Bt[n][k], At[m][k], acc[ai][bj][m][n], 0, 0, 0); __builtin_amdgcn_s_setprio(0); } while (0)
; #define PG8_WAIT_V(n) asm volatile("s_waitcnt vmcnt(" #n ")" ::: "memory")
; #define PG8_WAIT_L(n) asm volatile("s_waitcnt lgkmcnt(" #n ")" ::: "memory")
; #define PG8_BAR __builtin_amdgcn_s_barrier()
; #define PG8_SCHED __builtin_amdgcn_sched_barrier(0)
; template <class Epi>
; __device__ __forceinline__ void gemm_phase(LAS unsigned char* lds, const Gemm g, const StaticOrder& S, const Epi& E) {
;     ...
;             PG8_LDA(At, 1, 1); PG8_STAGE(PG8_SB(1, 0), b3, voffB); PG8_STAGE(PG8_SB(1, 1), b3 + hstepB, voffB); PG8_STAGE(PG8_SA(1, 0), a3, voffA);
;             PG8_WAIT_V(8); PG8_WAIT_L(0); PG8_BAR; PG8_MMA(1, 0, At, B0); PG8_MMA(1, 1, At, B1); PG8_BAR; PG8_SCHED;
;         }
	s_add_i32 s2, s50, s30
	v_lshl_add_u64 v[182:183], v[182:183], 0, s[16:17]
	s_mov_b32 m0, s2
	ds_read_b128 v[174:177], v190 offset:49152
	ds_read_b128 v[178:181], v190 offset:50176
	ds_read_b128 v[192:195], v190 offset:51200
	ds_read_b128 v[198:201], v190 offset:52224
	ds_read_b128 v[202:205], v190 offset:53248
	ds_read_b128 v[206:209], v190 offset:54272
	ds_read_b128 v[210:213], v190 offset:55296
	ds_read_b128 v[214:217], v190 offset:56320
	global_load_lds_dwordx4 v[182:183], off
	s_add_i32 m0, s2, 0x2000
	s_add_u32 s2, s26, 0x40080
	v_lshl_add_u64 v[182:183], v[218:219], 0, s[16:17]
	s_addc_u32 s3, s27, 0
	s_add_i32 s26, s51, s30
	global_load_lds_dwordx4 v[182:183], off
	v_lshl_add_u64 v[182:183], s[2:3], 0, v[154:155]
	s_mov_b32 m0, s26
	s_nop 0
	global_load_lds_dwordx4 v[182:183], off
	v_lshl_add_u64 v[182:183], s[2:3], 0, v[158:159]
	s_add_i32 m0, s26, 0x2000
	s_nop 0
	global_load_lds_dwordx4 v[182:183], off
	v_lshl_add_u64 v[182:183], v[220:221], 0, s[16:17]
	s_mov_b32 m0, s37
	s_nop 0
	global_load_lds_dwordx4 v[182:183], off
	v_lshl_add_u64 v[182:183], v[222:223], 0, s[16:17]
	s_mov_b32 m0, s38
	s_nop 0
	global_load_lds_dwordx4 v[182:183], off
	s_waitcnt vmcnt(8)
	s_waitcnt lgkmcnt(0)
	s_barrier
	s_waitcnt lgkmcnt(0)
	v_mfma_f32_16x16x32_bf16 v[60:63], v[128:131], v[174:177], v[60:63]
	v_mfma_f32_16x16x32_bf16 v[56:59], v[136:139], v[174:177], v[56:59]
	v_mfma_f32_16x16x32_bf16 v[44:47], v[128:131], v[192:195], v[44:47]
	v_mfma_f32_16x16x32_bf16 v[40:43], v[136:139], v[192:195], v[40:43]
	v_mfma_f32_16x16x32_bf16 v[28:31], v[128:131], v[202:205], v[28:31]
	v_mfma_f32_16x16x32_bf16 v[24:27], v[136:139], v[202:205], v[24:27]
	v_mfma_f32_16x16x32_bf16 v[12:15], v[128:131], v[210:213], v[12:15]
	v_mfma_f32_16x16x32_bf16 v[8:11], v[136:139], v[210:213], v[8:11]
	v_mfma_f32_16x16x32_bf16 v[60:63], v[132:135], v[178:181], v[60:63]
	v_mfma_f32_16x16x32_bf16 v[56:59], v[140:143], v[178:181], v[56:59]
	v_mfma_f32_16x16x32_bf16 v[44:47], v[132:135], v[198:201], v[44:47]
	v_mfma_f32_16x16x32_bf16 v[40:43], v[140:143], v[198:201], v[40:43]
	v_mfma_f32_16x16x32_bf16 v[28:31], v[132:135], v[206:209], v[28:31]
	v_mfma_f32_16x16x32_bf16 v[24:27], v[140:143], v[206:209], v[24:27]
	v_mfma_f32_16x16x32_bf16 v[12:15], v[132:135], v[214:217], v[12:15]
	v_mfma_f32_16x16x32_bf16 v[8:11], v[140:143], v[214:217], v[8:11]
	v_mfma_f32_16x16x32_bf16 v[52:55], v[144:147], v[174:177], v[52:55]
	v_mfma_f32_16x16x32_bf16 v[48:51], v[166:169], v[174:177], v[48:51]
	v_mfma_f32_16x16x32_bf16 v[36:39], v[144:147], v[192:195], v[36:39]
	v_mfma_f32_16x16x32_bf16 v[32:35], v[166:169], v[192:195], v[32:35]
	v_mfma_f32_16x16x32_bf16 v[20:23], v[144:147], v[202:205], v[20:23]
	v_mfma_f32_16x16x32_bf16 v[16:19], v[166:169], v[202:205], v[16:19]
	v_mfma_f32_16x16x32_bf16 v[4:7], v[144:147], v[210:213], v[4:7]
	v_mfma_f32_16x16x32_bf16 v[0:3], v[166:169], v[210:213], v[0:3]
	v_mfma_f32_16x16x32_bf16 v[52:55], v[148:151], v[178:181], v[52:55]
	v_mfma_f32_16x16x32_bf16 v[48:51], v[170:173], v[178:181], v[48:51]
	v_mfma_f32_16x16x32_bf16 v[36:39], v[148:151], v[198:201], v[36:39]
	v_mfma_f32_16x16x32_bf16 v[32:35], v[170:173], v[198:201], v[32:35]
	v_mfma_f32_16x16x32_bf16 v[20:23], v[148:151], v[206:209], v[20:23]
	v_mfma_f32_16x16x32_bf16 v[16:19], v[170:173], v[206:209], v[16:19]
	v_mfma_f32_16x16x32_bf16 v[4:7], v[148:151], v[214:217], v[4:7]
	v_mfma_f32_16x16x32_bf16 v[0:3], v[170:173], v[214:217], v[0:3]
	s_barrier
	s_add_i32 s49, s49, 2
	s_add_u32 s47, s47, 0x100
	s_addc_u32 s48, s48, 0
	s_cmp_gt_u32 s49, 13
	s_mov_b64 s[2:3], s[8:9]
	s_cbranch_scc0 .LBB0_823

; #define PG8_STAGE(bufoff, gbase, voff) do { _Pragma("unroll") for (int _i = 0; _i < 2; ++_i) \
;         __builtin_amdgcn_global_load_lds((const unsigned*)((const char*)(gbase) + (voff)[_i]), (LAS unsigned*)(lds + (bufoff) + ldsw + _i * 8192), 16, 0, 0); } while (0)
; #define PG8_LDA(dst, b, h) do { _Pragma("unroll") for (int m = 0; m < 4; ++m) _Pragma("unroll") for (int k = 0; k < 2; ++k) dst[m][k] = *(const LAS bf16x8*)(lds + PG8_SA(b, h) + aoff + m * 2048 + k * 1024); } while (0)
; #define PG8_LDB(dst, b, h) do { _Pragma("unroll") for (int n = 0; n < 2; ++n) _Pragma("unroll") for (int k = 0; k < 2; ++k) dst[n][k] = *(const LAS bf16x8*)(lds + PG8_SB(b, h) + boff + n * 2048 + k * 1024); } while (0)
; #define PG8_MMA(ai, bj, At, Bt) do { __builtin_amdgcn_s_setprio(1); _Pragma("unroll") for (int m = 0; m < 4; ++m) _Pragma("unroll") for (int n = 0; n < 2; ++n) _Pragma("unroll") for (int k = 0; k < 2; ++k) \
;         acc[ai][bj][m][n] = __builtin_amdgcn_mfma_f32_16x16x32_bf16(Bt[n][k], At[m][k], acc[ai][bj][m][n], 0, 0, 0); __builtin_amdgcn_s_setprio(0); } while (0)
; #define PG8_WAIT_V(n) asm volatile("s_waitcnt vmcnt(" #n ")" ::: "memory")
; #define PG8_WAIT_L(n) asm volatile("s_waitcnt lgkmcnt(" #n ")" ::: "memory")
; template <class Epi>
; __device__ __forceinline__ void gemm_phase(LAS unsigned char* lds, const Gemm g, const StaticOrder& S, const Epi& E) {
;     ...
;         const bool has_next = S.next(ui + 1, nxt);
;         const char* nA = has_next ? (const char*)g.A + (size_t)(nxt.pm >> 5) * aslab + (size_t)(nxt.pm & 31) * tstepA : cA; const char* nB = has_next ? (const char*)g.Bt + (size_t)nxt.pn * tstepB : cB;
;         for (int t = 0; t < nt; t += 2) {
;             const bool last = (t == nt - 2);
;             const char* a1 = cA + (size_t)(t + 1) * kstep;
;             const char* a2 = last ? nA : cA + (size_t)(t + 2) * kstep; const char* b2 = last ? nB : cB + (size_t)(t + 2) * kstep;
;             const char* a3 = a2 + kstep; const char* b3 = b2 + kstep;
;             PG8_LDB(B0, 0, 0); PG8_LDB(B1, 0, 1); PG8_SCHED; PG8_LDA(At, 0, 0); PG8_STAGE(PG8_SA(1, 1), a1 + hstepA, voffA);
;             PG8_WAIT_V(8); PG8_WAIT_L(0); PG8_BAR; PG8_MMA(0, 0, At, B0); PG8_MMA(0, 1, At, B1); PG8_BAR; PG8_SCHED;
;             PG8_LDA(At, 0, 1); PG8_STAGE(PG8_SB(0, 0), b2, voffB); PG8_STAGE(PG8_SB(0, 1), b2 + hstepB, voffB); PG8_STAGE(PG8_SA(0, 0), a2, voffA);
.LBB0_928:
	s_ashr_i32 s12, s40, 5
	s_ashr_i32 s13, s12, 31
	s_lshl_b64 s[12:13], s[12:13], 24
	v_readlane_b32 s14, v235, 38
	v_readlane_b32 s15, v235, 39
	s_add_u32 s11, s14, s12
	s_addc_u32 s13, s15, s13
	s_lshl_b32 s12, s40, 19
	s_and_b32 s12, s12, 0xf80000
	s_add_u32 s12, s11, s12
	s_addc_u32 s13, s13, 0
	s_and_b64 s[14:15], s[4:5], exec
	s_cselect_b32 s43, s13, s17
	s_cselect_b32 s44, s12, s16
	s_ashr_i32 s11, s10, 31
	s_lshl_b64 s[14:15], s[10:11], 19
	v_readlane_b32 s18, v235, 31
	v_readlane_b32 s19, v235, 32
	s_add_u32 s14, s18, s14
	s_addc_u32 s15, s19, s15
	s_and_b64 s[18:19], s[4:5], exec
	s_cselect_b32 s11, s15, s3
	s_cselect_b32 s45, s14, s2
	s_add_u32 s16, s16, 0x40080
	s_addc_u32 s17, s17, 0
	s_add_u32 s46, s2, 0x100
	s_addc_u32 s47, s3, 0
	s_mov_b32 s48, -2
	s_waitcnt vmcnt(0)
	ds_read_b128 v[146:149], v153
	ds_read_b128 v[160:163], v153 offset:1024
	ds_read_b128 v[164:167], v153 offset:2048
	ds_read_b128 v[168:171], v153 offset:3072
	ds_read_b128 v[172:175], v154
	ds_read_b128 v[176:179], v154 offset:1024
	ds_read_b128 v[180:183], v154 offset:2048
	ds_read_b128 v[184:187], v154 offset:3072
	s_add_u32 s2, s16, 0xfffc0080
	s_addc_u32 s3, s17, -1
	s_cmp_eq_u32 s48, 12
	s_cselect_b32 s19, s43, s3
	s_cselect_b32 s18, s44, s2
	s_cselect_b32 s3, s11, s47
	s_cselect_b32 s2, s45, s46
	v_lshl_add_u64 v[194:195], s[16:17], 0, v[140:141]
	s_add_i32 m0, s22, 0xc000
	ds_read_b128 v[190:193], v155
	ds_read_b128 v[198:201], v155 offset:1024
	ds_read_b128 v[202:205], v155 offset:2048
	ds_read_b128 v[206:209], v155 offset:3072
	ds_read_b128 v[210:213], v155 offset:4096
	ds_read_b128 v[214:217], v155 offset:5120
	ds_read_b128 v[218:221], v155 offset:6144
	ds_read_b128 v[222:225], v155 offset:7168
	global_load_lds_dwordx4 v[194:195], off
	v_lshl_add_u64 v[194:195], s[16:17], 0, v[142:143]
	s_add_i32 m0, s22, 0xe000
	s_nop 0
	global_load_lds_dwordx4 v[194:195], off
	s_waitcnt vmcnt(8)
	s_waitcnt lgkmcnt(0)
	s_barrier
	s_waitcnt lgkmcnt(0)
	v_mfma_f32_16x16x32_bf16 v[124:127], v[146:149], v[190:193], 0
	v_mfma_f32_16x16x32_bf16 v[116:119], v[164:167], v[190:193], 0
	v_mfma_f32_16x16x32_bf16 v[108:111], v[146:149], v[202:205], 0
	v_mfma_f32_16x16x32_bf16 v[100:103], v[164:167], v[202:205], 0
	v_mfma_f32_16x16x32_bf16 v[92:95], v[146:149], v[210:213], 0
	v_mfma_f32_16x16x32_bf16 v[84:87], v[164:167], v[210:213], 0
	v_mfma_f32_16x16x32_bf16 v[76:79], v[146:149], v[218:221], 0
	v_mfma_f32_16x16x32_bf16 v[68:71], v[164:167], v[218:221], 0
	v_mfma_f32_16x16x32_bf16 v[124:127], v[160:163], v[198:201], v[124:127]
	v_mfma_f32_16x16x32_bf16 v[116:119], v[168:171], v[198:201], v[116:119]
	v_mfma_f32_16x16x32_bf16 v[108:111], v[160:163], v[206:209], v[108:111]
	v_mfma_f32_16x16x32_bf16 v[100:103], v[168:171], v[206:209], v[100:103]
	v_mfma_f32_16x16x32_bf16 v[92:95], v[160:163], v[214:217], v[92:95]
	v_mfma_f32_16x16x32_bf16 v[84:87], v[168:171], v[214:217], v[84:87]
	v_mfma_f32_16x16x32_bf16 v[76:79], v[160:163], v[222:225], v[76:79]
	v_mfma_f32_16x16x32_bf16 v[68:71], v[168:171], v[222:225], v[68:71]
	v_mfma_f32_16x16x32_bf16 v[120:123], v[172:175], v[190:193], 0
	v_mfma_f32_16x16x32_bf16 v[112:115], v[180:183], v[190:193], 0
	v_mfma_f32_16x16x32_bf16 v[104:107], v[172:175], v[202:205], 0
	v_mfma_f32_16x16x32_bf16 v[96:99], v[180:183], v[202:205], 0
	v_mfma_f32_16x16x32_bf16 v[88:91], v[172:175], v[210:213], 0
	v_mfma_f32_16x16x32_bf16 v[80:83], v[180:183], v[210:213], 0
	v_mfma_f32_16x16x32_bf16 v[72:75], v[172:175], v[218:221], 0
	v_mfma_f32_16x16x32_bf16 v[64:67], v[180:183], v[218:221], 0
	v_mfma_f32_16x16x32_bf16 v[120:123], v[176:179], v[198:201], v[120:123]
	v_mfma_f32_16x16x32_bf16 v[112:115], v[184:187], v[198:201], v[112:115]
	v_mfma_f32_16x16x32_bf16 v[104:107], v[176:179], v[206:209], v[104:107]
	v_mfma_f32_16x16x32_bf16 v[96:99], v[184:187], v[206:209], v[96:99]
	v_mfma_f32_16x16x32_bf16 v[88:91], v[176:179], v[214:217], v[88:91]
	v_mfma_f32_16x16x32_bf16 v[80:83], v[184:187], v[214:217], v[80:83]
	v_mfma_f32_16x16x32_bf16 v[72:75], v[176:179], v[222:225], v[72:75]
	v_mfma_f32_16x16x32_bf16 v[64:67], v[184:187], v[222:225], v[64:67]
	s_barrier
	s_add_i32 s49, s35, s20
	v_lshl_add_u64 v[194:195], s[2:3], 0, v[132:133]
	s_mov_b32 m0, s49
	ds_read_b128 v[190:193], v155 offset:16384
	ds_read_b128 v[198:201], v155 offset:17408
	ds_read_b128 v[202:205], v155 offset:18432
	ds_read_b128 v[206:209], v155 offset:19456
	ds_read_b128 v[210:213], v155 offset:20480
	ds_read_b128 v[214:217], v155 offset:21504
	ds_read_b128 v[218:221], v155 offset:22528
	ds_read_b128 v[222:225], v155 offset:23552
	global_load_lds_dwordx4 v[194:195], off
	s_add_i32 m0, s49, 0x2000
	s_add_u32 s50, s2, 0x40000
	v_lshl_add_u64 v[226:227], s[2:3], 0, v[128:129]
	s_addc_u32 s51, s3, 0
	s_add_i32 s49, s36, s20
	global_load_lds_dwordx4 v[226:227], off
	v_lshl_add_u64 v[228:229], s[50:51], 0, v[132:133]
	s_mov_b32 m0, s49
	v_lshl_add_u64 v[230:231], s[18:19], 0, v[130:131]
	global_load_lds_dwordx4 v[228:229], off
	v_lshl_add_u64 v[228:229], s[50:51], 0, v[128:129]
	s_add_i32 m0, s49, 0x2000
	s_nop 0
	global_load_lds_dwordx4 v[228:229], off
	v_lshl_add_u64 v[228:229], s[18:19], 0, v[134:135]
	s_mov_b32 m0, s22
	s_nop 0
	global_load_lds_dwordx4 v[228:229], off
	s_mov_b32 m0, s23
	s_nop 0
	global_load_lds_dwordx4 v[230:231], off
	s_waitcnt vmcnt(8)
	s_waitcnt lgkmcnt(0)
	s_barrier
; #define PG8_STAGE(bufoff, gbase, voff) do { _Pragma("unroll") for (int _i = 0; _i < 2; ++_i) \
;         __builtin_amdgcn_global_load_lds((const unsigned*)((const char*)(gbase) + (voff)[_i]), (LAS unsigned*)(lds + (bufoff) + ldsw + _i * 8192), 16, 0, 0); } while (0)
; #define PG8_LDA(dst, b, h) do { _Pragma("unroll") for (int m = 0; m < 4; ++m) _Pragma("unroll") for (int k = 0; k < 2; ++k) dst[m][k] = *(const LAS bf16x8*)(lds + PG8_SA(b, h) + aoff + m * 2048 + k * 1024); } while (0)
; #define PG8_LDB(dst, b, h) do { _Pragma("unroll") for (int n = 0; n < 2; ++n) _Pragma("unroll") for (int k = 0; k < 2; ++k) dst[n][k] = *(const LAS bf16x8*)(lds + PG8_SB(b, h) + boff + n * 2048 + k * 1024); } while (0)
; #define PG8_MMA(ai, bj, At, Bt) do { __builtin_amdgcn_s_setprio(1); _Pragma("unroll") for (int m = 0; m < 4; ++m) _Pragma("unroll") for (int n = 0; n < 2; ++n) _Pragma("unroll") for (int k = 0; k < 2; ++k) \
;         acc[ai][bj][m][n] = __builtin_amdgcn_mfma_f32_16x16x32_bf16(Bt[n][k], At[m][k], acc[ai][bj][m][n], 0, 0, 0); __builtin_amdgcn_s_setprio(0); } while (0)
; #define PG8_WAIT_V(n) asm volatile("s_waitcnt vmcnt(" #n ")" ::: "memory")
; #define PG8_WAIT_L(n) asm volatile("s_waitcnt lgkmcnt(" #n ")" ::: "memory")
; #define PG8_BAR __builtin_amdgcn_s_barrier()
; #define PG8_SCHED __builtin_amdgcn_sched_barrier(0)
; template <class Epi>
; __device__ __forceinline__ void gemm_phase(LAS unsigned char* lds, const Gemm g, const StaticOrder& S, const Epi& E) {
;     ...
;             PG8_WAIT_V(8); PG8_WAIT_L(0); PG8_BAR; PG8_MMA(1, 0, At, B0); PG8_MMA(1, 1, At, B1); PG8_BAR; PG8_SCHED;
;             PG8_LDB(B0, 1, 0); PG8_LDB(B1, 1, 1); PG8_SCHED; PG8_LDA(At, 1, 0); PG8_STAGE(PG8_SA(0, 1), a2 + hstepA, voffA);
;             PG8_WAIT_V(8); PG8_WAIT_L(0); PG8_BAR; PG8_MMA(0, 0, At, B0); PG8_MMA(0, 1, At, B1); PG8_BAR; PG8_SCHED;
	s_waitcnt lgkmcnt(0)
	v_mfma_f32_16x16x32_bf16 v[60:63], v[146:149], v[190:193], 0
	v_mfma_f32_16x16x32_bf16 v[52:55], v[164:167], v[190:193], 0
	v_mfma_f32_16x16x32_bf16 v[44:47], v[146:149], v[202:205], 0
	v_mfma_f32_16x16x32_bf16 v[36:39], v[164:167], v[202:205], 0
	v_mfma_f32_16x16x32_bf16 v[28:31], v[146:149], v[210:213], 0
	v_mfma_f32_16x16x32_bf16 v[20:23], v[164:167], v[210:213], 0
	v_mfma_f32_16x16x32_bf16 v[12:15], v[146:149], v[218:221], 0
	v_mfma_f32_16x16x32_bf16 v[4:7], v[164:167], v[218:221], 0
	v_mfma_f32_16x16x32_bf16 v[60:63], v[160:163], v[198:201], v[60:63]
	v_mfma_f32_16x16x32_bf16 v[52:55], v[168:171], v[198:201], v[52:55]
	v_mfma_f32_16x16x32_bf16 v[44:47], v[160:163], v[206:209], v[44:47]
	v_mfma_f32_16x16x32_bf16 v[36:39], v[168:171], v[206:209], v[36:39]
	v_mfma_f32_16x16x32_bf16 v[28:31], v[160:163], v[214:217], v[28:31]
	v_mfma_f32_16x16x32_bf16 v[20:23], v[168:171], v[214:217], v[20:23]
	v_mfma_f32_16x16x32_bf16 v[12:15], v[160:163], v[222:225], v[12:15]
	v_mfma_f32_16x16x32_bf16 v[4:7], v[168:171], v[222:225], v[4:7]
	v_mfma_f32_16x16x32_bf16 v[56:59], v[172:175], v[190:193], 0
	v_mfma_f32_16x16x32_bf16 v[48:51], v[180:183], v[190:193], 0
	v_mfma_f32_16x16x32_bf16 v[40:43], v[172:175], v[202:205], 0
	v_mfma_f32_16x16x32_bf16 v[32:35], v[180:183], v[202:205], 0
	v_mfma_f32_16x16x32_bf16 v[24:27], v[172:175], v[210:213], 0
	v_mfma_f32_16x16x32_bf16 v[16:19], v[180:183], v[210:213], 0
	v_mfma_f32_16x16x32_bf16 v[8:11], v[172:175], v[218:221], 0
	v_mfma_f32_16x16x32_bf16 v[0:3], v[180:183], v[218:221], 0
	v_mfma_f32_16x16x32_bf16 v[56:59], v[176:179], v[198:201], v[56:59]
	v_mfma_f32_16x16x32_bf16 v[48:51], v[184:187], v[198:201], v[48:51]
	v_mfma_f32_16x16x32_bf16 v[40:43], v[176:179], v[206:209], v[40:43]
	v_mfma_f32_16x16x32_bf16 v[32:35], v[184:187], v[206:209], v[32:35]
	v_mfma_f32_16x16x32_bf16 v[24:27], v[176:179], v[214:217], v[24:27]
	v_mfma_f32_16x16x32_bf16 v[16:19], v[184:187], v[214:217], v[16:19]
	v_mfma_f32_16x16x32_bf16 v[8:11], v[176:179], v[222:225], v[8:11]
	v_mfma_f32_16x16x32_bf16 v[0:3], v[184:187], v[222:225], v[0:3]
	s_barrier
	s_add_i32 s49, 0, 0x18000
	v_add_u32_e32 v136, s49, v151
	s_add_i32 s50, 0, 0x1c000
	ds_read_b128 v[146:149], v136
	ds_read_b128 v[160:163], v136 offset:1024
	ds_read_b128 v[164:167], v136 offset:2048
	ds_read_b128 v[168:171], v136 offset:3072
	v_add_u32_e32 v136, s50, v151
	ds_read_b128 v[172:175], v136
	ds_read_b128 v[176:179], v136 offset:1024
	ds_read_b128 v[180:183], v136 offset:2048
	ds_read_b128 v[184:187], v136 offset:3072
	s_add_u32 s18, s18, 0x40000
	s_addc_u32 s19, s19, 0
	s_mov_b32 m0, s24
	v_lshl_add_u64 v[232:233], s[18:19], 0, v[134:135]
	ds_read_b128 v[190:193], v155 offset:32768
	ds_read_b128 v[198:201], v155 offset:33792
	ds_read_b128 v[202:205], v155 offset:34816
	ds_read_b128 v[206:209], v155 offset:35840
	ds_read_b128 v[210:213], v155 offset:36864
	ds_read_b128 v[214:217], v155 offset:37888
	ds_read_b128 v[218:221], v155 offset:38912
	ds_read_b128 v[222:225], v155 offset:39936
	global_load_lds_dwordx4 v[232:233], off
	v_lshl_add_u64 v[232:233], s[18:19], 0, v[130:131]
	s_mov_b32 m0, s25
	s_nop 0
	global_load_lds_dwordx4 v[232:233], off
	s_waitcnt vmcnt(8)
	s_waitcnt lgkmcnt(0)
	s_barrier
	s_waitcnt lgkmcnt(0)
	v_mfma_f32_16x16x32_bf16 v[124:127], v[146:149], v[190:193], v[124:127]
	v_mfma_f32_16x16x32_bf16 v[116:119], v[164:167], v[190:193], v[116:119]
	v_mfma_f32_16x16x32_bf16 v[108:111], v[146:149], v[202:205], v[108:111]
	v_mfma_f32_16x16x32_bf16 v[100:103], v[164:167], v[202:205], v[100:103]
	v_mfma_f32_16x16x32_bf16 v[92:95], v[146:149], v[210:213], v[92:95]
	v_mfma_f32_16x16x32_bf16 v[84:87], v[164:167], v[210:213], v[84:87]
	v_mfma_f32_16x16x32_bf16 v[76:79], v[146:149], v[218:221], v[76:79]
	v_mfma_f32_16x16x32_bf16 v[68:71], v[164:167], v[218:221], v[68:71]
	v_mfma_f32_16x16x32_bf16 v[124:127], v[160:163], v[198:201], v[124:127]
	v_mfma_f32_16x16x32_bf16 v[116:119], v[168:171], v[198:201], v[116:119]
	v_mfma_f32_16x16x32_bf16 v[108:111], v[160:163], v[206:209], v[108:111]
	v_mfma_f32_16x16x32_bf16 v[100:103], v[168:171], v[206:209], v[100:103]
	v_mfma_f32_16x16x32_bf16 v[92:95], v[160:163], v[214:217], v[92:95]
	v_mfma_f32_16x16x32_bf16 v[84:87], v[168:171], v[214:217], v[84:87]
	v_mfma_f32_16x16x32_bf16 v[76:79], v[160:163], v[222:225], v[76:79]
	v_mfma_f32_16x16x32_bf16 v[68:71], v[168:171], v[222:225], v[68:71]
	v_mfma_f32_16x16x32_bf16 v[120:123], v[172:175], v[190:193], v[120:123]
	v_mfma_f32_16x16x32_bf16 v[112:115], v[180:183], v[190:193], v[112:115]
	v_mfma_f32_16x16x32_bf16 v[104:107], v[172:175], v[202:205], v[104:107]
	v_mfma_f32_16x16x32_bf16 v[96:99], v[180:183], v[202:205], v[96:99]
	v_mfma_f32_16x16x32_bf16 v[88:91], v[172:175], v[210:213], v[88:91]
	v_mfma_f32_16x16x32_bf16 v[80:83], v[180:183], v[210:213], v[80:83]
	v_mfma_f32_16x16x32_bf16 v[72:75], v[172:175], v[218:221], v[72:75]
	v_mfma_f32_16x16x32_bf16 v[64:67], v[180:183], v[218:221], v[64:67]
	v_mfma_f32_16x16x32_bf16 v[120:123], v[176:179], v[198:201], v[120:123]
	v_mfma_f32_16x16x32_bf16 v[112:115], v[184:187], v[198:201], v[112:115]
	v_mfma_f32_16x16x32_bf16 v[104:107], v[176:179], v[206:209], v[104:107]
	v_mfma_f32_16x16x32_bf16 v[96:99], v[184:187], v[206:209], v[96:99]
	v_mfma_f32_16x16x32_bf16 v[88:91], v[176:179], v[214:217], v[88:91]
	v_mfma_f32_16x16x32_bf16 v[80:83], v[184:187], v[214:217], v[80:83]
	v_mfma_f32_16x16x32_bf16 v[72:75], v[176:179], v[222:225], v[72:75]
	v_mfma_f32_16x16x32_bf16 v[64:67], v[184:187], v[222:225], v[64:67]
	s_barrier
; #define PG8_STAGE(bufoff, gbase, voff) do { _Pragma("unroll") for (int _i = 0; _i < 2; ++_i) \
;         __builtin_amdgcn_global_load_lds((const unsigned*)((const char*)(gbase) + (voff)[_i]), (LAS unsigned*)(lds + (bufoff) + ldsw + _i * 8192), 16, 0, 0); } while (0)
; #define PG8_LDA(dst, b, h) do { _Pragma("unroll") for (int m = 0; m < 4; ++m) _Pragma("unroll") for (int k = 0; k < 2; ++k) dst[m][k] = *(const LAS bf16x8*)(lds + PG8_SA(b, h) + aoff + m * 2048 + k * 1024); } while (0)
; #define PG8_MMA(ai, bj, At, Bt) do { __builtin_amdgcn_s_setprio(1); _Pragma("unroll") for (int m = 0; m < 4; ++m) _Pragma("unroll") for (int n = 0; n < 2; ++n) _Pragma("unroll") for (int k = 0; k < 2; ++k) \
;         acc[ai][bj][m][n] = __builtin_amdgcn_mfma_f32_16x16x32_bf16(Bt[n][k], At[m][k], acc[ai][bj][m][n], 0, 0, 0); __builtin_amdgcn_s_setprio(0); } while (0)
; #define PG8_WAIT_V(n) asm volatile("s_waitcnt vmcnt(" #n ")" ::: "memory")
; #define PG8_WAIT_L(n) asm volatile("s_waitcnt lgkmcnt(" #n ")" ::: "memory")
; #define PG8_BAR __builtin_amdgcn_s_barrier()
; #define PG8_SCHED __builtin_amdgcn_sched_barrier(0)
; template <class Epi>
; __device__ __forceinline__ void gemm_phase(LAS unsigned char* lds, const Gemm g, const StaticOrder& S, const Epi& E) {
;     ...
;             PG8_LDA(At, 1, 1); PG8_STAGE(PG8_SB(1, 0), b3, voffB); PG8_STAGE(PG8_SB(1, 1), b3 + hstepB, voffB); PG8_STAGE(PG8_SA(1, 0), a3, voffA);
;             PG8_WAIT_V(8); PG8_WAIT_L(0); PG8_BAR; PG8_MMA(1, 0, At, B0); PG8_MMA(1, 1, At, B1); PG8_BAR; PG8_SCHED;
;         }
	s_add_i32 s18, s49, s20
	v_lshl_add_u64 v[194:195], v[194:195], 0, s[6:7]
	s_mov_b32 m0, s18
	ds_read_b128 v[190:193], v155 offset:49152
	ds_read_b128 v[198:201], v155 offset:50176
	ds_read_b128 v[202:205], v155 offset:51200
	ds_read_b128 v[206:209], v155 offset:52224
	ds_read_b128 v[210:213], v155 offset:53248
	ds_read_b128 v[214:217], v155 offset:54272
	ds_read_b128 v[218:221], v155 offset:55296
	ds_read_b128 v[222:225], v155 offset:56320
	global_load_lds_dwordx4 v[194:195], off
	s_add_i32 m0, s18, 0x2000
	s_add_u32 s2, s2, 0x40080
	v_lshl_add_u64 v[194:195], v[226:227], 0, s[6:7]
	s_addc_u32 s3, s3, 0
	s_add_i32 s18, s50, s20
	global_load_lds_dwordx4 v[194:195], off
	v_lshl_add_u64 v[194:195], s[2:3], 0, v[132:133]
	s_mov_b32 m0, s18
	s_nop 0
	global_load_lds_dwordx4 v[194:195], off
	v_lshl_add_u64 v[194:195], s[2:3], 0, v[128:129]
	s_add_i32 m0, s18, 0x2000
	s_nop 0
	global_load_lds_dwordx4 v[194:195], off
	v_lshl_add_u64 v[194:195], v[228:229], 0, s[6:7]
	s_mov_b32 m0, s30
	s_nop 0
	global_load_lds_dwordx4 v[194:195], off
	v_lshl_add_u64 v[194:195], v[230:231], 0, s[6:7]
	s_mov_b32 m0, s31
	s_nop 0
	global_load_lds_dwordx4 v[194:195], off
	s_waitcnt vmcnt(8)
	s_waitcnt lgkmcnt(0)
	s_barrier
	s_waitcnt lgkmcnt(0)
	v_mfma_f32_16x16x32_bf16 v[60:63], v[146:149], v[190:193], v[60:63]
	v_mfma_f32_16x16x32_bf16 v[52:55], v[164:167], v[190:193], v[52:55]
	v_mfma_f32_16x16x32_bf16 v[44:47], v[146:149], v[202:205], v[44:47]
	v_mfma_f32_16x16x32_bf16 v[36:39], v[164:167], v[202:205], v[36:39]
	v_mfma_f32_16x16x32_bf16 v[28:31], v[146:149], v[210:213], v[28:31]
	v_mfma_f32_16x16x32_bf16 v[20:23], v[164:167], v[210:213], v[20:23]
	v_mfma_f32_16x16x32_bf16 v[12:15], v[146:149], v[218:221], v[12:15]
	v_mfma_f32_16x16x32_bf16 v[4:7], v[164:167], v[218:221], v[4:7]
	v_mfma_f32_16x16x32_bf16 v[60:63], v[160:163], v[198:201], v[60:63]
	v_mfma_f32_16x16x32_bf16 v[52:55], v[168:171], v[198:201], v[52:55]
	v_mfma_f32_16x16x32_bf16 v[44:47], v[160:163], v[206:209], v[44:47]
	v_mfma_f32_16x16x32_bf16 v[36:39], v[168:171], v[206:209], v[36:39]
	v_mfma_f32_16x16x32_bf16 v[28:31], v[160:163], v[214:217], v[28:31]
	v_mfma_f32_16x16x32_bf16 v[20:23], v[168:171], v[214:217], v[20:23]
	v_mfma_f32_16x16x32_bf16 v[12:15], v[160:163], v[222:225], v[12:15]
	v_mfma_f32_16x16x32_bf16 v[4:7], v[168:171], v[222:225], v[4:7]
	v_mfma_f32_16x16x32_bf16 v[56:59], v[172:175], v[190:193], v[56:59]
	v_mfma_f32_16x16x32_bf16 v[48:51], v[180:183], v[190:193], v[48:51]
	v_mfma_f32_16x16x32_bf16 v[40:43], v[172:175], v[202:205], v[40:43]
	v_mfma_f32_16x16x32_bf16 v[32:35], v[180:183], v[202:205], v[32:35]
	v_mfma_f32_16x16x32_bf16 v[24:27], v[172:175], v[210:213], v[24:27]
	v_mfma_f32_16x16x32_bf16 v[16:19], v[180:183], v[210:213], v[16:19]
	v_mfma_f32_16x16x32_bf16 v[8:11], v[172:175], v[218:221], v[8:11]
	v_mfma_f32_16x16x32_bf16 v[0:3], v[180:183], v[218:221], v[0:3]
	v_mfma_f32_16x16x32_bf16 v[56:59], v[176:179], v[198:201], v[56:59]
	v_mfma_f32_16x16x32_bf16 v[48:51], v[184:187], v[198:201], v[48:51]
	v_mfma_f32_16x16x32_bf16 v[40:43], v[176:179], v[206:209], v[40:43]
	v_mfma_f32_16x16x32_bf16 v[32:35], v[184:187], v[206:209], v[32:35]
	v_mfma_f32_16x16x32_bf16 v[24:27], v[176:179], v[214:217], v[24:27]
	v_mfma_f32_16x16x32_bf16 v[16:19], v[184:187], v[214:217], v[16:19]
	v_mfma_f32_16x16x32_bf16 v[8:11], v[176:179], v[222:225], v[8:11]
	v_mfma_f32_16x16x32_bf16 v[0:3], v[184:187], v[222:225], v[0:3]
	s_barrier
	s_add_i32 s48, s48, 2
	s_add_u32 s16, s16, 0x100
	s_addc_u32 s17, s17, 0
	s_add_u32 s46, s46, 0x100
	s_addc_u32 s47, s47, 0
	s_cmp_gt_u32 s48, 13
	s_cbranch_scc0 .LBB0_929

; #define PG8_STAGE(bufoff, gbase, voff) do { _Pragma("unroll") for (int _i = 0; _i < 2; ++_i) \
;         __builtin_amdgcn_global_load_lds((const unsigned*)((const char*)(gbase) + (voff)[_i]), (LAS unsigned*)(lds + (bufoff) + ldsw + _i * 8192), 16, 0, 0); } while (0)
; #define PG8_LDA(dst, b, h) do { _Pragma("unroll") for (int m = 0; m < 4; ++m) _Pragma("unroll") for (int k = 0; k < 2; ++k) dst[m][k] = *(const LAS bf16x8*)(lds + PG8_SA(b, h) + aoff + m * 2048 + k * 1024); } while (0)
; #define PG8_LDB(dst, b, h) do { _Pragma("unroll") for (int n = 0; n < 2; ++n) _Pragma("unroll") for (int k = 0; k < 2; ++k) dst[n][k] = *(const LAS bf16x8*)(lds + PG8_SB(b, h) + boff + n * 2048 + k * 1024); } while (0)
; #define PG8_MMA(ai, bj, At, Bt) do { __builtin_amdgcn_s_setprio(1); _Pragma("unroll") for (int m = 0; m < 4; ++m) _Pragma("unroll") for (int n = 0; n < 2; ++n) _Pragma("unroll") for (int k = 0; k < 2; ++k) \
;         acc[ai][bj][m][n] = __builtin_amdgcn_mfma_f32_16x16x32_bf16(Bt[n][k], At[m][k], acc[ai][bj][m][n], 0, 0, 0); __builtin_amdgcn_s_setprio(0); } while (0)
; template <class Epi>
; __device__ __forceinline__ void gemm_phase(LAS unsigned char* lds, const Gemm g, const StaticOrder& S, const Epi& E) {
;     ...
;         for (int t = 0; t < nt; t += 2) {
;             const bool last = (t == nt - 2);
;             const char* a1 = cA + (size_t)(t + 1) * kstep;
;             const char* a2 = last ? nA : cA + (size_t)(t + 2) * kstep; const char* b2 = last ? nB : cB + (size_t)(t + 2) * kstep;
;             const char* a3 = a2 + kstep; const char* b3 = b2 + kstep;
;             PG8_LDB(B0, 0, 0); PG8_LDB(B1, 0, 1); PG8_SCHED; PG8_LDA(At, 0, 0); PG8_STAGE(PG8_SA(1, 1), a1 + hstepA, voffA);
;             PG8_WAIT_V(8); PG8_WAIT_L(0); PG8_BAR; PG8_MMA(0, 0, At, B0); PG8_MMA(0, 1, At, B1); PG8_BAR; PG8_SCHED;
;             PG8_LDA(At, 0, 1); PG8_STAGE(PG8_SB(0, 0), b2, voffB); PG8_STAGE(PG8_SB(0, 1), b2 + hstepB, voffB); PG8_STAGE(PG8_SA(0, 0), a2, voffA);
;             PG8_WAIT_V(8); PG8_WAIT_L(0); PG8_BAR; PG8_MMA(1, 0, At, B0); PG8_MMA(1, 1, At, B1); PG8_BAR; PG8_SCHED;
;     ...
; #pragma unroll
;         for (int a = 0; a < 2; ++a)
; #pragma unroll
;             for (int b = 0; b < 2; ++b)
; #pragma unroll
;                 for (int m = 0; m < 4; ++m)
; #pragma unroll
;                     for (int n = 0; n < 2; ++n) acc[a][b][m][n] = (f32x4){0.f, 0.f, 0.f, 0.f};
.LBB0_1033:
	s_add_u32 s42, s8, 0x100
	s_addc_u32 s43, s9, 0
	s_mov_b32 s44, -2
	s_waitcnt lgkmcnt(0)
	s_waitcnt vmcnt(0)
	ds_read_b128 v[128:131], v187
	ds_read_b128 v[132:135], v187 offset:1024
	ds_read_b128 v[136:139], v187 offset:2048
	ds_read_b128 v[140:143], v187 offset:3072
	ds_read_b128 v[144:147], v188
	ds_read_b128 v[148:151], v188 offset:1024
	ds_read_b128 v[166:169], v188 offset:2048
	ds_read_b128 v[170:173], v188 offset:3072
	s_add_u32 s8, s2, 0x100
	s_addc_u32 s9, s3, 0
	s_cmp_eq_u32 s44, 40
	s_cselect_b32 s23, s1, s9
	s_cselect_b32 s22, s0, s8
	s_cselect_b32 s21, s19, s43
	s_cselect_b32 s20, s18, s42
	v_lshl_add_u64 v[182:183], s[2:3], 0, v[160:161]
	s_add_i32 m0, s25, 0xc000
	ds_read_b128 v[174:177], v190
	ds_read_b128 v[178:181], v190 offset:1024
	ds_read_b128 v[192:195], v190 offset:2048
	ds_read_b128 v[198:201], v190 offset:3072
	ds_read_b128 v[202:205], v190 offset:4096
	ds_read_b128 v[206:209], v190 offset:5120
	ds_read_b128 v[210:213], v190 offset:6144
	ds_read_b128 v[214:217], v190 offset:7168
	global_load_lds_dwordx4 v[182:183], off
	v_lshl_add_u64 v[182:183], s[2:3], 0, v[162:163]
	s_add_i32 m0, s25, 0xe000
	s_nop 0
	global_load_lds_dwordx4 v[182:183], off
	s_waitcnt vmcnt(8)
	s_waitcnt lgkmcnt(0)
	s_barrier
	s_waitcnt lgkmcnt(0)
	v_mfma_f32_16x16x32_bf16 v[124:127], v[128:131], v[174:177], 0
	v_mfma_f32_16x16x32_bf16 v[120:123], v[136:139], v[174:177], 0
	v_mfma_f32_16x16x32_bf16 v[108:111], v[128:131], v[192:195], 0
	v_mfma_f32_16x16x32_bf16 v[104:107], v[136:139], v[192:195], 0
	v_mfma_f32_16x16x32_bf16 v[92:95], v[128:131], v[202:205], 0
	v_mfma_f32_16x16x32_bf16 v[88:91], v[136:139], v[202:205], 0
	v_mfma_f32_16x16x32_bf16 v[76:79], v[128:131], v[210:213], 0
	v_mfma_f32_16x16x32_bf16 v[72:75], v[136:139], v[210:213], 0
	v_mfma_f32_16x16x32_bf16 v[124:127], v[132:135], v[178:181], v[124:127]
	v_mfma_f32_16x16x32_bf16 v[120:123], v[140:143], v[178:181], v[120:123]
	v_mfma_f32_16x16x32_bf16 v[108:111], v[132:135], v[198:201], v[108:111]
	v_mfma_f32_16x16x32_bf16 v[104:107], v[140:143], v[198:201], v[104:107]
	v_mfma_f32_16x16x32_bf16 v[92:95], v[132:135], v[206:209], v[92:95]
	v_mfma_f32_16x16x32_bf16 v[88:91], v[140:143], v[206:209], v[88:91]
	v_mfma_f32_16x16x32_bf16 v[76:79], v[132:135], v[214:217], v[76:79]
	v_mfma_f32_16x16x32_bf16 v[72:75], v[140:143], v[214:217], v[72:75]
	v_mfma_f32_16x16x32_bf16 v[116:119], v[144:147], v[174:177], 0
	v_mfma_f32_16x16x32_bf16 v[112:115], v[166:169], v[174:177], 0
	v_mfma_f32_16x16x32_bf16 v[100:103], v[144:147], v[192:195], 0
	v_mfma_f32_16x16x32_bf16 v[96:99], v[166:169], v[192:195], 0
	v_mfma_f32_16x16x32_bf16 v[84:87], v[144:147], v[202:205], 0
	v_mfma_f32_16x16x32_bf16 v[80:83], v[166:169], v[202:205], 0
	v_mfma_f32_16x16x32_bf16 v[68:71], v[144:147], v[210:213], 0
	v_mfma_f32_16x16x32_bf16 v[64:67], v[166:169], v[210:213], 0
	v_mfma_f32_16x16x32_bf16 v[116:119], v[148:151], v[178:181], v[116:119]
	v_mfma_f32_16x16x32_bf16 v[112:115], v[170:173], v[178:181], v[112:115]
	v_mfma_f32_16x16x32_bf16 v[100:103], v[148:151], v[198:201], v[100:103]
	v_mfma_f32_16x16x32_bf16 v[96:99], v[170:173], v[198:201], v[96:99]
	v_mfma_f32_16x16x32_bf16 v[84:87], v[148:151], v[206:209], v[84:87]
	v_mfma_f32_16x16x32_bf16 v[80:83], v[170:173], v[206:209], v[80:83]
	v_mfma_f32_16x16x32_bf16 v[68:71], v[148:151], v[214:217], v[68:71]
	v_mfma_f32_16x16x32_bf16 v[64:67], v[170:173], v[214:217], v[64:67]
	s_barrier
	s_add_i32 s2, s36, s24
	v_lshl_add_u64 v[182:183], s[20:21], 0, v[154:155]
	s_mov_b32 m0, s2
	ds_read_b128 v[174:177], v190 offset:16384
	ds_read_b128 v[178:181], v190 offset:17408
	ds_read_b128 v[192:195], v190 offset:18432
	ds_read_b128 v[198:201], v190 offset:19456
	ds_read_b128 v[202:205], v190 offset:20480
	ds_read_b128 v[206:209], v190 offset:21504
	ds_read_b128 v[210:213], v190 offset:22528
	ds_read_b128 v[214:217], v190 offset:23552
	global_load_lds_dwordx4 v[182:183], off
	s_add_i32 m0, s2, 0x2000
	s_add_u32 s2, s20, 0xb0000
	v_lshl_add_u64 v[218:219], s[20:21], 0, v[158:159]
	s_addc_u32 s3, s21, 0
	s_add_i32 s45, s37, s24
	global_load_lds_dwordx4 v[218:219], off
	v_lshl_add_u64 v[220:221], s[2:3], 0, v[154:155]
	s_mov_b32 m0, s45
	v_lshl_add_u64 v[222:223], s[22:23], 0, v[156:157]
	global_load_lds_dwordx4 v[220:221], off
	v_lshl_add_u64 v[220:221], s[2:3], 0, v[158:159]
	s_add_i32 m0, s45, 0x2000
	s_nop 0
	global_load_lds_dwordx4 v[220:221], off
	v_lshl_add_u64 v[220:221], s[22:23], 0, v[152:153]
	s_mov_b32 m0, s25
	s_nop 0
	global_load_lds_dwordx4 v[220:221], off
	s_mov_b32 m0, s26
	s_nop 0
	global_load_lds_dwordx4 v[222:223], off
	s_waitcnt vmcnt(8)
	s_waitcnt lgkmcnt(0)
	s_barrier
; #define PG8_STAGE(bufoff, gbase, voff) do { _Pragma("unroll") for (int _i = 0; _i < 2; ++_i) \
;         __builtin_amdgcn_global_load_lds((const unsigned*)((const char*)(gbase) + (voff)[_i]), (LAS unsigned*)(lds + (bufoff) + ldsw + _i * 8192), 16, 0, 0); } while (0)
; #define PG8_LDA(dst, b, h) do { _Pragma("unroll") for (int m = 0; m < 4; ++m) _Pragma("unroll") for (int k = 0; k < 2; ++k) dst[m][k] = *(const LAS bf16x8*)(lds + PG8_SA(b, h) + aoff + m * 2048 + k * 1024); } while (0)
; #define PG8_LDB(dst, b, h) do { _Pragma("unroll") for (int n = 0; n < 2; ++n) _Pragma("unroll") for (int k = 0; k < 2; ++k) dst[n][k] = *(const LAS bf16x8*)(lds + PG8_SB(b, h) + boff + n * 2048 + k * 1024); } while (0)
; #define PG8_MMA(ai, bj, At, Bt) do { __builtin_amdgcn_s_setprio(1); _Pragma("unroll") for (int m = 0; m < 4; ++m) _Pragma("unroll") for (int n = 0; n < 2; ++n) _Pragma("unroll") for (int k = 0; k < 2; ++k) \
;         acc[ai][bj][m][n] = __builtin_amdgcn_mfma_f32_16x16x32_bf16(Bt[n][k], At[m][k], acc[ai][bj][m][n], 0, 0, 0); __builtin_amdgcn_s_setprio(0); } while (0)
; #define PG8_WAIT_V(n) asm volatile("s_waitcnt vmcnt(" #n ")" ::: "memory")
; #define PG8_WAIT_L(n) asm volatile("s_waitcnt lgkmcnt(" #n ")" ::: "memory")
; #define PG8_BAR __builtin_amdgcn_s_barrier()
; #define PG8_SCHED __builtin_amdgcn_sched_barrier(0)
; template <class Epi>
; __device__ __forceinline__ void gemm_phase(LAS unsigned char* lds, const Gemm g, const StaticOrder& S, const Epi& E) {
;     ...
;             PG8_WAIT_V(8); PG8_WAIT_L(0); PG8_BAR; PG8_MMA(1, 0, At, B0); PG8_MMA(1, 1, At, B1); PG8_BAR; PG8_SCHED;
;             PG8_LDB(B0, 1, 0); PG8_LDB(B1, 1, 1); PG8_SCHED; PG8_LDA(At, 1, 0); PG8_STAGE(PG8_SA(0, 1), a2 + hstepA, voffA);
;             PG8_WAIT_V(8); PG8_WAIT_L(0); PG8_BAR; PG8_MMA(0, 0, At, B0); PG8_MMA(0, 1, At, B1); PG8_BAR; PG8_SCHED;
	s_waitcnt lgkmcnt(0)
	v_mfma_f32_16x16x32_bf16 v[60:63], v[128:131], v[174:177], 0
	v_mfma_f32_16x16x32_bf16 v[56:59], v[136:139], v[174:177], 0
	v_mfma_f32_16x16x32_bf16 v[44:47], v[128:131], v[192:195], 0
	v_mfma_f32_16x16x32_bf16 v[40:43], v[136:139], v[192:195], 0
	v_mfma_f32_16x16x32_bf16 v[28:31], v[128:131], v[202:205], 0
	v_mfma_f32_16x16x32_bf16 v[24:27], v[136:139], v[202:205], 0
	v_mfma_f32_16x16x32_bf16 v[12:15], v[128:131], v[210:213], 0
	v_mfma_f32_16x16x32_bf16 v[8:11], v[136:139], v[210:213], 0
	v_mfma_f32_16x16x32_bf16 v[60:63], v[132:135], v[178:181], v[60:63]
	v_mfma_f32_16x16x32_bf16 v[56:59], v[140:143], v[178:181], v[56:59]
	v_mfma_f32_16x16x32_bf16 v[44:47], v[132:135], v[198:201], v[44:47]
	v_mfma_f32_16x16x32_bf16 v[40:43], v[140:143], v[198:201], v[40:43]
	v_mfma_f32_16x16x32_bf16 v[28:31], v[132:135], v[206:209], v[28:31]
	v_mfma_f32_16x16x32_bf16 v[24:27], v[140:143], v[206:209], v[24:27]
	v_mfma_f32_16x16x32_bf16 v[12:15], v[132:135], v[214:217], v[12:15]
	v_mfma_f32_16x16x32_bf16 v[8:11], v[140:143], v[214:217], v[8:11]
	v_mfma_f32_16x16x32_bf16 v[52:55], v[144:147], v[174:177], 0
	v_mfma_f32_16x16x32_bf16 v[48:51], v[166:169], v[174:177], 0
	v_mfma_f32_16x16x32_bf16 v[36:39], v[144:147], v[192:195], 0
	v_mfma_f32_16x16x32_bf16 v[32:35], v[166:169], v[192:195], 0
	v_mfma_f32_16x16x32_bf16 v[20:23], v[144:147], v[202:205], 0
	v_mfma_f32_16x16x32_bf16 v[16:19], v[166:169], v[202:205], 0
	v_mfma_f32_16x16x32_bf16 v[4:7], v[144:147], v[210:213], 0
	v_mfma_f32_16x16x32_bf16 v[0:3], v[166:169], v[210:213], 0
	v_mfma_f32_16x16x32_bf16 v[52:55], v[148:151], v[178:181], v[52:55]
	v_mfma_f32_16x16x32_bf16 v[48:51], v[170:173], v[178:181], v[48:51]
	v_mfma_f32_16x16x32_bf16 v[36:39], v[148:151], v[198:201], v[36:39]
	v_mfma_f32_16x16x32_bf16 v[32:35], v[170:173], v[198:201], v[32:35]
	v_mfma_f32_16x16x32_bf16 v[20:23], v[148:151], v[206:209], v[20:23]
	v_mfma_f32_16x16x32_bf16 v[16:19], v[170:173], v[206:209], v[16:19]
	v_mfma_f32_16x16x32_bf16 v[4:7], v[148:151], v[214:217], v[4:7]
	v_mfma_f32_16x16x32_bf16 v[0:3], v[170:173], v[214:217], v[0:3]
	s_barrier
	s_add_i32 s45, 0, 0x18000
	s_add_i32 s46, 0, 0x1c000
	v_add_u32_e32 v140, s45, v185
	v_add_u32_e32 v170, s46, v185
	ds_read_b128 v[128:131], v140
	ds_read_b128 v[132:135], v140 offset:1024
	ds_read_b128 v[136:139], v140 offset:2048
	ds_read_b128 v[140:143], v140 offset:3072
	ds_read_b128 v[144:147], v170
	ds_read_b128 v[148:151], v170 offset:1024
	ds_read_b128 v[166:169], v170 offset:2048
	ds_read_b128 v[170:173], v170 offset:3072
	s_add_u32 s2, s22, 0xb4000
	s_addc_u32 s3, s23, 0
	s_mov_b32 m0, s27
	v_lshl_add_u64 v[224:225], s[2:3], 0, v[152:153]
	ds_read_b128 v[174:177], v190 offset:32768
	ds_read_b128 v[178:181], v190 offset:33792
	ds_read_b128 v[192:195], v190 offset:34816
	ds_read_b128 v[198:201], v190 offset:35840
	ds_read_b128 v[202:205], v190 offset:36864
	ds_read_b128 v[206:209], v190 offset:37888
	ds_read_b128 v[210:213], v190 offset:38912
	ds_read_b128 v[214:217], v190 offset:39936
	global_load_lds_dwordx4 v[224:225], off
	v_lshl_add_u64 v[224:225], s[2:3], 0, v[156:157]
	s_mov_b32 m0, s28
	s_nop 0
	global_load_lds_dwordx4 v[224:225], off
	s_waitcnt vmcnt(8)
	s_waitcnt lgkmcnt(0)
	s_barrier
	s_waitcnt lgkmcnt(0)
	v_mfma_f32_16x16x32_bf16 v[124:127], v[128:131], v[174:177], v[124:127]
	v_mfma_f32_16x16x32_bf16 v[120:123], v[136:139], v[174:177], v[120:123]
	v_mfma_f32_16x16x32_bf16 v[108:111], v[128:131], v[192:195], v[108:111]
	v_mfma_f32_16x16x32_bf16 v[104:107], v[136:139], v[192:195], v[104:107]
	v_mfma_f32_16x16x32_bf16 v[92:95], v[128:131], v[202:205], v[92:95]
	v_mfma_f32_16x16x32_bf16 v[88:91], v[136:139], v[202:205], v[88:91]
	v_mfma_f32_16x16x32_bf16 v[76:79], v[128:131], v[210:213], v[76:79]
	v_mfma_f32_16x16x32_bf16 v[72:75], v[136:139], v[210:213], v[72:75]
	v_mfma_f32_16x16x32_bf16 v[124:127], v[132:135], v[178:181], v[124:127]
	v_mfma_f32_16x16x32_bf16 v[120:123], v[140:143], v[178:181], v[120:123]
	v_mfma_f32_16x16x32_bf16 v[108:111], v[132:135], v[198:201], v[108:111]
	v_mfma_f32_16x16x32_bf16 v[104:107], v[140:143], v[198:201], v[104:107]
	v_mfma_f32_16x16x32_bf16 v[92:95], v[132:135], v[206:209], v[92:95]
	v_mfma_f32_16x16x32_bf16 v[88:91], v[140:143], v[206:209], v[88:91]
	v_mfma_f32_16x16x32_bf16 v[76:79], v[132:135], v[214:217], v[76:79]
	v_mfma_f32_16x16x32_bf16 v[72:75], v[140:143], v[214:217], v[72:75]
	v_mfma_f32_16x16x32_bf16 v[116:119], v[144:147], v[174:177], v[116:119]
	v_mfma_f32_16x16x32_bf16 v[112:115], v[166:169], v[174:177], v[112:115]
	v_mfma_f32_16x16x32_bf16 v[100:103], v[144:147], v[192:195], v[100:103]
	v_mfma_f32_16x16x32_bf16 v[96:99], v[166:169], v[192:195], v[96:99]
	v_mfma_f32_16x16x32_bf16 v[84:87], v[144:147], v[202:205], v[84:87]
	v_mfma_f32_16x16x32_bf16 v[80:83], v[166:169], v[202:205], v[80:83]
	v_mfma_f32_16x16x32_bf16 v[68:71], v[144:147], v[210:213], v[68:71]
	v_mfma_f32_16x16x32_bf16 v[64:67], v[166:169], v[210:213], v[64:67]
	v_mfma_f32_16x16x32_bf16 v[116:119], v[148:151], v[178:181], v[116:119]
	v_mfma_f32_16x16x32_bf16 v[112:115], v[170:173], v[178:181], v[112:115]
	v_mfma_f32_16x16x32_bf16 v[100:103], v[148:151], v[198:201], v[100:103]
	v_mfma_f32_16x16x32_bf16 v[96:99], v[170:173], v[198:201], v[96:99]
	v_mfma_f32_16x16x32_bf16 v[84:87], v[148:151], v[206:209], v[84:87]
	v_mfma_f32_16x16x32_bf16 v[80:83], v[170:173], v[206:209], v[80:83]
	v_mfma_f32_16x16x32_bf16 v[68:71], v[148:151], v[214:217], v[68:71]
	v_mfma_f32_16x16x32_bf16 v[64:67], v[170:173], v[214:217], v[64:67]
	s_barrier
; #define PG8_STAGE(bufoff, gbase, voff) do { _Pragma("unroll") for (int _i = 0; _i < 2; ++_i) \
;         __builtin_amdgcn_global_load_lds((const unsigned*)((const char*)(gbase) + (voff)[_i]), (LAS unsigned*)(lds + (bufoff) + ldsw + _i * 8192), 16, 0, 0); } while (0)
; #define PG8_LDA(dst, b, h) do { _Pragma("unroll") for (int m = 0; m < 4; ++m) _Pragma("unroll") for (int k = 0; k < 2; ++k) dst[m][k] = *(const LAS bf16x8*)(lds + PG8_SA(b, h) + aoff + m * 2048 + k * 1024); } while (0)
; #define PG8_MMA(ai, bj, At, Bt) do { __builtin_amdgcn_s_setprio(1); _Pragma("unroll") for (int m = 0; m < 4; ++m) _Pragma("unroll") for (int n = 0; n < 2; ++n) _Pragma("unroll") for (int k = 0; k < 2; ++k) \
;         acc[ai][bj][m][n] = __builtin_amdgcn_mfma_f32_16x16x32_bf16(Bt[n][k], At[m][k], acc[ai][bj][m][n], 0, 0, 0); __builtin_amdgcn_s_setprio(0); } while (0)
; #define PG8_WAIT_V(n) asm volatile("s_waitcnt vmcnt(" #n ")" ::: "memory")
; #define PG8_WAIT_L(n) asm volatile("s_waitcnt lgkmcnt(" #n ")" ::: "memory")
; #define PG8_BAR __builtin_amdgcn_s_barrier()
; #define PG8_SCHED __builtin_amdgcn_sched_barrier(0)
; template <class Epi>
; __device__ __forceinline__ void gemm_phase(LAS unsigned char* lds, const Gemm g, const StaticOrder& S, const Epi& E) {
;     ...
;             PG8_LDA(At, 1, 1); PG8_STAGE(PG8_SB(1, 0), b3, voffB); PG8_STAGE(PG8_SB(1, 1), b3 + hstepB, voffB); PG8_STAGE(PG8_SA(1, 0), a3, voffA);
;             PG8_WAIT_V(8); PG8_WAIT_L(0); PG8_BAR; PG8_MMA(1, 0, At, B0); PG8_MMA(1, 1, At, B1); PG8_BAR; PG8_SCHED;
;         }
	s_add_i32 s2, s45, s24
	v_lshl_add_u64 v[182:183], v[182:183], 0, s[14:15]
	s_mov_b32 m0, s2
	ds_read_b128 v[174:177], v190 offset:49152
	ds_read_b128 v[178:181], v190 offset:50176
	ds_read_b128 v[192:195], v190 offset:51200
	ds_read_b128 v[198:201], v190 offset:52224
	ds_read_b128 v[202:205], v190 offset:53248
	ds_read_b128 v[206:209], v190 offset:54272
	ds_read_b128 v[210:213], v190 offset:55296
	ds_read_b128 v[214:217], v190 offset:56320
	global_load_lds_dwordx4 v[182:183], off
	s_add_i32 m0, s2, 0x2000
	s_add_u32 s2, s20, 0xb0080
	v_lshl_add_u64 v[182:183], v[218:219], 0, s[14:15]
	s_addc_u32 s3, s21, 0
	s_add_i32 s20, s46, s24
	global_load_lds_dwordx4 v[182:183], off
	v_lshl_add_u64 v[182:183], s[2:3], 0, v[154:155]
	s_mov_b32 m0, s20
	s_nop 0
	global_load_lds_dwordx4 v[182:183], off
	v_lshl_add_u64 v[182:183], s[2:3], 0, v[158:159]
	s_add_i32 m0, s20, 0x2000
	s_nop 0
	global_load_lds_dwordx4 v[182:183], off
	v_lshl_add_u64 v[182:183], v[220:221], 0, s[14:15]
	s_mov_b32 m0, s30
	s_nop 0
	global_load_lds_dwordx4 v[182:183], off
	v_lshl_add_u64 v[182:183], v[222:223], 0, s[14:15]
	s_mov_b32 m0, s31
	s_nop 0
	global_load_lds_dwordx4 v[182:183], off
	s_waitcnt vmcnt(8)
	s_waitcnt lgkmcnt(0)
	s_barrier
	s_waitcnt lgkmcnt(0)
	v_mfma_f32_16x16x32_bf16 v[60:63], v[128:131], v[174:177], v[60:63]
	v_mfma_f32_16x16x32_bf16 v[56:59], v[136:139], v[174:177], v[56:59]
	v_mfma_f32_16x16x32_bf16 v[44:47], v[128:131], v[192:195], v[44:47]
	v_mfma_f32_16x16x32_bf16 v[40:43], v[136:139], v[192:195], v[40:43]
	v_mfma_f32_16x16x32_bf16 v[28:31], v[128:131], v[202:205], v[28:31]
	v_mfma_f32_16x16x32_bf16 v[24:27], v[136:139], v[202:205], v[24:27]
	v_mfma_f32_16x16x32_bf16 v[12:15], v[128:131], v[210:213], v[12:15]
	v_mfma_f32_16x16x32_bf16 v[8:11], v[136:139], v[210:213], v[8:11]
	v_mfma_f32_16x16x32_bf16 v[60:63], v[132:135], v[178:181], v[60:63]
	v_mfma_f32_16x16x32_bf16 v[56:59], v[140:143], v[178:181], v[56:59]
	v_mfma_f32_16x16x32_bf16 v[44:47], v[132:135], v[198:201], v[44:47]
	v_mfma_f32_16x16x32_bf16 v[40:43], v[140:143], v[198:201], v[40:43]
	v_mfma_f32_16x16x32_bf16 v[28:31], v[132:135], v[206:209], v[28:31]
	v_mfma_f32_16x16x32_bf16 v[24:27], v[140:143], v[206:209], v[24:27]
	v_mfma_f32_16x16x32_bf16 v[12:15], v[132:135], v[214:217], v[12:15]
	v_mfma_f32_16x16x32_bf16 v[8:11], v[140:143], v[214:217], v[8:11]
	v_mfma_f32_16x16x32_bf16 v[52:55], v[144:147], v[174:177], v[52:55]
	v_mfma_f32_16x16x32_bf16 v[48:51], v[166:169], v[174:177], v[48:51]
	v_mfma_f32_16x16x32_bf16 v[36:39], v[144:147], v[192:195], v[36:39]
	v_mfma_f32_16x16x32_bf16 v[32:35], v[166:169], v[192:195], v[32:35]
	v_mfma_f32_16x16x32_bf16 v[20:23], v[144:147], v[202:205], v[20:23]
	v_mfma_f32_16x16x32_bf16 v[16:19], v[166:169], v[202:205], v[16:19]
	v_mfma_f32_16x16x32_bf16 v[4:7], v[144:147], v[210:213], v[4:7]
	v_mfma_f32_16x16x32_bf16 v[0:3], v[166:169], v[210:213], v[0:3]
	v_mfma_f32_16x16x32_bf16 v[52:55], v[148:151], v[178:181], v[52:55]
	v_mfma_f32_16x16x32_bf16 v[48:51], v[170:173], v[178:181], v[48:51]
	v_mfma_f32_16x16x32_bf16 v[36:39], v[148:151], v[198:201], v[36:39]
	v_mfma_f32_16x16x32_bf16 v[32:35], v[170:173], v[198:201], v[32:35]
	v_mfma_f32_16x16x32_bf16 v[20:23], v[148:151], v[206:209], v[20:23]
	v_mfma_f32_16x16x32_bf16 v[16:19], v[170:173], v[206:209], v[16:19]
	v_mfma_f32_16x16x32_bf16 v[4:7], v[148:151], v[214:217], v[4:7]
	v_mfma_f32_16x16x32_bf16 v[0:3], v[170:173], v[214:217], v[0:3]
	s_barrier
	s_add_i32 s44, s44, 2
	s_add_u32 s42, s42, 0x100
	s_addc_u32 s43, s43, 0
	s_cmp_gt_u32 s44, 41
	s_mov_b64 s[2:3], s[8:9]
	s_cbranch_scc0 .LBB0_1034

; #define PG8_STAGE(bufoff, gbase, voff) do { _Pragma("unroll") for (int _i = 0; _i < 2; ++_i) \
;         __builtin_amdgcn_global_load_lds((const unsigned*)((const char*)(gbase) + (voff)[_i]), (LAS unsigned*)(lds + (bufoff) + ldsw + _i * 8192), 16, 0, 0); } while (0)
; #define PG8_LDA(dst, b, h) do { _Pragma("unroll") for (int m = 0; m < 4; ++m) _Pragma("unroll") for (int k = 0; k < 2; ++k) dst[m][k] = *(const LAS bf16x8*)(lds + PG8_SA(b, h) + aoff + m * 2048 + k * 1024); } while (0)
; #define PG8_LDB(dst, b, h) do { _Pragma("unroll") for (int n = 0; n < 2; ++n) _Pragma("unroll") for (int k = 0; k < 2; ++k) dst[n][k] = *(const LAS bf16x8*)(lds + PG8_SB(b, h) + boff + n * 2048 + k * 1024); } while (0)
; #define PG8_MMA(ai, bj, At, Bt) do { __builtin_amdgcn_s_setprio(1); _Pragma("unroll") for (int m = 0; m < 4; ++m) _Pragma("unroll") for (int n = 0; n < 2; ++n) _Pragma("unroll") for (int k = 0; k < 2; ++k) \
;         acc[ai][bj][m][n] = __builtin_amdgcn_mfma_f32_16x16x32_bf16(Bt[n][k], At[m][k], acc[ai][bj][m][n], 0, 0, 0); __builtin_amdgcn_s_setprio(0); } while (0)
; template <class Epi>
; __device__ __forceinline__ void gemm_phase(LAS unsigned char* lds, const Gemm g, const StaticOrder& S, const Epi& E) {
;     ...
;         for (int t = 0; t < nt; t += 2) {
;             const bool last = (t == nt - 2);
;             const char* a1 = cA + (size_t)(t + 1) * kstep;
;             const char* a2 = last ? nA : cA + (size_t)(t + 2) * kstep; const char* b2 = last ? nB : cB + (size_t)(t + 2) * kstep;
;             const char* a3 = a2 + kstep; const char* b3 = b2 + kstep;
;             PG8_LDB(B0, 0, 0); PG8_LDB(B1, 0, 1); PG8_SCHED; PG8_LDA(At, 0, 0); PG8_STAGE(PG8_SA(1, 1), a1 + hstepA, voffA);
;             PG8_WAIT_V(8); PG8_WAIT_L(0); PG8_BAR; PG8_MMA(0, 0, At, B0); PG8_MMA(0, 1, At, B1); PG8_BAR; PG8_SCHED;
;             PG8_LDA(At, 0, 1); PG8_STAGE(PG8_SB(0, 0), b2, voffB); PG8_STAGE(PG8_SB(0, 1), b2 + hstepB, voffB); PG8_STAGE(PG8_SA(0, 0), a2, voffA);
;             PG8_WAIT_V(8); PG8_WAIT_L(0); PG8_BAR; PG8_MMA(1, 0, At, B0); PG8_MMA(1, 1, At, B1); PG8_BAR; PG8_SCHED;
;     ...
; #pragma unroll
;         for (int a = 0; a < 2; ++a)
; #pragma unroll
;             for (int b = 0; b < 2; ++b)
; #pragma unroll
;                 for (int m = 0; m < 4; ++m)
; #pragma unroll
;                     for (int n = 0; n < 2; ++n) acc[a][b][m][n] = (f32x4){0.f, 0.f, 0.f, 0.f};
.LBB0_1176:
	s_add_u32 s44, s20, 0x100
	s_addc_u32 s45, s21, 0
	s_mov_b32 s46, -2
	ds_read_b128 v[128:131], v200
	ds_read_b128 v[132:135], v200 offset:1024
	ds_read_b128 v[136:139], v200 offset:2048
	ds_read_b128 v[140:143], v200 offset:3072
	ds_read_b128 v[144:147], v201
	ds_read_b128 v[148:151], v201 offset:1024
	ds_read_b128 v[168:171], v201 offset:2048
	ds_read_b128 v[172:175], v201 offset:3072
	s_add_u32 s20, s2, 0x100
	s_addc_u32 s21, s3, 0
	s_cmp_eq_u32 s46, 40
	s_cselect_b32 s25, s7, s21
	s_cselect_b32 s24, s6, s20
	s_cselect_b32 s23, s19, s45
	s_cselect_b32 s22, s18, s44
	v_lshl_add_u64 v[218:219], s[2:3], 0, v[162:163]
	s_add_i32 m0, s27, 0xc000
	ds_read_b128 v[176:179], v202
	ds_read_b128 v[180:183], v202 offset:1024
	ds_read_b128 v[184:187], v202 offset:2048
	ds_read_b128 v[188:191], v202 offset:3072
	ds_read_b128 v[192:195], v202 offset:4096
	ds_read_b128 v[206:209], v202 offset:5120
	ds_read_b128 v[210:213], v202 offset:6144
	ds_read_b128 v[214:217], v202 offset:7168
	global_load_lds_dwordx4 v[218:219], off
	v_lshl_add_u64 v[218:219], s[2:3], 0, v[164:165]
	s_add_i32 m0, s27, 0xe000
	s_nop 0
	global_load_lds_dwordx4 v[218:219], off
	s_waitcnt vmcnt(8)
	s_waitcnt lgkmcnt(0)
	s_barrier
	s_waitcnt lgkmcnt(0)
	v_mfma_f32_16x16x32_bf16 v[124:127], v[128:131], v[176:179], 0
	v_mfma_f32_16x16x32_bf16 v[120:123], v[136:139], v[176:179], 0
	v_mfma_f32_16x16x32_bf16 v[108:111], v[128:131], v[184:187], 0
	v_mfma_f32_16x16x32_bf16 v[104:107], v[136:139], v[184:187], 0
	v_mfma_f32_16x16x32_bf16 v[92:95], v[128:131], v[192:195], 0
	v_mfma_f32_16x16x32_bf16 v[88:91], v[136:139], v[192:195], 0
	v_mfma_f32_16x16x32_bf16 v[76:79], v[128:131], v[210:213], 0
	v_mfma_f32_16x16x32_bf16 v[72:75], v[136:139], v[210:213], 0
	v_mfma_f32_16x16x32_bf16 v[124:127], v[132:135], v[180:183], v[124:127]
	v_mfma_f32_16x16x32_bf16 v[120:123], v[140:143], v[180:183], v[120:123]
	v_mfma_f32_16x16x32_bf16 v[108:111], v[132:135], v[188:191], v[108:111]
	v_mfma_f32_16x16x32_bf16 v[104:107], v[140:143], v[188:191], v[104:107]
	v_mfma_f32_16x16x32_bf16 v[92:95], v[132:135], v[206:209], v[92:95]
	v_mfma_f32_16x16x32_bf16 v[88:91], v[140:143], v[206:209], v[88:91]
	v_mfma_f32_16x16x32_bf16 v[76:79], v[132:135], v[214:217], v[76:79]
	v_mfma_f32_16x16x32_bf16 v[72:75], v[140:143], v[214:217], v[72:75]
	v_mfma_f32_16x16x32_bf16 v[116:119], v[144:147], v[176:179], 0
	v_mfma_f32_16x16x32_bf16 v[112:115], v[168:171], v[176:179], 0
	v_mfma_f32_16x16x32_bf16 v[100:103], v[144:147], v[184:187], 0
	v_mfma_f32_16x16x32_bf16 v[96:99], v[168:171], v[184:187], 0
	v_mfma_f32_16x16x32_bf16 v[84:87], v[144:147], v[192:195], 0
	v_mfma_f32_16x16x32_bf16 v[80:83], v[168:171], v[192:195], 0
	v_mfma_f32_16x16x32_bf16 v[68:71], v[144:147], v[210:213], 0
	v_mfma_f32_16x16x32_bf16 v[64:67], v[168:171], v[210:213], 0
	v_mfma_f32_16x16x32_bf16 v[116:119], v[148:151], v[180:183], v[116:119]
	v_mfma_f32_16x16x32_bf16 v[112:115], v[172:175], v[180:183], v[112:115]
	v_mfma_f32_16x16x32_bf16 v[100:103], v[148:151], v[188:191], v[100:103]
	v_mfma_f32_16x16x32_bf16 v[96:99], v[172:175], v[188:191], v[96:99]
	v_mfma_f32_16x16x32_bf16 v[84:87], v[148:151], v[206:209], v[84:87]
	v_mfma_f32_16x16x32_bf16 v[80:83], v[172:175], v[206:209], v[80:83]
	v_mfma_f32_16x16x32_bf16 v[68:71], v[148:151], v[214:217], v[68:71]
	v_mfma_f32_16x16x32_bf16 v[64:67], v[172:175], v[214:217], v[64:67]
	s_barrier
	s_add_i32 s2, s38, s26
	v_lshl_add_u64 v[218:219], s[22:23], 0, v[154:155]
	s_mov_b32 m0, s2
	ds_read_b128 v[176:179], v202 offset:16384
	ds_read_b128 v[180:183], v202 offset:17408
	ds_read_b128 v[184:187], v202 offset:18432
	ds_read_b128 v[188:191], v202 offset:19456
	ds_read_b128 v[192:195], v202 offset:20480
	ds_read_b128 v[206:209], v202 offset:21504
	ds_read_b128 v[210:213], v202 offset:22528
	ds_read_b128 v[214:217], v202 offset:23552
	global_load_lds_dwordx4 v[218:219], off
	s_add_i32 m0, s2, 0x2000
	s_add_u32 s2, s22, 0xb0000
	v_lshl_add_u64 v[220:221], s[22:23], 0, v[158:159]
	s_addc_u32 s3, s23, 0
	s_add_i32 s47, s39, s26
	global_load_lds_dwordx4 v[220:221], off
	v_lshl_add_u64 v[222:223], s[2:3], 0, v[154:155]
	s_mov_b32 m0, s47
	v_lshl_add_u64 v[224:225], s[24:25], 0, v[156:157]
	global_load_lds_dwordx4 v[222:223], off
	v_lshl_add_u64 v[222:223], s[2:3], 0, v[158:159]
	s_add_i32 m0, s47, 0x2000
	s_nop 0
	global_load_lds_dwordx4 v[222:223], off
	v_lshl_add_u64 v[222:223], s[24:25], 0, v[152:153]
	s_mov_b32 m0, s27
	s_nop 0
	global_load_lds_dwordx4 v[222:223], off
	s_mov_b32 m0, s28
	s_nop 0
	global_load_lds_dwordx4 v[224:225], off
	s_waitcnt vmcnt(8)
	s_waitcnt lgkmcnt(0)
	s_barrier
; #define PG8_STAGE(bufoff, gbase, voff) do { _Pragma("unroll") for (int _i = 0; _i < 2; ++_i) \
;         __builtin_amdgcn_global_load_lds((const unsigned*)((const char*)(gbase) + (voff)[_i]), (LAS unsigned*)(lds + (bufoff) + ldsw + _i * 8192), 16, 0, 0); } while (0)
; #define PG8_LDA(dst, b, h) do { _Pragma("unroll") for (int m = 0; m < 4; ++m) _Pragma("unroll") for (int k = 0; k < 2; ++k) dst[m][k] = *(const LAS bf16x8*)(lds + PG8_SA(b, h) + aoff + m * 2048 + k * 1024); } while (0)
; #define PG8_LDB(dst, b, h) do { _Pragma("unroll") for (int n = 0; n < 2; ++n) _Pragma("unroll") for (int k = 0; k < 2; ++k) dst[n][k] = *(const LAS bf16x8*)(lds + PG8_SB(b, h) + boff + n * 2048 + k * 1024); } while (0)
; #define PG8_MMA(ai, bj, At, Bt) do { __builtin_amdgcn_s_setprio(1); _Pragma("unroll") for (int m = 0; m < 4; ++m) _Pragma("unroll") for (int n = 0; n < 2; ++n) _Pragma("unroll") for (int k = 0; k < 2; ++k) \
;         acc[ai][bj][m][n] = __builtin_amdgcn_mfma_f32_16x16x32_bf16(Bt[n][k], At[m][k], acc[ai][bj][m][n], 0, 0, 0); __builtin_amdgcn_s_setprio(0); } while (0)
; #define PG8_WAIT_V(n) asm volatile("s_waitcnt vmcnt(" #n ")" ::: "memory")
; #define PG8_WAIT_L(n) asm volatile("s_waitcnt lgkmcnt(" #n ")" ::: "memory")
; #define PG8_BAR __builtin_amdgcn_s_barrier()
; #define PG8_SCHED __builtin_amdgcn_sched_barrier(0)
; template <class Epi>
; __device__ __forceinline__ void gemm_phase(LAS unsigned char* lds, const Gemm g, const StaticOrder& S, const Epi& E) {
;     ...
;             PG8_WAIT_V(8); PG8_WAIT_L(0); PG8_BAR; PG8_MMA(1, 0, At, B0); PG8_MMA(1, 1, At, B1); PG8_BAR; PG8_SCHED;
;             PG8_LDB(B0, 1, 0); PG8_LDB(B1, 1, 1); PG8_SCHED; PG8_LDA(At, 1, 0); PG8_STAGE(PG8_SA(0, 1), a2 + hstepA, voffA);
;             PG8_WAIT_V(8); PG8_WAIT_L(0); PG8_BAR; PG8_MMA(0, 0, At, B0); PG8_MMA(0, 1, At, B1); PG8_BAR; PG8_SCHED;
	s_waitcnt lgkmcnt(0)
	v_mfma_f32_16x16x32_bf16 v[60:63], v[128:131], v[176:179], 0
	v_mfma_f32_16x16x32_bf16 v[56:59], v[136:139], v[176:179], 0
	v_mfma_f32_16x16x32_bf16 v[44:47], v[128:131], v[184:187], 0
	v_mfma_f32_16x16x32_bf16 v[40:43], v[136:139], v[184:187], 0
	v_mfma_f32_16x16x32_bf16 v[28:31], v[128:131], v[192:195], 0
	v_mfma_f32_16x16x32_bf16 v[24:27], v[136:139], v[192:195], 0
	v_mfma_f32_16x16x32_bf16 v[12:15], v[128:131], v[210:213], 0
	v_mfma_f32_16x16x32_bf16 v[8:11], v[136:139], v[210:213], 0
	v_mfma_f32_16x16x32_bf16 v[60:63], v[132:135], v[180:183], v[60:63]
	v_mfma_f32_16x16x32_bf16 v[56:59], v[140:143], v[180:183], v[56:59]
	v_mfma_f32_16x16x32_bf16 v[44:47], v[132:135], v[188:191], v[44:47]
	v_mfma_f32_16x16x32_bf16 v[40:43], v[140:143], v[188:191], v[40:43]
	v_mfma_f32_16x16x32_bf16 v[28:31], v[132:135], v[206:209], v[28:31]
	v_mfma_f32_16x16x32_bf16 v[24:27], v[140:143], v[206:209], v[24:27]
	v_mfma_f32_16x16x32_bf16 v[12:15], v[132:135], v[214:217], v[12:15]
	v_mfma_f32_16x16x32_bf16 v[8:11], v[140:143], v[214:217], v[8:11]
	v_mfma_f32_16x16x32_bf16 v[52:55], v[144:147], v[176:179], 0
	v_mfma_f32_16x16x32_bf16 v[48:51], v[168:171], v[176:179], 0
	v_mfma_f32_16x16x32_bf16 v[36:39], v[144:147], v[184:187], 0
	v_mfma_f32_16x16x32_bf16 v[32:35], v[168:171], v[184:187], 0
	v_mfma_f32_16x16x32_bf16 v[20:23], v[144:147], v[192:195], 0
	v_mfma_f32_16x16x32_bf16 v[16:19], v[168:171], v[192:195], 0
	v_mfma_f32_16x16x32_bf16 v[4:7], v[144:147], v[210:213], 0
	v_mfma_f32_16x16x32_bf16 v[0:3], v[168:171], v[210:213], 0
	v_mfma_f32_16x16x32_bf16 v[52:55], v[148:151], v[180:183], v[52:55]
	v_mfma_f32_16x16x32_bf16 v[48:51], v[172:175], v[180:183], v[48:51]
	v_mfma_f32_16x16x32_bf16 v[36:39], v[148:151], v[188:191], v[36:39]
	v_mfma_f32_16x16x32_bf16 v[32:35], v[172:175], v[188:191], v[32:35]
	v_mfma_f32_16x16x32_bf16 v[20:23], v[148:151], v[206:209], v[20:23]
	v_mfma_f32_16x16x32_bf16 v[16:19], v[172:175], v[206:209], v[16:19]
	v_mfma_f32_16x16x32_bf16 v[4:7], v[148:151], v[214:217], v[4:7]
	v_mfma_f32_16x16x32_bf16 v[0:3], v[172:175], v[214:217], v[0:3]
	s_barrier
	s_add_i32 s47, 0, 0x18000
	s_add_i32 s48, 0, 0x1c000
	v_add_u32_e32 v140, s47, v198
	v_add_u32_e32 v172, s48, v198
	ds_read_b128 v[128:131], v140
	ds_read_b128 v[132:135], v140 offset:1024
	ds_read_b128 v[136:139], v140 offset:2048
	ds_read_b128 v[140:143], v140 offset:3072
	ds_read_b128 v[144:147], v172
	ds_read_b128 v[148:151], v172 offset:1024
	ds_read_b128 v[168:171], v172 offset:2048
	ds_read_b128 v[172:175], v172 offset:3072
	s_add_u32 s2, s24, 0xb4000
	s_addc_u32 s3, s25, 0
	s_mov_b32 m0, s29
	v_lshl_add_u64 v[226:227], s[2:3], 0, v[152:153]
	ds_read_b128 v[176:179], v202 offset:32768
	ds_read_b128 v[180:183], v202 offset:33792
	ds_read_b128 v[184:187], v202 offset:34816
	ds_read_b128 v[188:191], v202 offset:35840
	ds_read_b128 v[192:195], v202 offset:36864
	ds_read_b128 v[206:209], v202 offset:37888
	ds_read_b128 v[210:213], v202 offset:38912
	ds_read_b128 v[214:217], v202 offset:39936
	global_load_lds_dwordx4 v[226:227], off
	v_lshl_add_u64 v[226:227], s[2:3], 0, v[156:157]
	s_mov_b32 m0, s30
	s_nop 0
	global_load_lds_dwordx4 v[226:227], off
	s_waitcnt vmcnt(8)
	s_waitcnt lgkmcnt(0)
	s_barrier
	s_waitcnt lgkmcnt(0)
	v_mfma_f32_16x16x32_bf16 v[124:127], v[128:131], v[176:179], v[124:127]
	v_mfma_f32_16x16x32_bf16 v[120:123], v[136:139], v[176:179], v[120:123]
	v_mfma_f32_16x16x32_bf16 v[108:111], v[128:131], v[184:187], v[108:111]
	v_mfma_f32_16x16x32_bf16 v[104:107], v[136:139], v[184:187], v[104:107]
	v_mfma_f32_16x16x32_bf16 v[92:95], v[128:131], v[192:195], v[92:95]
	v_mfma_f32_16x16x32_bf16 v[88:91], v[136:139], v[192:195], v[88:91]
	v_mfma_f32_16x16x32_bf16 v[76:79], v[128:131], v[210:213], v[76:79]
	v_mfma_f32_16x16x32_bf16 v[72:75], v[136:139], v[210:213], v[72:75]
	v_mfma_f32_16x16x32_bf16 v[124:127], v[132:135], v[180:183], v[124:127]
	v_mfma_f32_16x16x32_bf16 v[120:123], v[140:143], v[180:183], v[120:123]
	v_mfma_f32_16x16x32_bf16 v[108:111], v[132:135], v[188:191], v[108:111]
	v_mfma_f32_16x16x32_bf16 v[104:107], v[140:143], v[188:191], v[104:107]
	v_mfma_f32_16x16x32_bf16 v[92:95], v[132:135], v[206:209], v[92:95]
	v_mfma_f32_16x16x32_bf16 v[88:91], v[140:143], v[206:209], v[88:91]
	v_mfma_f32_16x16x32_bf16 v[76:79], v[132:135], v[214:217], v[76:79]
	v_mfma_f32_16x16x32_bf16 v[72:75], v[140:143], v[214:217], v[72:75]
	v_mfma_f32_16x16x32_bf16 v[116:119], v[144:147], v[176:179], v[116:119]
	v_mfma_f32_16x16x32_bf16 v[112:115], v[168:171], v[176:179], v[112:115]
	v_mfma_f32_16x16x32_bf16 v[100:103], v[144:147], v[184:187], v[100:103]
	v_mfma_f32_16x16x32_bf16 v[96:99], v[168:171], v[184:187], v[96:99]
	v_mfma_f32_16x16x32_bf16 v[84:87], v[144:147], v[192:195], v[84:87]
	v_mfma_f32_16x16x32_bf16 v[80:83], v[168:171], v[192:195], v[80:83]
	v_mfma_f32_16x16x32_bf16 v[68:71], v[144:147], v[210:213], v[68:71]
	v_mfma_f32_16x16x32_bf16 v[64:67], v[168:171], v[210:213], v[64:67]
	v_mfma_f32_16x16x32_bf16 v[116:119], v[148:151], v[180:183], v[116:119]
	v_mfma_f32_16x16x32_bf16 v[112:115], v[172:175], v[180:183], v[112:115]
	v_mfma_f32_16x16x32_bf16 v[100:103], v[148:151], v[188:191], v[100:103]
	v_mfma_f32_16x16x32_bf16 v[96:99], v[172:175], v[188:191], v[96:99]
	v_mfma_f32_16x16x32_bf16 v[84:87], v[148:151], v[206:209], v[84:87]
	v_mfma_f32_16x16x32_bf16 v[80:83], v[172:175], v[206:209], v[80:83]
	v_mfma_f32_16x16x32_bf16 v[68:71], v[148:151], v[214:217], v[68:71]
	v_mfma_f32_16x16x32_bf16 v[64:67], v[172:175], v[214:217], v[64:67]
	s_barrier
; #define PG8_STAGE(bufoff, gbase, voff) do { _Pragma("unroll") for (int _i = 0; _i < 2; ++_i) \
;         __builtin_amdgcn_global_load_lds((const unsigned*)((const char*)(gbase) + (voff)[_i]), (LAS unsigned*)(lds + (bufoff) + ldsw + _i * 8192), 16, 0, 0); } while (0)
; #define PG8_LDA(dst, b, h) do { _Pragma("unroll") for (int m = 0; m < 4; ++m) _Pragma("unroll") for (int k = 0; k < 2; ++k) dst[m][k] = *(const LAS bf16x8*)(lds + PG8_SA(b, h) + aoff + m * 2048 + k * 1024); } while (0)
; #define PG8_MMA(ai, bj, At, Bt) do { __builtin_amdgcn_s_setprio(1); _Pragma("unroll") for (int m = 0; m < 4; ++m) _Pragma("unroll") for (int n = 0; n < 2; ++n) _Pragma("unroll") for (int k = 0; k < 2; ++k) \
;         acc[ai][bj][m][n] = __builtin_amdgcn_mfma_f32_16x16x32_bf16(Bt[n][k], At[m][k], acc[ai][bj][m][n], 0, 0, 0); __builtin_amdgcn_s_setprio(0); } while (0)
; #define PG8_WAIT_V(n) asm volatile("s_waitcnt vmcnt(" #n ")" ::: "memory")
; #define PG8_WAIT_L(n) asm volatile("s_waitcnt lgkmcnt(" #n ")" ::: "memory")
; #define PG8_BAR __builtin_amdgcn_s_barrier()
; #define PG8_SCHED __builtin_amdgcn_sched_barrier(0)
; template <class Epi>
; __device__ __forceinline__ void gemm_phase(LAS unsigned char* lds, const Gemm g, const StaticOrder& S, const Epi& E) {
;     ...
;             PG8_LDA(At, 1, 1); PG8_STAGE(PG8_SB(1, 0), b3, voffB); PG8_STAGE(PG8_SB(1, 1), b3 + hstepB, voffB); PG8_STAGE(PG8_SA(1, 0), a3, voffA);
;             PG8_WAIT_V(8); PG8_WAIT_L(0); PG8_BAR; PG8_MMA(1, 0, At, B0); PG8_MMA(1, 1, At, B1); PG8_BAR; PG8_SCHED;
;         }
	s_add_i32 s2, s47, s26
	v_lshl_add_u64 v[218:219], v[218:219], 0, s[14:15]
	s_mov_b32 m0, s2
	ds_read_b128 v[176:179], v202 offset:49152
	ds_read_b128 v[180:183], v202 offset:50176
	ds_read_b128 v[184:187], v202 offset:51200
	ds_read_b128 v[188:191], v202 offset:52224
	ds_read_b128 v[192:195], v202 offset:53248
	ds_read_b128 v[206:209], v202 offset:54272
	ds_read_b128 v[210:213], v202 offset:55296
	ds_read_b128 v[214:217], v202 offset:56320
	global_load_lds_dwordx4 v[218:219], off
	s_add_i32 m0, s2, 0x2000
	s_add_u32 s2, s22, 0xb0080
	v_lshl_add_u64 v[218:219], v[220:221], 0, s[14:15]
	s_addc_u32 s3, s23, 0
	s_add_i32 s22, s48, s26
	global_load_lds_dwordx4 v[218:219], off
	v_lshl_add_u64 v[218:219], s[2:3], 0, v[154:155]
	s_mov_b32 m0, s22
	s_nop 0
	global_load_lds_dwordx4 v[218:219], off
	v_lshl_add_u64 v[218:219], s[2:3], 0, v[158:159]
	s_add_i32 m0, s22, 0x2000
	s_nop 0
	global_load_lds_dwordx4 v[218:219], off
	v_lshl_add_u64 v[218:219], v[222:223], 0, s[14:15]
	s_mov_b32 m0, s34
	s_nop 0
	global_load_lds_dwordx4 v[218:219], off
	v_lshl_add_u64 v[218:219], v[224:225], 0, s[14:15]
	s_mov_b32 m0, s35
	s_nop 0
	global_load_lds_dwordx4 v[218:219], off
	s_waitcnt vmcnt(8)
	s_waitcnt lgkmcnt(0)
	s_barrier
	s_waitcnt lgkmcnt(0)
	v_mfma_f32_16x16x32_bf16 v[60:63], v[128:131], v[176:179], v[60:63]
	v_mfma_f32_16x16x32_bf16 v[56:59], v[136:139], v[176:179], v[56:59]
	v_mfma_f32_16x16x32_bf16 v[44:47], v[128:131], v[184:187], v[44:47]
	v_mfma_f32_16x16x32_bf16 v[40:43], v[136:139], v[184:187], v[40:43]
	v_mfma_f32_16x16x32_bf16 v[28:31], v[128:131], v[192:195], v[28:31]
	v_mfma_f32_16x16x32_bf16 v[24:27], v[136:139], v[192:195], v[24:27]
	v_mfma_f32_16x16x32_bf16 v[12:15], v[128:131], v[210:213], v[12:15]
	v_mfma_f32_16x16x32_bf16 v[8:11], v[136:139], v[210:213], v[8:11]
	v_mfma_f32_16x16x32_bf16 v[60:63], v[132:135], v[180:183], v[60:63]
	v_mfma_f32_16x16x32_bf16 v[56:59], v[140:143], v[180:183], v[56:59]
	v_mfma_f32_16x16x32_bf16 v[44:47], v[132:135], v[188:191], v[44:47]
	v_mfma_f32_16x16x32_bf16 v[40:43], v[140:143], v[188:191], v[40:43]
	v_mfma_f32_16x16x32_bf16 v[28:31], v[132:135], v[206:209], v[28:31]
	v_mfma_f32_16x16x32_bf16 v[24:27], v[140:143], v[206:209], v[24:27]
	v_mfma_f32_16x16x32_bf16 v[12:15], v[132:135], v[214:217], v[12:15]
	v_mfma_f32_16x16x32_bf16 v[8:11], v[140:143], v[214:217], v[8:11]
	v_mfma_f32_16x16x32_bf16 v[52:55], v[144:147], v[176:179], v[52:55]
	v_mfma_f32_16x16x32_bf16 v[48:51], v[168:171], v[176:179], v[48:51]
	v_mfma_f32_16x16x32_bf16 v[36:39], v[144:147], v[184:187], v[36:39]
	v_mfma_f32_16x16x32_bf16 v[32:35], v[168:171], v[184:187], v[32:35]
	v_mfma_f32_16x16x32_bf16 v[20:23], v[144:147], v[192:195], v[20:23]
	v_mfma_f32_16x16x32_bf16 v[16:19], v[168:171], v[192:195], v[16:19]
	v_mfma_f32_16x16x32_bf16 v[4:7], v[144:147], v[210:213], v[4:7]
	v_mfma_f32_16x16x32_bf16 v[0:3], v[168:171], v[210:213], v[0:3]
	v_mfma_f32_16x16x32_bf16 v[52:55], v[148:151], v[180:183], v[52:55]
	v_mfma_f32_16x16x32_bf16 v[48:51], v[172:175], v[180:183], v[48:51]
	v_mfma_f32_16x16x32_bf16 v[36:39], v[148:151], v[188:191], v[36:39]
	v_mfma_f32_16x16x32_bf16 v[32:35], v[172:175], v[188:191], v[32:35]
	v_mfma_f32_16x16x32_bf16 v[20:23], v[148:151], v[206:209], v[20:23]
	v_mfma_f32_16x16x32_bf16 v[16:19], v[172:175], v[206:209], v[16:19]
	v_mfma_f32_16x16x32_bf16 v[4:7], v[148:151], v[214:217], v[4:7]
	v_mfma_f32_16x16x32_bf16 v[0:3], v[172:175], v[214:217], v[0:3]
	s_barrier
	s_add_i32 s46, s46, 2
	s_add_u32 s44, s44, 0x100
	s_addc_u32 s45, s45, 0
	s_cmp_gt_u32 s46, 41
	s_mov_b64 s[2:3], s[20:21]
	s_cbranch_scc0 .LBB0_1177
